# all five GEMM K-loops: counted lgkmcnt ladder inside each 16-MFMA block (first MFMA starts after its own fragments arrive) instead of lgkmcnt(0) before the block
# baseline (speedup 1.0000x reference)
; #define PG8_STAGE(bufoff, gbase, voff) do { _Pragma("unroll") for (int _i = 0; _i < 2; ++_i) \
;         __builtin_amdgcn_global_load_lds((const unsigned*)((const char*)(gbase) + (voff)[_i]), (PG8_LAS unsigned*)(lds + (bufoff) + ldsw + _i * 8192), 16, 0, 0); } while (0)
; #define PG8_LDA(dst, b, h) do { _Pragma("unroll") for (int m = 0; m < 4; ++m) _Pragma("unroll") for (int k = 0; k < 2; ++k) dst[m][k] = *(const PG8_LAS bf16x8*)(lds + PG8_SA(b, h) + aoff + m * 2048 + k * 1024); } while (0)
; #define PG8_LDB(dst, b, h) do { _Pragma("unroll") for (int n = 0; n < 2; ++n) _Pragma("unroll") for (int k = 0; k < 2; ++k) dst[n][k] = *(const PG8_LAS bf16x8*)(lds + PG8_SB(b, h) + boff + n * 2048 + k * 1024); } while (0)
; #define PG8_MMA(ai, bj, At, Bt) do { __builtin_amdgcn_s_setprio(1); _Pragma("unroll") for (int m = 0; m < 4; ++m) _Pragma("unroll") for (int n = 0; n < 2; ++n) _Pragma("unroll") for (int k = 0; k < 2; ++k) \
;         acc[ai][bj][m][n] = __builtin_amdgcn_mfma_f32_16x16x32_bf16(Bt[n][k], At[m][k], acc[ai][bj][m][n], 0, 0, 0); __builtin_amdgcn_s_setprio(0); } while (0)
; #define PG8_WAIT_V(n) asm volatile("s_waitcnt vmcnt(" #n ")" ::: "memory")
; #define PG8_WAIT_L(n) asm volatile("s_waitcnt lgkmcnt(" #n ")" ::: "memory")
; #define PG8_BAR __builtin_amdgcn_s_barrier()
; #define PG8_SCHED __builtin_amdgcn_sched_barrier(0)
; template <class Epi>
; __device__ __forceinline__ void gemm_phase(PG8_LAS unsigned char* lds, const Gemm g, const StaticOrder& S, const Epi& E) {
;     ...
;             PG8_LDB(B0, 0, 0); PG8_SCHED; PG8_LDA(At, 0, 0); PG8_STAGE(PG8_SA(1, 1), a1 + hstep, voffA);
;             PG8_WAIT_L(8); PG8_BAR; PG8_WAIT_L(0); PG8_MMA(0, 0, At, B0); PG8_BAR; PG8_SCHED;
;             PG8_LDB(B1, 0, 1); PG8_STAGE(PG8_SB(0, 0), b2, voffB);
;             PG8_BAR; PG8_WAIT_L(0); PG8_MMA(0, 1, At, B1); PG8_BAR;
;             PG8_LDA(At, 0, 1); PG8_STAGE(PG8_SA(0, 0), a2, voffA);
;             PG8_BAR; PG8_WAIT_L(0); PG8_MMA(1, 0, At, B0); PG8_BAR; PG8_SCHED;
;             PG8_STAGE(PG8_SB(0, 1), b2 + hstep, voffB);
;             PG8_WAIT_V(6); PG8_BAR; PG8_MMA(1, 1, At, B1); PG8_BAR;
;             PG8_LDB(B0, 1, 0); PG8_SCHED; PG8_LDA(At, 1, 0); PG8_STAGE(PG8_SA(0, 1), a2 + hstep, voffA);
;             PG8_WAIT_L(8); PG8_BAR; PG8_WAIT_L(0); PG8_MMA(0, 0, At, B0); PG8_BAR; PG8_SCHED;
.LBB0_56:
	ds_read_b128 v[148:151], v158
	ds_read_b128 v[152:155], v158 offset:1024
	ds_read_b128 v[162:165], v158 offset:2048
	ds_read_b128 v[166:169], v158 offset:3072
	s_add_u32 s28, s26, 0xfff80080
	s_addc_u32 s29, s27, -1
	s_cmp_eq_u32 s50, 28
	s_cselect_b32 s31, s5, s29
	s_cselect_b32 s30, s19, s28
	s_cselect_b32 s29, s17, s49
	s_cselect_b32 s28, s25, s48
	v_lshl_add_u64 v[202:203], s[26:27], 0, v[140:141]
	s_add_i32 m0, s37, 0xc000
	ds_read_b128 v[170:173], v159
	ds_read_b128 v[174:177], v159 offset:1024
	ds_read_b128 v[178:181], v159 offset:2048
	ds_read_b128 v[182:185], v159 offset:3072
	ds_read_b128 v[186:189], v159 offset:4096
	ds_read_b128 v[190:193], v159 offset:5120
	ds_read_b128 v[194:197], v159 offset:6144
	ds_read_b128 v[198:201], v159 offset:7168
	global_load_lds_dwordx4 v[202:203], off
	v_lshl_add_u64 v[202:203], s[26:27], 0, v[142:143]
	s_add_i32 m0, s37, 0xe000
	s_nop 0
	global_load_lds_dwordx4 v[202:203], off
	s_waitcnt lgkmcnt(8)
	s_barrier
	s_nop 0
	s_setprio 1
	s_nop 0
	s_waitcnt lgkmcnt(7)
	v_mfma_f32_16x16x32_bf16 v[126:129], v[148:151], v[170:173], v[126:129]
	v_mfma_f32_16x16x32_bf16 v[122:125], v[162:165], v[170:173], v[122:125]
	s_waitcnt lgkmcnt(5)
	v_mfma_f32_16x16x32_bf16 v[110:113], v[148:151], v[178:181], v[110:113]
	v_mfma_f32_16x16x32_bf16 v[106:109], v[162:165], v[178:181], v[106:109]
	s_waitcnt lgkmcnt(3)
	v_mfma_f32_16x16x32_bf16 v[94:97], v[148:151], v[186:189], v[94:97]
	v_mfma_f32_16x16x32_bf16 v[90:93], v[162:165], v[186:189], v[90:93]
	s_waitcnt lgkmcnt(1)
	v_mfma_f32_16x16x32_bf16 v[78:81], v[148:151], v[194:197], v[78:81]
	v_mfma_f32_16x16x32_bf16 v[74:77], v[162:165], v[194:197], v[74:77]
	v_mfma_f32_16x16x32_bf16 v[126:129], v[152:155], v[174:177], v[126:129]
	v_mfma_f32_16x16x32_bf16 v[122:125], v[166:169], v[174:177], v[122:125]
	v_mfma_f32_16x16x32_bf16 v[110:113], v[152:155], v[182:185], v[110:113]
	v_mfma_f32_16x16x32_bf16 v[106:109], v[166:169], v[182:185], v[106:109]
	v_mfma_f32_16x16x32_bf16 v[94:97], v[152:155], v[190:193], v[94:97]
	v_mfma_f32_16x16x32_bf16 v[90:93], v[166:169], v[190:193], v[90:93]
	s_waitcnt lgkmcnt(0)
	v_mfma_f32_16x16x32_bf16 v[78:81], v[152:155], v[198:201], v[78:81]
	v_mfma_f32_16x16x32_bf16 v[74:77], v[166:169], v[198:201], v[74:77]
	s_setprio 0
	s_barrier
	s_add_i32 s51, s46, s36
	v_lshl_add_u64 v[218:219], s[28:29], 0, v[132:133]
	s_mov_b32 m0, s51
	ds_read_b128 v[202:205], v160
	ds_read_b128 v[206:209], v160 offset:1024
	ds_read_b128 v[210:213], v160 offset:2048
	ds_read_b128 v[214:217], v160 offset:3072
	global_load_lds_dwordx4 v[218:219], off
	v_lshl_add_u64 v[220:221], s[28:29], 0, v[136:137]
	s_add_i32 m0, s51, 0x2000
	s_nop 0
	global_load_lds_dwordx4 v[220:221], off
	s_barrier
	s_nop 0
	s_setprio 1
	s_nop 0
	s_waitcnt lgkmcnt(3)
	v_mfma_f32_16x16x32_bf16 v[118:121], v[202:205], v[170:173], v[118:121]
	s_waitcnt lgkmcnt(1)
	v_mfma_f32_16x16x32_bf16 v[114:117], v[210:213], v[170:173], v[114:117]
	v_mfma_f32_16x16x32_bf16 v[102:105], v[202:205], v[178:181], v[102:105]
	v_mfma_f32_16x16x32_bf16 v[98:101], v[210:213], v[178:181], v[98:101]
	v_mfma_f32_16x16x32_bf16 v[86:89], v[202:205], v[186:189], v[86:89]
	v_mfma_f32_16x16x32_bf16 v[82:85], v[210:213], v[186:189], v[82:85]
	v_mfma_f32_16x16x32_bf16 v[70:73], v[202:205], v[194:197], v[70:73]
	v_mfma_f32_16x16x32_bf16 v[66:69], v[210:213], v[194:197], v[66:69]
	v_mfma_f32_16x16x32_bf16 v[118:121], v[206:209], v[174:177], v[118:121]
	s_waitcnt lgkmcnt(0)
	v_mfma_f32_16x16x32_bf16 v[114:117], v[214:217], v[174:177], v[114:117]
	v_mfma_f32_16x16x32_bf16 v[102:105], v[206:209], v[182:185], v[102:105]
	v_mfma_f32_16x16x32_bf16 v[98:101], v[214:217], v[182:185], v[98:101]
	v_mfma_f32_16x16x32_bf16 v[86:89], v[206:209], v[190:193], v[86:89]
	v_mfma_f32_16x16x32_bf16 v[82:85], v[214:217], v[190:193], v[82:85]
	v_mfma_f32_16x16x32_bf16 v[70:73], v[206:209], v[198:201], v[70:73]
	v_mfma_f32_16x16x32_bf16 v[66:69], v[214:217], v[198:201], v[66:69]
	s_setprio 0
	s_mov_b32 m0, s37
	v_lshl_add_u64 v[222:223], s[30:31], 0, v[130:131]
	s_barrier
	ds_read_b128 v[170:173], v159 offset:16384
	ds_read_b128 v[174:177], v159 offset:17408
	ds_read_b128 v[178:181], v159 offset:18432
	ds_read_b128 v[182:185], v159 offset:19456
	ds_read_b128 v[186:189], v159 offset:20480
	ds_read_b128 v[190:193], v159 offset:21504
	ds_read_b128 v[194:197], v159 offset:22528
	ds_read_b128 v[198:201], v159 offset:23552
	global_load_lds_dwordx4 v[222:223], off
	v_lshl_add_u64 v[224:225], s[30:31], 0, v[134:135]
	s_mov_b32 m0, s38
	s_nop 0
	global_load_lds_dwordx4 v[224:225], off
	s_barrier
	s_nop 0
	s_setprio 1
	s_nop 0
	s_waitcnt lgkmcnt(7)
	v_mfma_f32_16x16x32_bf16 v[62:65], v[148:151], v[170:173], v[62:65]
	v_mfma_f32_16x16x32_bf16 v[58:61], v[162:165], v[170:173], v[58:61]
	s_waitcnt lgkmcnt(5)
	v_mfma_f32_16x16x32_bf16 v[46:49], v[148:151], v[178:181], v[46:49]
	v_mfma_f32_16x16x32_bf16 v[42:45], v[162:165], v[178:181], v[42:45]
	s_waitcnt lgkmcnt(3)
	v_mfma_f32_16x16x32_bf16 v[30:33], v[148:151], v[186:189], v[30:33]
	v_mfma_f32_16x16x32_bf16 v[26:29], v[162:165], v[186:189], v[26:29]
	s_waitcnt lgkmcnt(1)
	v_mfma_f32_16x16x32_bf16 v[14:17], v[148:151], v[194:197], v[14:17]
	v_mfma_f32_16x16x32_bf16 v[10:13], v[162:165], v[194:197], v[10:13]
	v_mfma_f32_16x16x32_bf16 v[62:65], v[152:155], v[174:177], v[62:65]
	v_mfma_f32_16x16x32_bf16 v[58:61], v[166:169], v[174:177], v[58:61]
	v_mfma_f32_16x16x32_bf16 v[46:49], v[152:155], v[182:185], v[46:49]
	v_mfma_f32_16x16x32_bf16 v[42:45], v[166:169], v[182:185], v[42:45]
	v_mfma_f32_16x16x32_bf16 v[30:33], v[152:155], v[190:193], v[30:33]
	v_mfma_f32_16x16x32_bf16 v[26:29], v[166:169], v[190:193], v[26:29]
	s_waitcnt lgkmcnt(0)
	v_mfma_f32_16x16x32_bf16 v[14:17], v[152:155], v[198:201], v[14:17]
	v_mfma_f32_16x16x32_bf16 v[10:13], v[166:169], v[198:201], v[10:13]
	s_setprio 0
	s_barrier
; #define PG8_STAGE(bufoff, gbase, voff) do { _Pragma("unroll") for (int _i = 0; _i < 2; ++_i) \
;         __builtin_amdgcn_global_load_lds((const unsigned*)((const char*)(gbase) + (voff)[_i]), (PG8_LAS unsigned*)(lds + (bufoff) + ldsw + _i * 8192), 16, 0, 0); } while (0)
; #define PG8_LDA(dst, b, h) do { _Pragma("unroll") for (int m = 0; m < 4; ++m) _Pragma("unroll") for (int k = 0; k < 2; ++k) dst[m][k] = *(const PG8_LAS bf16x8*)(lds + PG8_SA(b, h) + aoff + m * 2048 + k * 1024); } while (0)
; #define PG8_LDB(dst, b, h) do { _Pragma("unroll") for (int n = 0; n < 2; ++n) _Pragma("unroll") for (int k = 0; k < 2; ++k) dst[n][k] = *(const PG8_LAS bf16x8*)(lds + PG8_SB(b, h) + boff + n * 2048 + k * 1024); } while (0)
; #define PG8_MMA(ai, bj, At, Bt) do { __builtin_amdgcn_s_setprio(1); _Pragma("unroll") for (int m = 0; m < 4; ++m) _Pragma("unroll") for (int n = 0; n < 2; ++n) _Pragma("unroll") for (int k = 0; k < 2; ++k) \
;         acc[ai][bj][m][n] = __builtin_amdgcn_mfma_f32_16x16x32_bf16(Bt[n][k], At[m][k], acc[ai][bj][m][n], 0, 0, 0); __builtin_amdgcn_s_setprio(0); } while (0)
; #define PG8_WAIT_V(n) asm volatile("s_waitcnt vmcnt(" #n ")" ::: "memory")
; #define PG8_WAIT_L(n) asm volatile("s_waitcnt lgkmcnt(" #n ")" ::: "memory")
; #define PG8_BAR __builtin_amdgcn_s_barrier()
; #define PG8_SCHED __builtin_amdgcn_sched_barrier(0)
; template <class Epi>
; __device__ __forceinline__ void gemm_phase(PG8_LAS unsigned char* lds, const Gemm g, const StaticOrder& S, const Epi& E) {
;     ...
;             PG8_WAIT_V(6); PG8_BAR; PG8_MMA(1, 1, At, B1); PG8_BAR;
;             PG8_LDB(B0, 1, 0); PG8_SCHED; PG8_LDA(At, 1, 0); PG8_STAGE(PG8_SA(0, 1), a2 + hstep, voffA);
;             PG8_WAIT_L(8); PG8_BAR; PG8_WAIT_L(0); PG8_MMA(0, 0, At, B0); PG8_BAR; PG8_SCHED;
;             PG8_LDB(B1, 1, 1); PG8_STAGE(PG8_SB(1, 0), b3, voffB);
;             PG8_BAR; PG8_WAIT_L(0); PG8_MMA(0, 1, At, B1); PG8_BAR;
;             PG8_LDA(At, 1, 1); PG8_STAGE(PG8_SA(1, 0), a3, voffA);
;             PG8_BAR; PG8_WAIT_L(0); PG8_MMA(1, 0, At, B0); PG8_BAR; PG8_SCHED;
	s_add_u32 s52, s28, 0x80000
	s_addc_u32 s53, s29, 0
	s_add_i32 s51, s47, s36
	v_lshl_add_u64 v[148:149], s[52:53], 0, v[132:133]
	s_mov_b32 m0, s51
	s_nop 0
	global_load_lds_dwordx4 v[148:149], off
	v_lshl_add_u64 v[148:149], s[52:53], 0, v[136:137]
	s_add_i32 m0, s51, 0x2000
	s_nop 0
	global_load_lds_dwordx4 v[148:149], off
	s_waitcnt vmcnt(6)
	s_barrier
	s_setprio 1
	v_mfma_f32_16x16x32_bf16 v[54:57], v[202:205], v[170:173], v[54:57]
	v_mfma_f32_16x16x32_bf16 v[50:53], v[210:213], v[170:173], v[50:53]
	v_mfma_f32_16x16x32_bf16 v[38:41], v[202:205], v[178:181], v[38:41]
	v_mfma_f32_16x16x32_bf16 v[34:37], v[210:213], v[178:181], v[34:37]
	v_mfma_f32_16x16x32_bf16 v[22:25], v[202:205], v[186:189], v[22:25]
	v_mfma_f32_16x16x32_bf16 v[18:21], v[210:213], v[186:189], v[18:21]
	v_mfma_f32_16x16x32_bf16 v[6:9], v[202:205], v[194:197], v[6:9]
	v_mfma_f32_16x16x32_bf16 v[2:5], v[210:213], v[194:197], v[2:5]
	v_mfma_f32_16x16x32_bf16 v[54:57], v[206:209], v[174:177], v[54:57]
	v_mfma_f32_16x16x32_bf16 v[50:53], v[214:217], v[174:177], v[50:53]
	v_mfma_f32_16x16x32_bf16 v[38:41], v[206:209], v[182:185], v[38:41]
	v_mfma_f32_16x16x32_bf16 v[34:37], v[214:217], v[182:185], v[34:37]
	v_mfma_f32_16x16x32_bf16 v[22:25], v[206:209], v[190:193], v[22:25]
	v_mfma_f32_16x16x32_bf16 v[18:21], v[214:217], v[190:193], v[18:21]
	v_mfma_f32_16x16x32_bf16 v[6:9], v[206:209], v[198:201], v[6:9]
	v_mfma_f32_16x16x32_bf16 v[2:5], v[214:217], v[198:201], v[2:5]
	s_setprio 0
	s_add_i32 s51, 0, 0x18000
	v_add_u32_e32 v138, s51, v156
	s_barrier
	ds_read_b128 v[148:151], v138
	ds_read_b128 v[152:155], v138 offset:1024
	ds_read_b128 v[162:165], v138 offset:2048
	ds_read_b128 v[166:169], v138 offset:3072
	s_add_u32 s30, s30, 0x80000
	s_addc_u32 s31, s31, 0
	s_mov_b32 m0, s39
	v_lshl_add_u64 v[202:203], s[30:31], 0, v[130:131]
	ds_read_b128 v[170:173], v159 offset:32768
	ds_read_b128 v[174:177], v159 offset:33792
	ds_read_b128 v[178:181], v159 offset:34816
	ds_read_b128 v[182:185], v159 offset:35840
	ds_read_b128 v[186:189], v159 offset:36864
	ds_read_b128 v[190:193], v159 offset:37888
	ds_read_b128 v[194:197], v159 offset:38912
	ds_read_b128 v[198:201], v159 offset:39936
	global_load_lds_dwordx4 v[202:203], off
	v_lshl_add_u64 v[202:203], s[30:31], 0, v[134:135]
	s_mov_b32 m0, s40
	s_nop 0
	global_load_lds_dwordx4 v[202:203], off
	s_waitcnt lgkmcnt(8)
	s_barrier
	s_nop 0
	s_setprio 1
	s_nop 0
	s_waitcnt lgkmcnt(7)
	v_mfma_f32_16x16x32_bf16 v[126:129], v[148:151], v[170:173], v[126:129]
	v_mfma_f32_16x16x32_bf16 v[122:125], v[162:165], v[170:173], v[122:125]
	s_waitcnt lgkmcnt(5)
	v_mfma_f32_16x16x32_bf16 v[110:113], v[148:151], v[178:181], v[110:113]
	v_mfma_f32_16x16x32_bf16 v[106:109], v[162:165], v[178:181], v[106:109]
	s_waitcnt lgkmcnt(3)
	v_mfma_f32_16x16x32_bf16 v[94:97], v[148:151], v[186:189], v[94:97]
	v_mfma_f32_16x16x32_bf16 v[90:93], v[162:165], v[186:189], v[90:93]
	s_waitcnt lgkmcnt(1)
	v_mfma_f32_16x16x32_bf16 v[78:81], v[148:151], v[194:197], v[78:81]
	v_mfma_f32_16x16x32_bf16 v[74:77], v[162:165], v[194:197], v[74:77]
	v_mfma_f32_16x16x32_bf16 v[126:129], v[152:155], v[174:177], v[126:129]
	v_mfma_f32_16x16x32_bf16 v[122:125], v[166:169], v[174:177], v[122:125]
	v_mfma_f32_16x16x32_bf16 v[110:113], v[152:155], v[182:185], v[110:113]
	v_mfma_f32_16x16x32_bf16 v[106:109], v[166:169], v[182:185], v[106:109]
	v_mfma_f32_16x16x32_bf16 v[94:97], v[152:155], v[190:193], v[94:97]
	v_mfma_f32_16x16x32_bf16 v[90:93], v[166:169], v[190:193], v[90:93]
	s_waitcnt lgkmcnt(0)
	v_mfma_f32_16x16x32_bf16 v[78:81], v[152:155], v[198:201], v[78:81]
	v_mfma_f32_16x16x32_bf16 v[74:77], v[166:169], v[198:201], v[74:77]
	s_setprio 0
	s_barrier
	s_add_i32 s30, 0, 0x1c000
	s_add_i32 s31, s51, s36
	v_add_u32_e32 v138, s30, v156
	v_lshl_add_u64 v[218:219], v[218:219], 0, s[12:13]
	s_mov_b32 m0, s31
	ds_read_b128 v[202:205], v138
	ds_read_b128 v[206:209], v138 offset:1024
	ds_read_b128 v[210:213], v138 offset:2048
	ds_read_b128 v[214:217], v138 offset:3072
	global_load_lds_dwordx4 v[218:219], off
	v_lshl_add_u64 v[218:219], v[220:221], 0, s[12:13]
	s_add_i32 m0, s31, 0x2000
	s_nop 0
	global_load_lds_dwordx4 v[218:219], off
	s_barrier
; #define PG8_STAGE(bufoff, gbase, voff) do { _Pragma("unroll") for (int _i = 0; _i < 2; ++_i) \
;         __builtin_amdgcn_global_load_lds((const unsigned*)((const char*)(gbase) + (voff)[_i]), (PG8_LAS unsigned*)(lds + (bufoff) + ldsw + _i * 8192), 16, 0, 0); } while (0)
; #define PG8_LDA(dst, b, h) do { _Pragma("unroll") for (int m = 0; m < 4; ++m) _Pragma("unroll") for (int k = 0; k < 2; ++k) dst[m][k] = *(const PG8_LAS bf16x8*)(lds + PG8_SA(b, h) + aoff + m * 2048 + k * 1024); } while (0)
; #define PG8_MMA(ai, bj, At, Bt) do { __builtin_amdgcn_s_setprio(1); _Pragma("unroll") for (int m = 0; m < 4; ++m) _Pragma("unroll") for (int n = 0; n < 2; ++n) _Pragma("unroll") for (int k = 0; k < 2; ++k) \
;         acc[ai][bj][m][n] = __builtin_amdgcn_mfma_f32_16x16x32_bf16(Bt[n][k], At[m][k], acc[ai][bj][m][n], 0, 0, 0); __builtin_amdgcn_s_setprio(0); } while (0)
; #define PG8_WAIT_V(n) asm volatile("s_waitcnt vmcnt(" #n ")" ::: "memory")
; #define PG8_WAIT_L(n) asm volatile("s_waitcnt lgkmcnt(" #n ")" ::: "memory")
; #define PG8_BAR __builtin_amdgcn_s_barrier()
; #define PG8_SCHED __builtin_amdgcn_sched_barrier(0)
; template <class Epi>
; __device__ __forceinline__ void gemm_phase(PG8_LAS unsigned char* lds, const Gemm g, const StaticOrder& S, const Epi& E) {
;     ...
;             PG8_LDA(At, 1, 1); PG8_STAGE(PG8_SA(1, 0), a3, voffA);
;             PG8_BAR; PG8_WAIT_L(0); PG8_MMA(1, 0, At, B0); PG8_BAR; PG8_SCHED;
;             PG8_STAGE(PG8_SB(1, 1), b3 + hstep, voffB);
;             PG8_WAIT_V(6); PG8_BAR; PG8_MMA(1, 1, At, B1); PG8_BAR;
	s_nop 0
	s_setprio 1
	s_nop 0
	s_waitcnt lgkmcnt(3)
	v_mfma_f32_16x16x32_bf16 v[118:121], v[202:205], v[170:173], v[118:121]
	s_waitcnt lgkmcnt(1)
	v_mfma_f32_16x16x32_bf16 v[114:117], v[210:213], v[170:173], v[114:117]
	v_mfma_f32_16x16x32_bf16 v[102:105], v[202:205], v[178:181], v[102:105]
	v_mfma_f32_16x16x32_bf16 v[98:101], v[210:213], v[178:181], v[98:101]
	v_mfma_f32_16x16x32_bf16 v[86:89], v[202:205], v[186:189], v[86:89]
	v_mfma_f32_16x16x32_bf16 v[82:85], v[210:213], v[186:189], v[82:85]
	v_mfma_f32_16x16x32_bf16 v[70:73], v[202:205], v[194:197], v[70:73]
	v_mfma_f32_16x16x32_bf16 v[66:69], v[210:213], v[194:197], v[66:69]
	v_mfma_f32_16x16x32_bf16 v[118:121], v[206:209], v[174:177], v[118:121]
	s_waitcnt lgkmcnt(0)
	v_mfma_f32_16x16x32_bf16 v[114:117], v[214:217], v[174:177], v[114:117]
	v_mfma_f32_16x16x32_bf16 v[102:105], v[206:209], v[182:185], v[102:105]
	v_mfma_f32_16x16x32_bf16 v[98:101], v[214:217], v[182:185], v[98:101]
	v_mfma_f32_16x16x32_bf16 v[86:89], v[206:209], v[190:193], v[86:89]
	v_mfma_f32_16x16x32_bf16 v[82:85], v[214:217], v[190:193], v[82:85]
	v_mfma_f32_16x16x32_bf16 v[70:73], v[206:209], v[198:201], v[70:73]
	v_mfma_f32_16x16x32_bf16 v[66:69], v[214:217], v[198:201], v[66:69]
	s_setprio 0
	s_mov_b32 m0, s42
	v_lshl_add_u64 v[218:219], v[222:223], 0, s[12:13]
	s_barrier
	ds_read_b128 v[170:173], v159 offset:49152
	ds_read_b128 v[174:177], v159 offset:50176
	ds_read_b128 v[178:181], v159 offset:51200
	ds_read_b128 v[182:185], v159 offset:52224
	ds_read_b128 v[186:189], v159 offset:53248
	ds_read_b128 v[190:193], v159 offset:54272
	ds_read_b128 v[194:197], v159 offset:55296
	ds_read_b128 v[198:201], v159 offset:56320
	global_load_lds_dwordx4 v[218:219], off
	v_lshl_add_u64 v[218:219], v[224:225], 0, s[12:13]
	s_mov_b32 m0, s43
	s_nop 0
	global_load_lds_dwordx4 v[218:219], off
	s_barrier
	s_nop 0
	s_setprio 1
	s_nop 0
	s_waitcnt lgkmcnt(7)
	v_mfma_f32_16x16x32_bf16 v[62:65], v[148:151], v[170:173], v[62:65]
	v_mfma_f32_16x16x32_bf16 v[58:61], v[162:165], v[170:173], v[58:61]
	s_waitcnt lgkmcnt(5)
	v_mfma_f32_16x16x32_bf16 v[46:49], v[148:151], v[178:181], v[46:49]
	v_mfma_f32_16x16x32_bf16 v[42:45], v[162:165], v[178:181], v[42:45]
	s_waitcnt lgkmcnt(3)
	v_mfma_f32_16x16x32_bf16 v[30:33], v[148:151], v[186:189], v[30:33]
	v_mfma_f32_16x16x32_bf16 v[26:29], v[162:165], v[186:189], v[26:29]
	s_waitcnt lgkmcnt(1)
	v_mfma_f32_16x16x32_bf16 v[14:17], v[148:151], v[194:197], v[14:17]
	v_mfma_f32_16x16x32_bf16 v[10:13], v[162:165], v[194:197], v[10:13]
	v_mfma_f32_16x16x32_bf16 v[62:65], v[152:155], v[174:177], v[62:65]
	v_mfma_f32_16x16x32_bf16 v[58:61], v[166:169], v[174:177], v[58:61]
	v_mfma_f32_16x16x32_bf16 v[46:49], v[152:155], v[182:185], v[46:49]
	v_mfma_f32_16x16x32_bf16 v[42:45], v[166:169], v[182:185], v[42:45]
	v_mfma_f32_16x16x32_bf16 v[30:33], v[152:155], v[190:193], v[30:33]
	v_mfma_f32_16x16x32_bf16 v[26:29], v[166:169], v[190:193], v[26:29]
	s_waitcnt lgkmcnt(0)
	v_mfma_f32_16x16x32_bf16 v[14:17], v[152:155], v[198:201], v[14:17]
	v_mfma_f32_16x16x32_bf16 v[10:13], v[166:169], v[198:201], v[10:13]
	s_setprio 0
	s_barrier
	s_add_u32 s28, s28, 0x80080
	s_addc_u32 s29, s29, 0
	s_add_i32 s30, s30, s36
	v_lshl_add_u64 v[148:149], s[28:29], 0, v[132:133]
	s_mov_b32 m0, s30
	s_nop 0
	global_load_lds_dwordx4 v[148:149], off
	v_lshl_add_u64 v[148:149], s[28:29], 0, v[136:137]
	s_add_i32 m0, s30, 0x2000
	s_nop 0
	global_load_lds_dwordx4 v[148:149], off
	s_waitcnt vmcnt(6)
	s_barrier
	s_setprio 1
	v_mfma_f32_16x16x32_bf16 v[54:57], v[202:205], v[170:173], v[54:57]
	v_mfma_f32_16x16x32_bf16 v[50:53], v[210:213], v[170:173], v[50:53]
	v_mfma_f32_16x16x32_bf16 v[38:41], v[202:205], v[178:181], v[38:41]
	v_mfma_f32_16x16x32_bf16 v[34:37], v[210:213], v[178:181], v[34:37]
	v_mfma_f32_16x16x32_bf16 v[22:25], v[202:205], v[186:189], v[22:25]
	v_mfma_f32_16x16x32_bf16 v[18:21], v[210:213], v[186:189], v[18:21]
	v_mfma_f32_16x16x32_bf16 v[6:9], v[202:205], v[194:197], v[6:9]
	v_mfma_f32_16x16x32_bf16 v[2:5], v[210:213], v[194:197], v[2:5]
	v_mfma_f32_16x16x32_bf16 v[54:57], v[206:209], v[174:177], v[54:57]
	v_mfma_f32_16x16x32_bf16 v[50:53], v[214:217], v[174:177], v[50:53]
	v_mfma_f32_16x16x32_bf16 v[38:41], v[206:209], v[182:185], v[38:41]
	v_mfma_f32_16x16x32_bf16 v[34:37], v[214:217], v[182:185], v[34:37]
	v_mfma_f32_16x16x32_bf16 v[22:25], v[206:209], v[190:193], v[22:25]
	v_mfma_f32_16x16x32_bf16 v[18:21], v[214:217], v[190:193], v[18:21]
	v_mfma_f32_16x16x32_bf16 v[6:9], v[206:209], v[198:201], v[6:9]
	v_mfma_f32_16x16x32_bf16 v[2:5], v[214:217], v[198:201], v[2:5]
	s_setprio 0
	s_add_i32 s50, s50, 2
	s_add_u32 s26, s26, 0x100
	s_addc_u32 s27, s27, 0
	s_add_u32 s48, s48, 0x100
	s_addc_u32 s49, s49, 0
	s_cmp_gt_u32 s50, 29
	s_barrier
	s_cbranch_scc0 .LBB0_56
	s_lshl_b32 s19, s4, 8
	s_ashr_i32 s17, s4, 3
	v_lshl_add_u32 v148, s24, 8, v1
	s_cmpk_gt_u32 s19, 0x7ff
	v_ashrrev_i32_e32 v149, 31, v148
	s_cselect_b64 s[24:25], -1, 0
	v_lshlrev_b64 v[150:151], 12, v[148:149]
	v_lshlrev_b64 v[152:153], 13, v[148:149]
	s_mov_b64 s[4:5], -1
	s_and_b64 vcc, exec, s[24:25]
	s_cbranch_vccz .LBB0_64
	s_mov_b64 s[28:29], -1
	s_mov_b64 s[4:5], 0
	s_cmp_lt_i32 s17, 2
	s_mov_b64 s[26:27], 0
	s_cbranch_scc0 .LBB0_201
	s_and_b64 vcc, exec, s[28:29]
	s_cbranch_vccnz .LBB0_204

; #define PG8_STAGE(bufoff, gbase, voff) do { _Pragma("unroll") for (int _i = 0; _i < 2; ++_i) \
;         __builtin_amdgcn_global_load_lds((const unsigned*)((const char*)(gbase) + (voff)[_i]), (PG8_LAS unsigned*)(lds + (bufoff) + ldsw + _i * 8192), 16, 0, 0); } while (0)
; #define PG8_LDA(dst, b, h) do { _Pragma("unroll") for (int m = 0; m < 4; ++m) _Pragma("unroll") for (int k = 0; k < 2; ++k) dst[m][k] = *(const PG8_LAS bf16x8*)(lds + PG8_SA(b, h) + aoff + m * 2048 + k * 1024); } while (0)
; #define PG8_LDB(dst, b, h) do { _Pragma("unroll") for (int n = 0; n < 2; ++n) _Pragma("unroll") for (int k = 0; k < 2; ++k) dst[n][k] = *(const PG8_LAS bf16x8*)(lds + PG8_SB(b, h) + boff + n * 2048 + k * 1024); } while (0)
; #define PG8_MMA(ai, bj, At, Bt) do { __builtin_amdgcn_s_setprio(1); _Pragma("unroll") for (int m = 0; m < 4; ++m) _Pragma("unroll") for (int n = 0; n < 2; ++n) _Pragma("unroll") for (int k = 0; k < 2; ++k) \
;         acc[ai][bj][m][n] = __builtin_amdgcn_mfma_f32_16x16x32_bf16(Bt[n][k], At[m][k], acc[ai][bj][m][n], 0, 0, 0); __builtin_amdgcn_s_setprio(0); } while (0)
; #define PG8_WAIT_V(n) asm volatile("s_waitcnt vmcnt(" #n ")" ::: "memory")
; #define PG8_WAIT_L(n) asm volatile("s_waitcnt lgkmcnt(" #n ")" ::: "memory")
; #define PG8_BAR __builtin_amdgcn_s_barrier()
; #define PG8_SCHED __builtin_amdgcn_sched_barrier(0)
; template <class Epi>
; __device__ __forceinline__ void gemm_phase(PG8_LAS unsigned char* lds, const Gemm g, const StaticOrder& S, const Epi& E) {
;     ...
;             PG8_LDB(B0, 0, 0); PG8_SCHED; PG8_LDA(At, 0, 0); PG8_STAGE(PG8_SA(1, 1), a1 + hstep, voffA);
;             PG8_WAIT_L(8); PG8_BAR; PG8_WAIT_L(0); PG8_MMA(0, 0, At, B0); PG8_BAR; PG8_SCHED;
;             PG8_LDB(B1, 0, 1); PG8_STAGE(PG8_SB(0, 0), b2, voffB);
;             PG8_BAR; PG8_WAIT_L(0); PG8_MMA(0, 1, At, B1); PG8_BAR;
;             PG8_LDA(At, 0, 1); PG8_STAGE(PG8_SA(0, 0), a2, voffA);
;             PG8_BAR; PG8_WAIT_L(0); PG8_MMA(1, 0, At, B0); PG8_BAR; PG8_SCHED;
;             PG8_STAGE(PG8_SB(0, 1), b2 + hstep, voffB);
;             PG8_WAIT_V(6); PG8_BAR; PG8_MMA(1, 1, At, B1); PG8_BAR;
;             PG8_LDB(B0, 1, 0); PG8_SCHED; PG8_LDA(At, 1, 0); PG8_STAGE(PG8_SA(0, 1), a2 + hstep, voffA);
;             PG8_WAIT_L(8); PG8_BAR; PG8_WAIT_L(0); PG8_MMA(0, 0, At, B0); PG8_BAR; PG8_SCHED;
.LBB0_653:
	ds_read_b128 v[154:157], v150
	ds_read_b128 v[158:161], v150 offset:1024
	ds_read_b128 v[162:165], v150 offset:2048
	ds_read_b128 v[166:169], v150 offset:3072
	s_add_u32 s28, s26, 0xfff00080
	s_addc_u32 s29, s27, -1
	s_cmp_eq_u32 s58, 60
	s_cselect_b32 s31, s19, s29
	s_cselect_b32 s30, s54, s28
	s_cselect_b32 s29, s17, s57
	s_cselect_b32 s28, s55, s56
	v_lshl_add_u64 v[146:147], s[26:27], 0, v[138:139]
	s_add_i32 m0, s25, 0xc000
	ds_read_b128 v[170:173], v151
	ds_read_b128 v[174:177], v151 offset:1024
	ds_read_b128 v[178:181], v151 offset:2048
	ds_read_b128 v[182:185], v151 offset:3072
	ds_read_b128 v[186:189], v151 offset:4096
	ds_read_b128 v[190:193], v151 offset:5120
	ds_read_b128 v[194:197], v151 offset:6144
	ds_read_b128 v[198:201], v151 offset:7168
	global_load_lds_dwordx4 v[146:147], off
	v_lshl_add_u64 v[146:147], s[26:27], 0, v[140:141]
	s_add_i32 m0, s25, 0xe000
	s_nop 0
	global_load_lds_dwordx4 v[146:147], off
	s_waitcnt lgkmcnt(8)
	s_barrier
	s_nop 0
	s_setprio 1
	s_nop 0
	s_waitcnt lgkmcnt(7)
	v_mfma_f32_16x16x32_bf16 v[126:129], v[154:157], v[170:173], v[126:129]
	v_mfma_f32_16x16x32_bf16 v[122:125], v[162:165], v[170:173], v[122:125]
	s_waitcnt lgkmcnt(5)
	v_mfma_f32_16x16x32_bf16 v[114:117], v[154:157], v[178:181], v[114:117]
	v_mfma_f32_16x16x32_bf16 v[106:109], v[162:165], v[178:181], v[106:109]
	s_waitcnt lgkmcnt(3)
	v_mfma_f32_16x16x32_bf16 v[98:101], v[154:157], v[186:189], v[98:101]
	v_mfma_f32_16x16x32_bf16 v[90:93], v[162:165], v[186:189], v[90:93]
	s_waitcnt lgkmcnt(1)
	v_mfma_f32_16x16x32_bf16 v[82:85], v[154:157], v[194:197], v[82:85]
	v_mfma_f32_16x16x32_bf16 v[74:77], v[162:165], v[194:197], v[74:77]
	v_mfma_f32_16x16x32_bf16 v[126:129], v[158:161], v[174:177], v[126:129]
	v_mfma_f32_16x16x32_bf16 v[122:125], v[166:169], v[174:177], v[122:125]
	v_mfma_f32_16x16x32_bf16 v[114:117], v[158:161], v[182:185], v[114:117]
	v_mfma_f32_16x16x32_bf16 v[106:109], v[166:169], v[182:185], v[106:109]
	v_mfma_f32_16x16x32_bf16 v[98:101], v[158:161], v[190:193], v[98:101]
	v_mfma_f32_16x16x32_bf16 v[90:93], v[166:169], v[190:193], v[90:93]
	s_waitcnt lgkmcnt(0)
	v_mfma_f32_16x16x32_bf16 v[82:85], v[158:161], v[198:201], v[82:85]
	v_mfma_f32_16x16x32_bf16 v[74:77], v[166:169], v[198:201], v[74:77]
	s_setprio 0
	s_barrier
	s_add_i32 s59, s47, s39
	v_lshl_add_u64 v[146:147], s[28:29], 0, v[132:133]
	s_mov_b32 m0, s59
	ds_read_b128 v[202:205], v152
	ds_read_b128 v[206:209], v152 offset:1024
	ds_read_b128 v[210:213], v152 offset:2048
	ds_read_b128 v[214:217], v152 offset:3072
	global_load_lds_dwordx4 v[146:147], off
	v_lshl_add_u64 v[218:219], s[28:29], 0, v[136:137]
	s_add_i32 m0, s59, 0x2000
	s_nop 0
	global_load_lds_dwordx4 v[218:219], off
	s_barrier
	s_nop 0
	s_setprio 1
	s_nop 0
	s_waitcnt lgkmcnt(3)
	v_mfma_f32_16x16x32_bf16 v[118:121], v[202:205], v[170:173], v[118:121]
	s_waitcnt lgkmcnt(1)
	v_mfma_f32_16x16x32_bf16 v[110:113], v[210:213], v[170:173], v[110:113]
	v_mfma_f32_16x16x32_bf16 v[102:105], v[202:205], v[178:181], v[102:105]
	v_mfma_f32_16x16x32_bf16 v[94:97], v[210:213], v[178:181], v[94:97]
	v_mfma_f32_16x16x32_bf16 v[86:89], v[202:205], v[186:189], v[86:89]
	v_mfma_f32_16x16x32_bf16 v[78:81], v[210:213], v[186:189], v[78:81]
	v_mfma_f32_16x16x32_bf16 v[70:73], v[202:205], v[194:197], v[70:73]
	v_mfma_f32_16x16x32_bf16 v[66:69], v[210:213], v[194:197], v[66:69]
	v_mfma_f32_16x16x32_bf16 v[118:121], v[206:209], v[174:177], v[118:121]
	s_waitcnt lgkmcnt(0)
	v_mfma_f32_16x16x32_bf16 v[110:113], v[214:217], v[174:177], v[110:113]
	v_mfma_f32_16x16x32_bf16 v[102:105], v[206:209], v[182:185], v[102:105]
	v_mfma_f32_16x16x32_bf16 v[94:97], v[214:217], v[182:185], v[94:97]
	v_mfma_f32_16x16x32_bf16 v[86:89], v[206:209], v[190:193], v[86:89]
	v_mfma_f32_16x16x32_bf16 v[78:81], v[214:217], v[190:193], v[78:81]
	v_mfma_f32_16x16x32_bf16 v[70:73], v[206:209], v[198:201], v[70:73]
	v_mfma_f32_16x16x32_bf16 v[66:69], v[214:217], v[198:201], v[66:69]
	s_setprio 0
	s_mov_b32 m0, s25
	v_lshl_add_u64 v[220:221], s[30:31], 0, v[130:131]
	s_barrier
	ds_read_b128 v[170:173], v151 offset:16384
	ds_read_b128 v[174:177], v151 offset:17408
	ds_read_b128 v[178:181], v151 offset:18432
	ds_read_b128 v[182:185], v151 offset:19456
	ds_read_b128 v[186:189], v151 offset:20480
	ds_read_b128 v[190:193], v151 offset:21504
	ds_read_b128 v[194:197], v151 offset:22528
	ds_read_b128 v[198:201], v151 offset:23552
	global_load_lds_dwordx4 v[220:221], off
	v_lshl_add_u64 v[222:223], s[30:31], 0, v[134:135]
	s_mov_b32 m0, s40
	s_nop 0
	global_load_lds_dwordx4 v[222:223], off
	s_barrier
	s_nop 0
	s_setprio 1
	s_nop 0
	s_waitcnt lgkmcnt(7)
	v_mfma_f32_16x16x32_bf16 v[62:65], v[154:157], v[170:173], v[62:65]
	v_mfma_f32_16x16x32_bf16 v[58:61], v[162:165], v[170:173], v[58:61]
	s_waitcnt lgkmcnt(5)
	v_mfma_f32_16x16x32_bf16 v[54:57], v[154:157], v[178:181], v[54:57]
	v_mfma_f32_16x16x32_bf16 v[46:49], v[162:165], v[178:181], v[46:49]
	s_waitcnt lgkmcnt(3)
	v_mfma_f32_16x16x32_bf16 v[38:41], v[154:157], v[186:189], v[38:41]
	v_mfma_f32_16x16x32_bf16 v[30:33], v[162:165], v[186:189], v[30:33]
	s_waitcnt lgkmcnt(1)
	v_mfma_f32_16x16x32_bf16 v[22:25], v[154:157], v[194:197], v[22:25]
	v_mfma_f32_16x16x32_bf16 v[14:17], v[162:165], v[194:197], v[14:17]
	v_mfma_f32_16x16x32_bf16 v[62:65], v[158:161], v[174:177], v[62:65]
	v_mfma_f32_16x16x32_bf16 v[58:61], v[166:169], v[174:177], v[58:61]
	v_mfma_f32_16x16x32_bf16 v[54:57], v[158:161], v[182:185], v[54:57]
	v_mfma_f32_16x16x32_bf16 v[46:49], v[166:169], v[182:185], v[46:49]
	v_mfma_f32_16x16x32_bf16 v[38:41], v[158:161], v[190:193], v[38:41]
	v_mfma_f32_16x16x32_bf16 v[30:33], v[166:169], v[190:193], v[30:33]
	s_waitcnt lgkmcnt(0)
	v_mfma_f32_16x16x32_bf16 v[22:25], v[158:161], v[198:201], v[22:25]
	v_mfma_f32_16x16x32_bf16 v[14:17], v[166:169], v[198:201], v[14:17]
	s_setprio 0
	s_barrier
; #define PG8_STAGE(bufoff, gbase, voff) do { _Pragma("unroll") for (int _i = 0; _i < 2; ++_i) \
;         __builtin_amdgcn_global_load_lds((const unsigned*)((const char*)(gbase) + (voff)[_i]), (PG8_LAS unsigned*)(lds + (bufoff) + ldsw + _i * 8192), 16, 0, 0); } while (0)
; #define PG8_LDA(dst, b, h) do { _Pragma("unroll") for (int m = 0; m < 4; ++m) _Pragma("unroll") for (int k = 0; k < 2; ++k) dst[m][k] = *(const PG8_LAS bf16x8*)(lds + PG8_SA(b, h) + aoff + m * 2048 + k * 1024); } while (0)
; #define PG8_LDB(dst, b, h) do { _Pragma("unroll") for (int n = 0; n < 2; ++n) _Pragma("unroll") for (int k = 0; k < 2; ++k) dst[n][k] = *(const PG8_LAS bf16x8*)(lds + PG8_SB(b, h) + boff + n * 2048 + k * 1024); } while (0)
; #define PG8_MMA(ai, bj, At, Bt) do { __builtin_amdgcn_s_setprio(1); _Pragma("unroll") for (int m = 0; m < 4; ++m) _Pragma("unroll") for (int n = 0; n < 2; ++n) _Pragma("unroll") for (int k = 0; k < 2; ++k) \
;         acc[ai][bj][m][n] = __builtin_amdgcn_mfma_f32_16x16x32_bf16(Bt[n][k], At[m][k], acc[ai][bj][m][n], 0, 0, 0); __builtin_amdgcn_s_setprio(0); } while (0)
; #define PG8_WAIT_V(n) asm volatile("s_waitcnt vmcnt(" #n ")" ::: "memory")
; #define PG8_WAIT_L(n) asm volatile("s_waitcnt lgkmcnt(" #n ")" ::: "memory")
; #define PG8_BAR __builtin_amdgcn_s_barrier()
; #define PG8_SCHED __builtin_amdgcn_sched_barrier(0)
; template <class Epi>
; __device__ __forceinline__ void gemm_phase(PG8_LAS unsigned char* lds, const Gemm g, const StaticOrder& S, const Epi& E) {
;     ...
;             PG8_WAIT_V(6); PG8_BAR; PG8_MMA(1, 1, At, B1); PG8_BAR;
;             PG8_LDB(B0, 1, 0); PG8_SCHED; PG8_LDA(At, 1, 0); PG8_STAGE(PG8_SA(0, 1), a2 + hstep, voffA);
;             PG8_WAIT_L(8); PG8_BAR; PG8_WAIT_L(0); PG8_MMA(0, 0, At, B0); PG8_BAR; PG8_SCHED;
;             PG8_LDB(B1, 1, 1); PG8_STAGE(PG8_SB(1, 0), b3, voffB);
;             PG8_BAR; PG8_WAIT_L(0); PG8_MMA(0, 1, At, B1); PG8_BAR;
;             PG8_LDA(At, 1, 1); PG8_STAGE(PG8_SA(1, 0), a3, voffA);
;             PG8_BAR; PG8_WAIT_L(0); PG8_MMA(1, 0, At, B0); PG8_BAR; PG8_SCHED;
	s_add_u32 s60, s28, 0x100000
	s_addc_u32 s61, s29, 0
	s_add_i32 s59, s48, s39
	v_lshl_add_u64 v[154:155], s[60:61], 0, v[132:133]
	s_mov_b32 m0, s59
	s_nop 0
	global_load_lds_dwordx4 v[154:155], off
	v_lshl_add_u64 v[154:155], s[60:61], 0, v[136:137]
	s_add_i32 m0, s59, 0x2000
	s_nop 0
	global_load_lds_dwordx4 v[154:155], off
	s_waitcnt vmcnt(6)
	s_barrier
	s_setprio 1
	v_mfma_f32_16x16x32_bf16 v[50:53], v[202:205], v[170:173], v[50:53]
	v_mfma_f32_16x16x32_bf16 v[42:45], v[210:213], v[170:173], v[42:45]
	v_mfma_f32_16x16x32_bf16 v[34:37], v[202:205], v[178:181], v[34:37]
	v_mfma_f32_16x16x32_bf16 v[26:29], v[210:213], v[178:181], v[26:29]
	v_mfma_f32_16x16x32_bf16 v[18:21], v[202:205], v[186:189], v[18:21]
	v_mfma_f32_16x16x32_bf16 v[10:13], v[210:213], v[186:189], v[10:13]
	v_mfma_f32_16x16x32_bf16 v[6:9], v[202:205], v[194:197], v[6:9]
	v_mfma_f32_16x16x32_bf16 v[2:5], v[210:213], v[194:197], v[2:5]
	v_mfma_f32_16x16x32_bf16 v[50:53], v[206:209], v[174:177], v[50:53]
	v_mfma_f32_16x16x32_bf16 v[42:45], v[214:217], v[174:177], v[42:45]
	v_mfma_f32_16x16x32_bf16 v[34:37], v[206:209], v[182:185], v[34:37]
	v_mfma_f32_16x16x32_bf16 v[26:29], v[214:217], v[182:185], v[26:29]
	v_mfma_f32_16x16x32_bf16 v[18:21], v[206:209], v[190:193], v[18:21]
	v_mfma_f32_16x16x32_bf16 v[10:13], v[214:217], v[190:193], v[10:13]
	v_mfma_f32_16x16x32_bf16 v[6:9], v[206:209], v[198:201], v[6:9]
	v_mfma_f32_16x16x32_bf16 v[2:5], v[214:217], v[198:201], v[2:5]
	s_setprio 0
	s_add_i32 s59, 0, 0x18000
	v_add_u32_e32 v153, s59, v148
	s_barrier
	ds_read_b128 v[154:157], v153
	ds_read_b128 v[158:161], v153 offset:1024
	ds_read_b128 v[162:165], v153 offset:2048
	ds_read_b128 v[166:169], v153 offset:3072
	s_add_u32 s30, s30, 0x100000
	s_addc_u32 s31, s31, 0
	s_mov_b32 m0, s41
	v_lshl_add_u64 v[202:203], s[30:31], 0, v[130:131]
	ds_read_b128 v[170:173], v151 offset:32768
	ds_read_b128 v[174:177], v151 offset:33792
	ds_read_b128 v[178:181], v151 offset:34816
	ds_read_b128 v[182:185], v151 offset:35840
	ds_read_b128 v[186:189], v151 offset:36864
	ds_read_b128 v[190:193], v151 offset:37888
	ds_read_b128 v[194:197], v151 offset:38912
	ds_read_b128 v[198:201], v151 offset:39936
	global_load_lds_dwordx4 v[202:203], off
	v_lshl_add_u64 v[202:203], s[30:31], 0, v[134:135]
	s_mov_b32 m0, s42
	s_nop 0
	global_load_lds_dwordx4 v[202:203], off
	s_waitcnt lgkmcnt(8)
	s_barrier
	s_nop 0
	s_setprio 1
	s_nop 0
	s_waitcnt lgkmcnt(7)
	v_mfma_f32_16x16x32_bf16 v[126:129], v[154:157], v[170:173], v[126:129]
	v_mfma_f32_16x16x32_bf16 v[122:125], v[162:165], v[170:173], v[122:125]
	s_waitcnt lgkmcnt(5)
	v_mfma_f32_16x16x32_bf16 v[114:117], v[154:157], v[178:181], v[114:117]
	v_mfma_f32_16x16x32_bf16 v[106:109], v[162:165], v[178:181], v[106:109]
	s_waitcnt lgkmcnt(3)
	v_mfma_f32_16x16x32_bf16 v[98:101], v[154:157], v[186:189], v[98:101]
	v_mfma_f32_16x16x32_bf16 v[90:93], v[162:165], v[186:189], v[90:93]
	s_waitcnt lgkmcnt(1)
	v_mfma_f32_16x16x32_bf16 v[82:85], v[154:157], v[194:197], v[82:85]
	v_mfma_f32_16x16x32_bf16 v[74:77], v[162:165], v[194:197], v[74:77]
	v_mfma_f32_16x16x32_bf16 v[126:129], v[158:161], v[174:177], v[126:129]
	v_mfma_f32_16x16x32_bf16 v[122:125], v[166:169], v[174:177], v[122:125]
	v_mfma_f32_16x16x32_bf16 v[114:117], v[158:161], v[182:185], v[114:117]
	v_mfma_f32_16x16x32_bf16 v[106:109], v[166:169], v[182:185], v[106:109]
	v_mfma_f32_16x16x32_bf16 v[98:101], v[158:161], v[190:193], v[98:101]
	v_mfma_f32_16x16x32_bf16 v[90:93], v[166:169], v[190:193], v[90:93]
	s_waitcnt lgkmcnt(0)
	v_mfma_f32_16x16x32_bf16 v[82:85], v[158:161], v[198:201], v[82:85]
	v_mfma_f32_16x16x32_bf16 v[74:77], v[166:169], v[198:201], v[74:77]
	s_setprio 0
	s_barrier
	s_add_i32 s30, 0, 0x1c000
	s_add_i32 s31, s59, s39
	v_add_u32_e32 v153, s30, v148
	v_lshl_add_u64 v[146:147], v[146:147], 0, s[6:7]
	s_mov_b32 m0, s31
	ds_read_b128 v[202:205], v153
	ds_read_b128 v[206:209], v153 offset:1024
	ds_read_b128 v[210:213], v153 offset:2048
	ds_read_b128 v[214:217], v153 offset:3072
	global_load_lds_dwordx4 v[146:147], off
	v_lshl_add_u64 v[146:147], v[218:219], 0, s[6:7]
	s_add_i32 m0, s31, 0x2000
	s_nop 0
	global_load_lds_dwordx4 v[146:147], off
	s_barrier
	s_nop 0
	s_setprio 1
	s_nop 0
	s_waitcnt lgkmcnt(3)
	v_mfma_f32_16x16x32_bf16 v[118:121], v[202:205], v[170:173], v[118:121]
	s_waitcnt lgkmcnt(1)
	v_mfma_f32_16x16x32_bf16 v[110:113], v[210:213], v[170:173], v[110:113]
	v_mfma_f32_16x16x32_bf16 v[102:105], v[202:205], v[178:181], v[102:105]
	v_mfma_f32_16x16x32_bf16 v[94:97], v[210:213], v[178:181], v[94:97]
	v_mfma_f32_16x16x32_bf16 v[86:89], v[202:205], v[186:189], v[86:89]
	v_mfma_f32_16x16x32_bf16 v[78:81], v[210:213], v[186:189], v[78:81]
	v_mfma_f32_16x16x32_bf16 v[70:73], v[202:205], v[194:197], v[70:73]
	v_mfma_f32_16x16x32_bf16 v[66:69], v[210:213], v[194:197], v[66:69]
	v_mfma_f32_16x16x32_bf16 v[118:121], v[206:209], v[174:177], v[118:121]
	s_waitcnt lgkmcnt(0)
	v_mfma_f32_16x16x32_bf16 v[110:113], v[214:217], v[174:177], v[110:113]
	v_mfma_f32_16x16x32_bf16 v[102:105], v[206:209], v[182:185], v[102:105]
	v_mfma_f32_16x16x32_bf16 v[94:97], v[214:217], v[182:185], v[94:97]
	v_mfma_f32_16x16x32_bf16 v[86:89], v[206:209], v[190:193], v[86:89]
	v_mfma_f32_16x16x32_bf16 v[78:81], v[214:217], v[190:193], v[78:81]
	v_mfma_f32_16x16x32_bf16 v[70:73], v[206:209], v[198:201], v[70:73]
	v_mfma_f32_16x16x32_bf16 v[66:69], v[214:217], v[198:201], v[66:69]
	s_setprio 0
	s_mov_b32 m0, s44
	v_lshl_add_u64 v[146:147], v[220:221], 0, s[6:7]
	s_barrier
; #define PG8_STAGE(bufoff, gbase, voff) do { _Pragma("unroll") for (int _i = 0; _i < 2; ++_i) \
;         __builtin_amdgcn_global_load_lds((const unsigned*)((const char*)(gbase) + (voff)[_i]), (PG8_LAS unsigned*)(lds + (bufoff) + ldsw + _i * 8192), 16, 0, 0); } while (0)
; #define PG8_LDA(dst, b, h) do { _Pragma("unroll") for (int m = 0; m < 4; ++m) _Pragma("unroll") for (int k = 0; k < 2; ++k) dst[m][k] = *(const PG8_LAS bf16x8*)(lds + PG8_SA(b, h) + aoff + m * 2048 + k * 1024); } while (0)
; #define PG8_MMA(ai, bj, At, Bt) do { __builtin_amdgcn_s_setprio(1); _Pragma("unroll") for (int m = 0; m < 4; ++m) _Pragma("unroll") for (int n = 0; n < 2; ++n) _Pragma("unroll") for (int k = 0; k < 2; ++k) \
;         acc[ai][bj][m][n] = __builtin_amdgcn_mfma_f32_16x16x32_bf16(Bt[n][k], At[m][k], acc[ai][bj][m][n], 0, 0, 0); __builtin_amdgcn_s_setprio(0); } while (0)
; #define PG8_WAIT_V(n) asm volatile("s_waitcnt vmcnt(" #n ")" ::: "memory")
; #define PG8_WAIT_L(n) asm volatile("s_waitcnt lgkmcnt(" #n ")" ::: "memory")
; #define PG8_BAR __builtin_amdgcn_s_barrier()
; #define PG8_SCHED __builtin_amdgcn_sched_barrier(0)
; template <class Epi>
; __device__ __forceinline__ void gemm_phase(PG8_LAS unsigned char* lds, const Gemm g, const StaticOrder& S, const Epi& E) {
;     ...
;             PG8_LDA(At, 1, 1); PG8_STAGE(PG8_SA(1, 0), a3, voffA);
;             PG8_BAR; PG8_WAIT_L(0); PG8_MMA(1, 0, At, B0); PG8_BAR; PG8_SCHED;
;             PG8_STAGE(PG8_SB(1, 1), b3 + hstep, voffB);
;             PG8_WAIT_V(6); PG8_BAR; PG8_MMA(1, 1, At, B1); PG8_BAR;
	ds_read_b128 v[170:173], v151 offset:49152
	ds_read_b128 v[174:177], v151 offset:50176
	ds_read_b128 v[178:181], v151 offset:51200
	ds_read_b128 v[182:185], v151 offset:52224
	ds_read_b128 v[186:189], v151 offset:53248
	ds_read_b128 v[190:193], v151 offset:54272
	ds_read_b128 v[194:197], v151 offset:55296
	ds_read_b128 v[198:201], v151 offset:56320
	global_load_lds_dwordx4 v[146:147], off
	v_lshl_add_u64 v[146:147], v[222:223], 0, s[6:7]
	s_mov_b32 m0, s45
	s_nop 0
	global_load_lds_dwordx4 v[146:147], off
	s_barrier
	s_nop 0
	s_setprio 1
	s_nop 0
	s_waitcnt lgkmcnt(7)
	v_mfma_f32_16x16x32_bf16 v[62:65], v[154:157], v[170:173], v[62:65]
	v_mfma_f32_16x16x32_bf16 v[58:61], v[162:165], v[170:173], v[58:61]
	s_waitcnt lgkmcnt(5)
	v_mfma_f32_16x16x32_bf16 v[54:57], v[154:157], v[178:181], v[54:57]
	v_mfma_f32_16x16x32_bf16 v[46:49], v[162:165], v[178:181], v[46:49]
	s_waitcnt lgkmcnt(3)
	v_mfma_f32_16x16x32_bf16 v[38:41], v[154:157], v[186:189], v[38:41]
	v_mfma_f32_16x16x32_bf16 v[30:33], v[162:165], v[186:189], v[30:33]
	s_waitcnt lgkmcnt(1)
	v_mfma_f32_16x16x32_bf16 v[22:25], v[154:157], v[194:197], v[22:25]
	v_mfma_f32_16x16x32_bf16 v[14:17], v[162:165], v[194:197], v[14:17]
	v_mfma_f32_16x16x32_bf16 v[62:65], v[158:161], v[174:177], v[62:65]
	v_mfma_f32_16x16x32_bf16 v[58:61], v[166:169], v[174:177], v[58:61]
	v_mfma_f32_16x16x32_bf16 v[54:57], v[158:161], v[182:185], v[54:57]
	v_mfma_f32_16x16x32_bf16 v[46:49], v[166:169], v[182:185], v[46:49]
	v_mfma_f32_16x16x32_bf16 v[38:41], v[158:161], v[190:193], v[38:41]
	v_mfma_f32_16x16x32_bf16 v[30:33], v[166:169], v[190:193], v[30:33]
	s_waitcnt lgkmcnt(0)
	v_mfma_f32_16x16x32_bf16 v[22:25], v[158:161], v[198:201], v[22:25]
	v_mfma_f32_16x16x32_bf16 v[14:17], v[166:169], v[198:201], v[14:17]
	s_setprio 0
	s_barrier
	s_add_u32 s28, s28, 0x100080
	s_addc_u32 s29, s29, 0
	s_add_i32 s30, s30, s39
	v_lshl_add_u64 v[146:147], s[28:29], 0, v[132:133]
	s_mov_b32 m0, s30
	s_nop 0
	global_load_lds_dwordx4 v[146:147], off
	v_lshl_add_u64 v[146:147], s[28:29], 0, v[136:137]
	s_add_i32 m0, s30, 0x2000
	s_nop 0
	global_load_lds_dwordx4 v[146:147], off
	s_waitcnt vmcnt(6)
	s_barrier
	s_setprio 1
	v_mfma_f32_16x16x32_bf16 v[50:53], v[202:205], v[170:173], v[50:53]
	v_mfma_f32_16x16x32_bf16 v[42:45], v[210:213], v[170:173], v[42:45]
	v_mfma_f32_16x16x32_bf16 v[34:37], v[202:205], v[178:181], v[34:37]
	v_mfma_f32_16x16x32_bf16 v[26:29], v[210:213], v[178:181], v[26:29]
	v_mfma_f32_16x16x32_bf16 v[18:21], v[202:205], v[186:189], v[18:21]
	v_mfma_f32_16x16x32_bf16 v[10:13], v[210:213], v[186:189], v[10:13]
	v_mfma_f32_16x16x32_bf16 v[6:9], v[202:205], v[194:197], v[6:9]
	v_mfma_f32_16x16x32_bf16 v[2:5], v[210:213], v[194:197], v[2:5]
	v_mfma_f32_16x16x32_bf16 v[50:53], v[206:209], v[174:177], v[50:53]
	v_mfma_f32_16x16x32_bf16 v[42:45], v[214:217], v[174:177], v[42:45]
	v_mfma_f32_16x16x32_bf16 v[34:37], v[206:209], v[182:185], v[34:37]
	v_mfma_f32_16x16x32_bf16 v[26:29], v[214:217], v[182:185], v[26:29]
	v_mfma_f32_16x16x32_bf16 v[18:21], v[206:209], v[190:193], v[18:21]
	v_mfma_f32_16x16x32_bf16 v[10:13], v[214:217], v[190:193], v[10:13]
	v_mfma_f32_16x16x32_bf16 v[6:9], v[206:209], v[198:201], v[6:9]
	v_mfma_f32_16x16x32_bf16 v[2:5], v[214:217], v[198:201], v[2:5]
	s_setprio 0
	s_add_i32 s58, s58, 2
	s_add_u32 s26, s26, 0x100
	s_addc_u32 s27, s27, 0
	s_add_u32 s56, s56, 0x100
	s_addc_u32 s57, s57, 0
	s_cmp_gt_u32 s58, 61
	s_barrier
	s_cbranch_scc0 .LBB0_653
; __device__ __forceinline__ unsigned pk2(float lo, float hi) { unsigned r; asm volatile("v_cvt_pk_bf16_f32 %0, %1, %2" : "=v"(r) : "v"(lo), "v"(hi)); return r; }
;     __device__ __forceinline__ void operator()(const f32x4 (&acc)[2][2][4][2], const Unit& u, int wr, int wc, int fr, int fq) const {
;         const int row0 = u.pm * BM + wr * 64 + fr, col0 = u.pn * BM + wc * 32 + 8 * fq;
; #pragma unroll
;         for (int ai = 0; ai < 2; ++ai)
; #pragma unroll
;             for (int m = 0; m < 4; ++m)
; #pragma unroll
;                 for (int bj = 0; bj < 2; ++bj) f(row0 + ai * HALF + m * 16, col0 + bj * HALF, acc[ai][bj][m][0], acc[ai][bj][m][1]);
; __device__ __forceinline__ void store8bf(u16* dst, f32x4 v0, f32x4 v1) { u32x4 w; w.x = pk2(v0[0], v0[1]); w.y = pk2(v0[2], v0[3]); w.z = pk2(v1[0], v1[1]); w.w = pk2(v1[2], v1[3]); *(u32x4*)dst = w; }
	v_lshl_add_u32 v154, s24, 8, v1
	v_lshl_or_b32 v146, s53, 8, v149
	v_ashrrev_i32_e32 v155, 31, v154
	v_lshlrev_b64 v[156:157], 12, v[154:155]
	v_ashrrev_i32_e32 v147, 31, v146
	v_lshl_add_u64 v[156:157], s[4:5], 0, v[156:157]
	v_lshlrev_b64 v[158:159], 1, v[146:147]
	v_lshl_add_u64 v[146:147], v[156:157], 0, v[158:159]
	v_cvt_pk_bf16_f32 v126, v126, v127
	v_cvt_pk_bf16_f32 v127, v128, v129
	v_cvt_pk_bf16_f32 v128, v122, v123
	v_cvt_pk_bf16_f32 v129, v124, v125
	global_store_dwordx4 v[146:147], v[126:129], off
	v_cvt_pk_bf16_f32 v118, v118, v119
	v_cvt_pk_bf16_f32 v119, v120, v121
	v_cvt_pk_bf16_f32 v120, v110, v111
	v_or_b32_e32 v110, 16, v154
	v_ashrrev_i32_e32 v111, 31, v110
	v_lshlrev_b64 v[110:111], 12, v[110:111]
	v_lshl_add_u64 v[110:111], s[4:5], 0, v[110:111]
	v_cvt_pk_bf16_f32 v121, v112, v113
	global_store_dwordx4 v[146:147], v[118:121], off offset:256
	s_mov_b32 s53, s16
	s_mov_b32 s24, s18
	v_lshl_add_u64 v[118:119], v[110:111], 0, v[158:159]
	v_cvt_pk_bf16_f32 v110, v114, v115
	v_cvt_pk_bf16_f32 v111, v116, v117
	v_cvt_pk_bf16_f32 v112, v106, v107
	v_cvt_pk_bf16_f32 v113, v108, v109
	global_store_dwordx4 v[118:119], v[110:113], off
	v_cvt_pk_bf16_f32 v102, v102, v103
	v_cvt_pk_bf16_f32 v103, v104, v105
	v_cvt_pk_bf16_f32 v104, v94, v95
	v_or_b32_e32 v94, 32, v154
	v_ashrrev_i32_e32 v95, 31, v94
	v_lshlrev_b64 v[94:95], 12, v[94:95]
	v_lshl_add_u64 v[94:95], s[4:5], 0, v[94:95]
	v_cvt_pk_bf16_f32 v105, v96, v97
	global_store_dwordx4 v[118:119], v[102:105], off offset:256
	s_mov_b64 s[28:29], s[22:23]
	s_mov_b64 s[26:27], s[20:21]
	v_lshl_add_u64 v[102:103], v[94:95], 0, v[158:159]
	v_cvt_pk_bf16_f32 v94, v98, v99
	v_cvt_pk_bf16_f32 v95, v100, v101
	v_cvt_pk_bf16_f32 v96, v90, v91
	v_cvt_pk_bf16_f32 v97, v92, v93
	global_store_dwordx4 v[102:103], v[94:97], off
	v_cvt_pk_bf16_f32 v86, v86, v87
	v_cvt_pk_bf16_f32 v87, v88, v89
	v_cvt_pk_bf16_f32 v88, v78, v79
	v_or_b32_e32 v78, 48, v154
	v_ashrrev_i32_e32 v79, 31, v78
	v_lshlrev_b64 v[78:79], 12, v[78:79]
	v_lshl_add_u64 v[78:79], s[4:5], 0, v[78:79]
	v_cvt_pk_bf16_f32 v89, v80, v81
	global_store_dwordx4 v[102:103], v[86:89], off offset:256
	s_nop 1
	v_lshl_add_u64 v[86:87], v[78:79], 0, v[158:159]
	v_cvt_pk_bf16_f32 v78, v82, v83
	v_cvt_pk_bf16_f32 v79, v84, v85
	v_cvt_pk_bf16_f32 v80, v74, v75
	v_cvt_pk_bf16_f32 v81, v76, v77
	global_store_dwordx4 v[86:87], v[78:81], off
	v_cvt_pk_bf16_f32 v70, v70, v71
	v_cvt_pk_bf16_f32 v71, v72, v73
	v_cvt_pk_bf16_f32 v72, v66, v67
	v_cvt_pk_bf16_f32 v73, v68, v69
	global_store_dwordx4 v[86:87], v[70:73], off offset:256
	v_cvt_pk_bf16_f32 v62, v62, v63
	v_cvt_pk_bf16_f32 v63, v64, v65
	v_cvt_pk_bf16_f32 v64, v58, v59
	v_add_co_u32_e32 v58, vcc, s49, v146
	v_lshl_add_u64 v[66:67], v[146:147], 0, s[8:9]
	s_nop 0
	v_addc_co_u32_e32 v59, vcc, 0, v147, vcc
	v_cvt_pk_bf16_f32 v65, v60, v61
	global_store_dwordx4 v[58:59], v[62:65], off
	v_cvt_pk_bf16_f32 v50, v50, v51
	v_cvt_pk_bf16_f32 v51, v52, v53
	v_cvt_pk_bf16_f32 v52, v42, v43
	v_cvt_pk_bf16_f32 v53, v44, v45
	global_store_dwordx4 v[66:67], v[50:53], off offset:256
	v_cvt_pk_bf16_f32 v42, v54, v55
	v_cvt_pk_bf16_f32 v43, v56, v57
	v_cvt_pk_bf16_f32 v44, v46, v47
	v_add_co_u32_e32 v46, vcc, s50, v146
	s_nop 0
	v_lshl_add_u64 v[50:51], v[146:147], 0, s[10:11]
	v_addc_co_u32_e32 v47, vcc, 0, v147, vcc
	v_cvt_pk_bf16_f32 v45, v48, v49
	global_store_dwordx4 v[46:47], v[42:45], off
	v_cvt_pk_bf16_f32 v34, v34, v35
	v_cvt_pk_bf16_f32 v35, v36, v37
	v_cvt_pk_bf16_f32 v36, v26, v27
	v_cvt_pk_bf16_f32 v37, v28, v29
	global_store_dwordx4 v[50:51], v[34:37], off offset:256
	v_cvt_pk_bf16_f32 v26, v38, v39
	v_cvt_pk_bf16_f32 v27, v40, v41
	v_cvt_pk_bf16_f32 v28, v30, v31
	v_add_co_u32_e32 v30, vcc, s51, v146
	s_nop 0
	v_lshl_add_u64 v[34:35], v[146:147], 0, s[12:13]
	v_addc_co_u32_e32 v31, vcc, 0, v147, vcc
	v_cvt_pk_bf16_f32 v29, v32, v33
	global_store_dwordx4 v[30:31], v[26:29], off
	v_cvt_pk_bf16_f32 v18, v18, v19
	v_cvt_pk_bf16_f32 v19, v20, v21
	v_cvt_pk_bf16_f32 v20, v10, v11
	v_cvt_pk_bf16_f32 v21, v12, v13
	global_store_dwordx4 v[34:35], v[18:21], off offset:256
	v_cvt_pk_bf16_f32 v10, v22, v23
	v_cvt_pk_bf16_f32 v11, v24, v25
	v_cvt_pk_bf16_f32 v12, v14, v15
	v_add_co_u32_e32 v14, vcc, s52, v146
	s_nop 0
	v_lshl_add_u64 v[18:19], v[146:147], 0, s[14:15]
	v_addc_co_u32_e32 v15, vcc, 0, v147, vcc
	s_and_b64 vcc, exec, s[2:3]
	v_cvt_pk_bf16_f32 v13, v16, v17
	global_store_dwordx4 v[14:15], v[10:13], off
	v_cvt_pk_bf16_f32 v6, v6, v7
	v_cvt_pk_bf16_f32 v7, v8, v9
	v_cvt_pk_bf16_f32 v8, v2, v3
	v_cvt_pk_bf16_f32 v9, v4, v5
	global_store_dwordx4 v[18:19], v[6:9], off offset:256
	s_cbranch_vccz .LBB0_646
	s_waitcnt vmcnt(0)
	s_cmpk_gt_u32 s33, 0xff
	s_cbranch_scc1 .LBB0_657
	s_barrier

; #define PG8_STAGE(bufoff, gbase, voff) do { _Pragma("unroll") for (int _i = 0; _i < 2; ++_i) \
;         __builtin_amdgcn_global_load_lds((const unsigned*)((const char*)(gbase) + (voff)[_i]), (PG8_LAS unsigned*)(lds + (bufoff) + ldsw + _i * 8192), 16, 0, 0); } while (0)
; #define PG8_LDA(dst, b, h) do { _Pragma("unroll") for (int m = 0; m < 4; ++m) _Pragma("unroll") for (int k = 0; k < 2; ++k) dst[m][k] = *(const PG8_LAS bf16x8*)(lds + PG8_SA(b, h) + aoff + m * 2048 + k * 1024); } while (0)
; #define PG8_LDB(dst, b, h) do { _Pragma("unroll") for (int n = 0; n < 2; ++n) _Pragma("unroll") for (int k = 0; k < 2; ++k) dst[n][k] = *(const PG8_LAS bf16x8*)(lds + PG8_SB(b, h) + boff + n * 2048 + k * 1024); } while (0)
; #define PG8_MMA(ai, bj, At, Bt) do { __builtin_amdgcn_s_setprio(1); _Pragma("unroll") for (int m = 0; m < 4; ++m) _Pragma("unroll") for (int n = 0; n < 2; ++n) _Pragma("unroll") for (int k = 0; k < 2; ++k) \
;         acc[ai][bj][m][n] = __builtin_amdgcn_mfma_f32_16x16x32_bf16(Bt[n][k], At[m][k], acc[ai][bj][m][n], 0, 0, 0); __builtin_amdgcn_s_setprio(0); } while (0)
; #define PG8_WAIT_L(n) asm volatile("s_waitcnt lgkmcnt(" #n ")" ::: "memory")
; #define PG8_BAR __builtin_amdgcn_s_barrier()
; #define PG8_SCHED __builtin_amdgcn_sched_barrier(0)
; template <class Epi>
; __device__ __forceinline__ void gemm_phase(PG8_LAS unsigned char* lds, const Gemm g, const StaticOrder& S, const Epi& E) {
;     ...
;             PG8_LDB(B0, 0, 0); PG8_SCHED; PG8_LDA(At, 0, 0); PG8_STAGE(PG8_SA(1, 1), a1 + hstep, voffA);
;             PG8_WAIT_L(8); PG8_BAR; PG8_WAIT_L(0); PG8_MMA(0, 0, At, B0); PG8_BAR; PG8_SCHED;
;             PG8_LDB(B1, 0, 1); PG8_STAGE(PG8_SB(0, 0), b2, voffB);
;             PG8_BAR; PG8_WAIT_L(0); PG8_MMA(0, 1, At, B1); PG8_BAR;
;             PG8_LDA(At, 0, 1); PG8_STAGE(PG8_SA(0, 0), a2, voffA);
;             PG8_BAR; PG8_WAIT_L(0); PG8_MMA(1, 0, At, B0); PG8_BAR; PG8_SCHED;
.LBB0_722:
	ds_read_b128 v[150:153], v159
	ds_read_b128 v[154:157], v159 offset:1024
	ds_read_b128 v[162:165], v159 offset:2048
	ds_read_b128 v[166:169], v159 offset:3072
	s_add_u32 s22, s20, 0xfff80080
	s_addc_u32 s23, s21, -1
	s_cmp_eq_u32 s50, 28
	s_cselect_b32 s25, s3, s23
	s_cselect_b32 s24, s5, s22
	s_cselect_b32 s23, s13, s49
	s_cselect_b32 s22, s15, s48
	v_lshl_add_u64 v[202:203], s[20:21], 0, v[142:143]
	s_add_i32 m0, s30, 0xc000
	ds_read_b128 v[170:173], v160
	ds_read_b128 v[174:177], v160 offset:1024
	ds_read_b128 v[178:181], v160 offset:2048
	ds_read_b128 v[182:185], v160 offset:3072
	ds_read_b128 v[186:189], v160 offset:4096
	ds_read_b128 v[190:193], v160 offset:5120
	ds_read_b128 v[194:197], v160 offset:6144
	ds_read_b128 v[198:201], v160 offset:7168
	global_load_lds_dwordx4 v[202:203], off
	v_lshl_add_u64 v[202:203], s[20:21], 0, v[144:145]
	s_add_i32 m0, s30, 0xe000
	s_nop 0
	global_load_lds_dwordx4 v[202:203], off
	s_waitcnt lgkmcnt(8)
	s_barrier
	s_nop 0
	s_setprio 1
	s_nop 0
	s_waitcnt lgkmcnt(7)
	v_mfma_f32_16x16x32_bf16 v[126:129], v[150:153], v[170:173], v[126:129]
	v_mfma_f32_16x16x32_bf16 v[122:125], v[162:165], v[170:173], v[122:125]
	s_waitcnt lgkmcnt(5)
	v_mfma_f32_16x16x32_bf16 v[110:113], v[150:153], v[178:181], v[110:113]
	v_mfma_f32_16x16x32_bf16 v[106:109], v[162:165], v[178:181], v[106:109]
	s_waitcnt lgkmcnt(3)
	v_mfma_f32_16x16x32_bf16 v[94:97], v[150:153], v[186:189], v[94:97]
	v_mfma_f32_16x16x32_bf16 v[90:93], v[162:165], v[186:189], v[90:93]
	s_waitcnt lgkmcnt(1)
	v_mfma_f32_16x16x32_bf16 v[78:81], v[150:153], v[194:197], v[78:81]
	v_mfma_f32_16x16x32_bf16 v[74:77], v[162:165], v[194:197], v[74:77]
	v_mfma_f32_16x16x32_bf16 v[126:129], v[154:157], v[174:177], v[126:129]
	v_mfma_f32_16x16x32_bf16 v[122:125], v[166:169], v[174:177], v[122:125]
	v_mfma_f32_16x16x32_bf16 v[110:113], v[154:157], v[182:185], v[110:113]
	v_mfma_f32_16x16x32_bf16 v[106:109], v[166:169], v[182:185], v[106:109]
	v_mfma_f32_16x16x32_bf16 v[94:97], v[154:157], v[190:193], v[94:97]
	v_mfma_f32_16x16x32_bf16 v[90:93], v[166:169], v[190:193], v[90:93]
	s_waitcnt lgkmcnt(0)
	v_mfma_f32_16x16x32_bf16 v[78:81], v[154:157], v[198:201], v[78:81]
	v_mfma_f32_16x16x32_bf16 v[74:77], v[166:169], v[198:201], v[74:77]
	s_setprio 0
	s_barrier
	s_add_i32 s51, s43, s29
	v_lshl_add_u64 v[218:219], s[22:23], 0, v[134:135]
	s_mov_b32 m0, s51
	ds_read_b128 v[202:205], v161
	ds_read_b128 v[206:209], v161 offset:1024
	ds_read_b128 v[210:213], v161 offset:2048
	ds_read_b128 v[214:217], v161 offset:3072
	global_load_lds_dwordx4 v[218:219], off
	v_lshl_add_u64 v[220:221], s[22:23], 0, v[138:139]
	s_add_i32 m0, s51, 0x2000
	s_nop 0
	global_load_lds_dwordx4 v[220:221], off
	s_barrier
	s_nop 0
	s_setprio 1
	s_nop 0
	s_waitcnt lgkmcnt(3)
	v_mfma_f32_16x16x32_bf16 v[118:121], v[202:205], v[170:173], v[118:121]
	s_waitcnt lgkmcnt(1)
	v_mfma_f32_16x16x32_bf16 v[114:117], v[210:213], v[170:173], v[114:117]
	v_mfma_f32_16x16x32_bf16 v[102:105], v[202:205], v[178:181], v[102:105]
	v_mfma_f32_16x16x32_bf16 v[98:101], v[210:213], v[178:181], v[98:101]
	v_mfma_f32_16x16x32_bf16 v[86:89], v[202:205], v[186:189], v[86:89]
	v_mfma_f32_16x16x32_bf16 v[82:85], v[210:213], v[186:189], v[82:85]
	v_mfma_f32_16x16x32_bf16 v[70:73], v[202:205], v[194:197], v[70:73]
	v_mfma_f32_16x16x32_bf16 v[66:69], v[210:213], v[194:197], v[66:69]
	v_mfma_f32_16x16x32_bf16 v[118:121], v[206:209], v[174:177], v[118:121]
	s_waitcnt lgkmcnt(0)
	v_mfma_f32_16x16x32_bf16 v[114:117], v[214:217], v[174:177], v[114:117]
	v_mfma_f32_16x16x32_bf16 v[102:105], v[206:209], v[182:185], v[102:105]
	v_mfma_f32_16x16x32_bf16 v[98:101], v[214:217], v[182:185], v[98:101]
	v_mfma_f32_16x16x32_bf16 v[86:89], v[206:209], v[190:193], v[86:89]
	v_mfma_f32_16x16x32_bf16 v[82:85], v[214:217], v[190:193], v[82:85]
	v_mfma_f32_16x16x32_bf16 v[70:73], v[206:209], v[198:201], v[70:73]
	v_mfma_f32_16x16x32_bf16 v[66:69], v[214:217], v[198:201], v[66:69]
	s_setprio 0
	s_mov_b32 m0, s30
	v_lshl_add_u64 v[222:223], s[24:25], 0, v[132:133]
	s_barrier
	ds_read_b128 v[170:173], v160 offset:16384
	ds_read_b128 v[174:177], v160 offset:17408
	ds_read_b128 v[178:181], v160 offset:18432
	ds_read_b128 v[182:185], v160 offset:19456
	ds_read_b128 v[186:189], v160 offset:20480
	ds_read_b128 v[190:193], v160 offset:21504
	ds_read_b128 v[194:197], v160 offset:22528
	ds_read_b128 v[198:201], v160 offset:23552
	global_load_lds_dwordx4 v[222:223], off
	v_lshl_add_u64 v[224:225], s[24:25], 0, v[136:137]
	s_mov_b32 m0, s31
	s_nop 0
	global_load_lds_dwordx4 v[224:225], off
	s_barrier
	s_nop 0
	s_setprio 1
	s_nop 0
	s_waitcnt lgkmcnt(7)
	v_mfma_f32_16x16x32_bf16 v[62:65], v[150:153], v[170:173], v[62:65]
	v_mfma_f32_16x16x32_bf16 v[58:61], v[162:165], v[170:173], v[58:61]
	s_waitcnt lgkmcnt(5)
	v_mfma_f32_16x16x32_bf16 v[46:49], v[150:153], v[178:181], v[46:49]
	v_mfma_f32_16x16x32_bf16 v[42:45], v[162:165], v[178:181], v[42:45]
	s_waitcnt lgkmcnt(3)
	v_mfma_f32_16x16x32_bf16 v[30:33], v[150:153], v[186:189], v[30:33]
	v_mfma_f32_16x16x32_bf16 v[26:29], v[162:165], v[186:189], v[26:29]
	s_waitcnt lgkmcnt(1)
	v_mfma_f32_16x16x32_bf16 v[14:17], v[150:153], v[194:197], v[14:17]
	v_mfma_f32_16x16x32_bf16 v[10:13], v[162:165], v[194:197], v[10:13]
	v_mfma_f32_16x16x32_bf16 v[62:65], v[154:157], v[174:177], v[62:65]
	v_mfma_f32_16x16x32_bf16 v[58:61], v[166:169], v[174:177], v[58:61]
	v_mfma_f32_16x16x32_bf16 v[46:49], v[154:157], v[182:185], v[46:49]
	v_mfma_f32_16x16x32_bf16 v[42:45], v[166:169], v[182:185], v[42:45]
	v_mfma_f32_16x16x32_bf16 v[30:33], v[154:157], v[190:193], v[30:33]
	v_mfma_f32_16x16x32_bf16 v[26:29], v[166:169], v[190:193], v[26:29]
	s_waitcnt lgkmcnt(0)
	v_mfma_f32_16x16x32_bf16 v[14:17], v[154:157], v[198:201], v[14:17]
	v_mfma_f32_16x16x32_bf16 v[10:13], v[166:169], v[198:201], v[10:13]
	s_setprio 0
	s_barrier
; #define PG8_STAGE(bufoff, gbase, voff) do { _Pragma("unroll") for (int _i = 0; _i < 2; ++_i) \
;         __builtin_amdgcn_global_load_lds((const unsigned*)((const char*)(gbase) + (voff)[_i]), (PG8_LAS unsigned*)(lds + (bufoff) + ldsw + _i * 8192), 16, 0, 0); } while (0)
; #define PG8_LDA(dst, b, h) do { _Pragma("unroll") for (int m = 0; m < 4; ++m) _Pragma("unroll") for (int k = 0; k < 2; ++k) dst[m][k] = *(const PG8_LAS bf16x8*)(lds + PG8_SA(b, h) + aoff + m * 2048 + k * 1024); } while (0)
; #define PG8_LDB(dst, b, h) do { _Pragma("unroll") for (int n = 0; n < 2; ++n) _Pragma("unroll") for (int k = 0; k < 2; ++k) dst[n][k] = *(const PG8_LAS bf16x8*)(lds + PG8_SB(b, h) + boff + n * 2048 + k * 1024); } while (0)
; #define PG8_MMA(ai, bj, At, Bt) do { __builtin_amdgcn_s_setprio(1); _Pragma("unroll") for (int m = 0; m < 4; ++m) _Pragma("unroll") for (int n = 0; n < 2; ++n) _Pragma("unroll") for (int k = 0; k < 2; ++k) \
;         acc[ai][bj][m][n] = __builtin_amdgcn_mfma_f32_16x16x32_bf16(Bt[n][k], At[m][k], acc[ai][bj][m][n], 0, 0, 0); __builtin_amdgcn_s_setprio(0); } while (0)
; #define PG8_WAIT_V(n) asm volatile("s_waitcnt vmcnt(" #n ")" ::: "memory")
; #define PG8_WAIT_L(n) asm volatile("s_waitcnt lgkmcnt(" #n ")" ::: "memory")
; #define PG8_BAR __builtin_amdgcn_s_barrier()
; #define PG8_SCHED __builtin_amdgcn_sched_barrier(0)
; template <class Epi>
; __device__ __forceinline__ void gemm_phase(PG8_LAS unsigned char* lds, const Gemm g, const StaticOrder& S, const Epi& E) {
;     ...
;             PG8_STAGE(PG8_SB(0, 1), b2 + hstep, voffB);
;             PG8_WAIT_V(6); PG8_BAR; PG8_MMA(1, 1, At, B1); PG8_BAR;
;             PG8_LDB(B0, 1, 0); PG8_SCHED; PG8_LDA(At, 1, 0); PG8_STAGE(PG8_SA(0, 1), a2 + hstep, voffA);
;             PG8_WAIT_L(8); PG8_BAR; PG8_WAIT_L(0); PG8_MMA(0, 0, At, B0); PG8_BAR; PG8_SCHED;
;             PG8_LDB(B1, 1, 1); PG8_STAGE(PG8_SB(1, 0), b3, voffB);
;             PG8_BAR; PG8_WAIT_L(0); PG8_MMA(0, 1, At, B1); PG8_BAR;
	s_add_u32 s52, s22, 0x80000
	s_addc_u32 s53, s23, 0
	s_add_i32 s51, s44, s29
	v_lshl_add_u64 v[150:151], s[52:53], 0, v[134:135]
	s_mov_b32 m0, s51
	s_nop 0
	global_load_lds_dwordx4 v[150:151], off
	v_lshl_add_u64 v[150:151], s[52:53], 0, v[138:139]
	s_add_i32 m0, s51, 0x2000
	s_nop 0
	global_load_lds_dwordx4 v[150:151], off
	s_waitcnt vmcnt(6)
	s_barrier
	s_setprio 1
	v_mfma_f32_16x16x32_bf16 v[54:57], v[202:205], v[170:173], v[54:57]
	v_mfma_f32_16x16x32_bf16 v[50:53], v[210:213], v[170:173], v[50:53]
	v_mfma_f32_16x16x32_bf16 v[38:41], v[202:205], v[178:181], v[38:41]
	v_mfma_f32_16x16x32_bf16 v[34:37], v[210:213], v[178:181], v[34:37]
	v_mfma_f32_16x16x32_bf16 v[22:25], v[202:205], v[186:189], v[22:25]
	v_mfma_f32_16x16x32_bf16 v[18:21], v[210:213], v[186:189], v[18:21]
	v_mfma_f32_16x16x32_bf16 v[6:9], v[202:205], v[194:197], v[6:9]
	v_mfma_f32_16x16x32_bf16 v[2:5], v[210:213], v[194:197], v[2:5]
	v_mfma_f32_16x16x32_bf16 v[54:57], v[206:209], v[174:177], v[54:57]
	v_mfma_f32_16x16x32_bf16 v[50:53], v[214:217], v[174:177], v[50:53]
	v_mfma_f32_16x16x32_bf16 v[38:41], v[206:209], v[182:185], v[38:41]
	v_mfma_f32_16x16x32_bf16 v[34:37], v[214:217], v[182:185], v[34:37]
	v_mfma_f32_16x16x32_bf16 v[22:25], v[206:209], v[190:193], v[22:25]
	v_mfma_f32_16x16x32_bf16 v[18:21], v[214:217], v[190:193], v[18:21]
	v_mfma_f32_16x16x32_bf16 v[6:9], v[206:209], v[198:201], v[6:9]
	v_mfma_f32_16x16x32_bf16 v[2:5], v[214:217], v[198:201], v[2:5]
	s_setprio 0
	s_add_i32 s51, 0, 0x18000
	v_add_u32_e32 v140, s51, v131
	s_barrier
	ds_read_b128 v[150:153], v140
	ds_read_b128 v[154:157], v140 offset:1024
	ds_read_b128 v[162:165], v140 offset:2048
	ds_read_b128 v[166:169], v140 offset:3072
	s_add_u32 s24, s24, 0x80000
	s_addc_u32 s25, s25, 0
	s_mov_b32 m0, s33
	v_lshl_add_u64 v[202:203], s[24:25], 0, v[132:133]
	ds_read_b128 v[170:173], v160 offset:32768
	ds_read_b128 v[174:177], v160 offset:33792
	ds_read_b128 v[178:181], v160 offset:34816
	ds_read_b128 v[182:185], v160 offset:35840
	ds_read_b128 v[186:189], v160 offset:36864
	ds_read_b128 v[190:193], v160 offset:37888
	ds_read_b128 v[194:197], v160 offset:38912
	ds_read_b128 v[198:201], v160 offset:39936
	global_load_lds_dwordx4 v[202:203], off
	v_lshl_add_u64 v[202:203], s[24:25], 0, v[136:137]
	s_mov_b32 m0, s34
	s_nop 0
	global_load_lds_dwordx4 v[202:203], off
	s_waitcnt lgkmcnt(8)
	s_barrier
	s_nop 0
	s_setprio 1
	s_nop 0
	s_waitcnt lgkmcnt(7)
	v_mfma_f32_16x16x32_bf16 v[126:129], v[150:153], v[170:173], v[126:129]
	v_mfma_f32_16x16x32_bf16 v[122:125], v[162:165], v[170:173], v[122:125]
	s_waitcnt lgkmcnt(5)
	v_mfma_f32_16x16x32_bf16 v[110:113], v[150:153], v[178:181], v[110:113]
	v_mfma_f32_16x16x32_bf16 v[106:109], v[162:165], v[178:181], v[106:109]
	s_waitcnt lgkmcnt(3)
	v_mfma_f32_16x16x32_bf16 v[94:97], v[150:153], v[186:189], v[94:97]
	v_mfma_f32_16x16x32_bf16 v[90:93], v[162:165], v[186:189], v[90:93]
	s_waitcnt lgkmcnt(1)
	v_mfma_f32_16x16x32_bf16 v[78:81], v[150:153], v[194:197], v[78:81]
	v_mfma_f32_16x16x32_bf16 v[74:77], v[162:165], v[194:197], v[74:77]
	v_mfma_f32_16x16x32_bf16 v[126:129], v[154:157], v[174:177], v[126:129]
	v_mfma_f32_16x16x32_bf16 v[122:125], v[166:169], v[174:177], v[122:125]
	v_mfma_f32_16x16x32_bf16 v[110:113], v[154:157], v[182:185], v[110:113]
	v_mfma_f32_16x16x32_bf16 v[106:109], v[166:169], v[182:185], v[106:109]
	v_mfma_f32_16x16x32_bf16 v[94:97], v[154:157], v[190:193], v[94:97]
	v_mfma_f32_16x16x32_bf16 v[90:93], v[166:169], v[190:193], v[90:93]
	s_waitcnt lgkmcnt(0)
	v_mfma_f32_16x16x32_bf16 v[78:81], v[154:157], v[198:201], v[78:81]
	v_mfma_f32_16x16x32_bf16 v[74:77], v[166:169], v[198:201], v[74:77]
	s_setprio 0
	s_barrier
	s_add_i32 s24, 0, 0x1c000
	s_add_i32 s25, s51, s29
	v_add_u32_e32 v140, s24, v131
	v_lshl_add_u64 v[218:219], v[218:219], 0, s[10:11]
	s_mov_b32 m0, s25
	ds_read_b128 v[202:205], v140
	ds_read_b128 v[206:209], v140 offset:1024
	ds_read_b128 v[210:213], v140 offset:2048
	ds_read_b128 v[214:217], v140 offset:3072
	global_load_lds_dwordx4 v[218:219], off
	v_lshl_add_u64 v[218:219], v[220:221], 0, s[10:11]
	s_add_i32 m0, s25, 0x2000
	s_nop 0
	global_load_lds_dwordx4 v[218:219], off
	s_barrier
	s_nop 0
	s_setprio 1
	s_nop 0
	s_waitcnt lgkmcnt(3)
	v_mfma_f32_16x16x32_bf16 v[118:121], v[202:205], v[170:173], v[118:121]
	s_waitcnt lgkmcnt(1)
	v_mfma_f32_16x16x32_bf16 v[114:117], v[210:213], v[170:173], v[114:117]
	v_mfma_f32_16x16x32_bf16 v[102:105], v[202:205], v[178:181], v[102:105]
	v_mfma_f32_16x16x32_bf16 v[98:101], v[210:213], v[178:181], v[98:101]
	v_mfma_f32_16x16x32_bf16 v[86:89], v[202:205], v[186:189], v[86:89]
	v_mfma_f32_16x16x32_bf16 v[82:85], v[210:213], v[186:189], v[82:85]
	v_mfma_f32_16x16x32_bf16 v[70:73], v[202:205], v[194:197], v[70:73]
	v_mfma_f32_16x16x32_bf16 v[66:69], v[210:213], v[194:197], v[66:69]
	v_mfma_f32_16x16x32_bf16 v[118:121], v[206:209], v[174:177], v[118:121]
	s_waitcnt lgkmcnt(0)
	v_mfma_f32_16x16x32_bf16 v[114:117], v[214:217], v[174:177], v[114:117]
	v_mfma_f32_16x16x32_bf16 v[102:105], v[206:209], v[182:185], v[102:105]
	v_mfma_f32_16x16x32_bf16 v[98:101], v[214:217], v[182:185], v[98:101]
	v_mfma_f32_16x16x32_bf16 v[86:89], v[206:209], v[190:193], v[86:89]
	v_mfma_f32_16x16x32_bf16 v[82:85], v[214:217], v[190:193], v[82:85]
	v_mfma_f32_16x16x32_bf16 v[70:73], v[206:209], v[198:201], v[70:73]
	v_mfma_f32_16x16x32_bf16 v[66:69], v[214:217], v[198:201], v[66:69]
	s_setprio 0
	s_mov_b32 m0, s38
	v_lshl_add_u64 v[218:219], v[222:223], 0, s[10:11]
	s_barrier
; #define PG8_STAGE(bufoff, gbase, voff) do { _Pragma("unroll") for (int _i = 0; _i < 2; ++_i) \
;         __builtin_amdgcn_global_load_lds((const unsigned*)((const char*)(gbase) + (voff)[_i]), (PG8_LAS unsigned*)(lds + (bufoff) + ldsw + _i * 8192), 16, 0, 0); } while (0)
; #define PG8_LDA(dst, b, h) do { _Pragma("unroll") for (int m = 0; m < 4; ++m) _Pragma("unroll") for (int k = 0; k < 2; ++k) dst[m][k] = *(const PG8_LAS bf16x8*)(lds + PG8_SA(b, h) + aoff + m * 2048 + k * 1024); } while (0)
; #define PG8_MMA(ai, bj, At, Bt) do { __builtin_amdgcn_s_setprio(1); _Pragma("unroll") for (int m = 0; m < 4; ++m) _Pragma("unroll") for (int n = 0; n < 2; ++n) _Pragma("unroll") for (int k = 0; k < 2; ++k) \
;         acc[ai][bj][m][n] = __builtin_amdgcn_mfma_f32_16x16x32_bf16(Bt[n][k], At[m][k], acc[ai][bj][m][n], 0, 0, 0); __builtin_amdgcn_s_setprio(0); } while (0)
; #define PG8_WAIT_V(n) asm volatile("s_waitcnt vmcnt(" #n ")" ::: "memory")
; #define PG8_WAIT_L(n) asm volatile("s_waitcnt lgkmcnt(" #n ")" ::: "memory")
; #define PG8_BAR __builtin_amdgcn_s_barrier()
; #define PG8_SCHED __builtin_amdgcn_sched_barrier(0)
; template <class Epi>
; __device__ __forceinline__ void gemm_phase(PG8_LAS unsigned char* lds, const Gemm g, const StaticOrder& S, const Epi& E) {
;     ...
;             PG8_LDA(At, 1, 1); PG8_STAGE(PG8_SA(1, 0), a3, voffA);
;             PG8_BAR; PG8_WAIT_L(0); PG8_MMA(1, 0, At, B0); PG8_BAR; PG8_SCHED;
;             PG8_STAGE(PG8_SB(1, 1), b3 + hstep, voffB);
;             PG8_WAIT_V(6); PG8_BAR; PG8_MMA(1, 1, At, B1); PG8_BAR;
	ds_read_b128 v[170:173], v160 offset:49152
	ds_read_b128 v[174:177], v160 offset:50176
	ds_read_b128 v[178:181], v160 offset:51200
	ds_read_b128 v[182:185], v160 offset:52224
	ds_read_b128 v[186:189], v160 offset:53248
	ds_read_b128 v[190:193], v160 offset:54272
	ds_read_b128 v[194:197], v160 offset:55296
	ds_read_b128 v[198:201], v160 offset:56320
	global_load_lds_dwordx4 v[218:219], off
	v_lshl_add_u64 v[218:219], v[224:225], 0, s[10:11]
	s_mov_b32 m0, s39
	s_nop 0
	global_load_lds_dwordx4 v[218:219], off
	s_barrier
	s_nop 0
	s_setprio 1
	s_nop 0
	s_waitcnt lgkmcnt(7)
	v_mfma_f32_16x16x32_bf16 v[62:65], v[150:153], v[170:173], v[62:65]
	v_mfma_f32_16x16x32_bf16 v[58:61], v[162:165], v[170:173], v[58:61]
	s_waitcnt lgkmcnt(5)
	v_mfma_f32_16x16x32_bf16 v[46:49], v[150:153], v[178:181], v[46:49]
	v_mfma_f32_16x16x32_bf16 v[42:45], v[162:165], v[178:181], v[42:45]
	s_waitcnt lgkmcnt(3)
	v_mfma_f32_16x16x32_bf16 v[30:33], v[150:153], v[186:189], v[30:33]
	v_mfma_f32_16x16x32_bf16 v[26:29], v[162:165], v[186:189], v[26:29]
	s_waitcnt lgkmcnt(1)
	v_mfma_f32_16x16x32_bf16 v[14:17], v[150:153], v[194:197], v[14:17]
	v_mfma_f32_16x16x32_bf16 v[10:13], v[162:165], v[194:197], v[10:13]
	v_mfma_f32_16x16x32_bf16 v[62:65], v[154:157], v[174:177], v[62:65]
	v_mfma_f32_16x16x32_bf16 v[58:61], v[166:169], v[174:177], v[58:61]
	v_mfma_f32_16x16x32_bf16 v[46:49], v[154:157], v[182:185], v[46:49]
	v_mfma_f32_16x16x32_bf16 v[42:45], v[166:169], v[182:185], v[42:45]
	v_mfma_f32_16x16x32_bf16 v[30:33], v[154:157], v[190:193], v[30:33]
	v_mfma_f32_16x16x32_bf16 v[26:29], v[166:169], v[190:193], v[26:29]
	s_waitcnt lgkmcnt(0)
	v_mfma_f32_16x16x32_bf16 v[14:17], v[154:157], v[198:201], v[14:17]
	v_mfma_f32_16x16x32_bf16 v[10:13], v[166:169], v[198:201], v[10:13]
	s_setprio 0
	s_barrier
	s_add_u32 s22, s22, 0x80080
	s_addc_u32 s23, s23, 0
	s_add_i32 s24, s24, s29
	v_lshl_add_u64 v[150:151], s[22:23], 0, v[134:135]
	s_mov_b32 m0, s24
	s_nop 0
	global_load_lds_dwordx4 v[150:151], off
	v_lshl_add_u64 v[150:151], s[22:23], 0, v[138:139]
	s_add_i32 m0, s24, 0x2000
	s_nop 0
	global_load_lds_dwordx4 v[150:151], off
	s_waitcnt vmcnt(6)
	s_barrier
	s_setprio 1
	v_mfma_f32_16x16x32_bf16 v[54:57], v[202:205], v[170:173], v[54:57]
	v_mfma_f32_16x16x32_bf16 v[50:53], v[210:213], v[170:173], v[50:53]
	v_mfma_f32_16x16x32_bf16 v[38:41], v[202:205], v[178:181], v[38:41]
	v_mfma_f32_16x16x32_bf16 v[34:37], v[210:213], v[178:181], v[34:37]
	v_mfma_f32_16x16x32_bf16 v[22:25], v[202:205], v[186:189], v[22:25]
	v_mfma_f32_16x16x32_bf16 v[18:21], v[210:213], v[186:189], v[18:21]
	v_mfma_f32_16x16x32_bf16 v[6:9], v[202:205], v[194:197], v[6:9]
	v_mfma_f32_16x16x32_bf16 v[2:5], v[210:213], v[194:197], v[2:5]
	v_mfma_f32_16x16x32_bf16 v[54:57], v[206:209], v[174:177], v[54:57]
	v_mfma_f32_16x16x32_bf16 v[50:53], v[214:217], v[174:177], v[50:53]
	v_mfma_f32_16x16x32_bf16 v[38:41], v[206:209], v[182:185], v[38:41]
	v_mfma_f32_16x16x32_bf16 v[34:37], v[214:217], v[182:185], v[34:37]
	v_mfma_f32_16x16x32_bf16 v[22:25], v[206:209], v[190:193], v[22:25]
	v_mfma_f32_16x16x32_bf16 v[18:21], v[214:217], v[190:193], v[18:21]
	v_mfma_f32_16x16x32_bf16 v[6:9], v[206:209], v[198:201], v[6:9]
	v_mfma_f32_16x16x32_bf16 v[2:5], v[214:217], v[198:201], v[2:5]
	s_setprio 0
	s_add_i32 s50, s50, 2
	s_add_u32 s20, s20, 0x100
	s_addc_u32 s21, s21, 0
	s_add_u32 s48, s48, 0x100
	s_addc_u32 s49, s49, 0
	s_cmp_gt_u32 s50, 29
	s_barrier
	s_cbranch_scc0 .LBB0_722
	v_lshl_add_u32 v152, s2, 8, v1
	s_lshl_b32 s13, s4, 8
	v_or_b32_e32 v150, s13, v158
	v_mad_i64_i32 v[154:155], s[2:3], v152, s45, 0
	v_cmp_lt_i32_e64 s[2:3], s46, v150
	s_and_saveexec_b64 s[20:21], s[2:3]
	s_xor_b64 s[20:21], exec, s[20:21]
	s_cbranch_execz .LBB0_726
	s_cmpk_gt_u32 s13, 0x317f
	s_cbranch_scc1 .LBB0_726
	v_lshl_add_u64 v[156:157], s[8:9], 0, v[154:155]
	v_mov_b32_e32 v151, v141
	v_lshl_add_u64 v[156:157], v[150:151], 1, v[156:157]
	v_add_co_u32_e32 v156, vcc, 0xffffa000, v156
	v_cvt_pk_bf16_f32 v162, v126, v127
	v_cvt_pk_bf16_f32 v163, v128, v129
	v_cvt_pk_bf16_f32 v164, v122, v123
	v_cvt_pk_bf16_f32 v165, v124, v125
	s_nop 1
	v_addc_co_u32_e32 v157, vcc, -1, v157, vcc
	global_store_dwordx4 v[156:157], v[162:165], off

; #define PG8_STAGE(bufoff, gbase, voff) do { _Pragma("unroll") for (int _i = 0; _i < 2; ++_i) \
;         __builtin_amdgcn_global_load_lds((const unsigned*)((const char*)(gbase) + (voff)[_i]), (PG8_LAS unsigned*)(lds + (bufoff) + ldsw + _i * 8192), 16, 0, 0); } while (0)
; #define PG8_LDA(dst, b, h) do { _Pragma("unroll") for (int m = 0; m < 4; ++m) _Pragma("unroll") for (int k = 0; k < 2; ++k) dst[m][k] = *(const PG8_LAS bf16x8*)(lds + PG8_SA(b, h) + aoff + m * 2048 + k * 1024); } while (0)
; #define PG8_LDB(dst, b, h) do { _Pragma("unroll") for (int n = 0; n < 2; ++n) _Pragma("unroll") for (int k = 0; k < 2; ++k) dst[n][k] = *(const PG8_LAS bf16x8*)(lds + PG8_SB(b, h) + boff + n * 2048 + k * 1024); } while (0)
; #define PG8_MMA(ai, bj, At, Bt) do { __builtin_amdgcn_s_setprio(1); _Pragma("unroll") for (int m = 0; m < 4; ++m) _Pragma("unroll") for (int n = 0; n < 2; ++n) _Pragma("unroll") for (int k = 0; k < 2; ++k) \
;         acc[ai][bj][m][n] = __builtin_amdgcn_mfma_f32_16x16x32_bf16(Bt[n][k], At[m][k], acc[ai][bj][m][n], 0, 0, 0); __builtin_amdgcn_s_setprio(0); } while (0)
; #define PG8_WAIT_L(n) asm volatile("s_waitcnt lgkmcnt(" #n ")" ::: "memory")
; #define PG8_BAR __builtin_amdgcn_s_barrier()
; #define PG8_SCHED __builtin_amdgcn_sched_barrier(0)
; template <class Epi>
; __device__ __forceinline__ void gemm_phase(PG8_LAS unsigned char* lds, const Gemm g, const StaticOrder& S, const Epi& E) {
;     ...
;             PG8_LDB(B0, 0, 0); PG8_SCHED; PG8_LDA(At, 0, 0); PG8_STAGE(PG8_SA(1, 1), a1 + hstep, voffA);
;             PG8_WAIT_L(8); PG8_BAR; PG8_WAIT_L(0); PG8_MMA(0, 0, At, B0); PG8_BAR; PG8_SCHED;
;             PG8_LDB(B1, 0, 1); PG8_STAGE(PG8_SB(0, 0), b2, voffB);
;             PG8_BAR; PG8_WAIT_L(0); PG8_MMA(0, 1, At, B1); PG8_BAR;
;             PG8_LDA(At, 0, 1); PG8_STAGE(PG8_SA(0, 0), a2, voffA);
;             PG8_BAR; PG8_WAIT_L(0); PG8_MMA(1, 0, At, B0); PG8_BAR; PG8_SCHED;
.LBB0_1056:
	ds_read_b128 v[148:151], v155
	ds_read_b128 v[158:161], v155 offset:1024
	ds_read_b128 v[162:165], v155 offset:2048
	ds_read_b128 v[166:169], v155 offset:3072
	s_add_u32 s6, s4, 0xfff80080
	s_addc_u32 s7, s5, -1
	s_cmp_eq_u32 s56, 28
	s_cselect_b32 s31, s25, s7
	s_cselect_b32 s30, s52, s6
	s_cselect_b32 s7, s23, s55
	s_cselect_b32 s6, s53, s54
	v_lshl_add_u64 v[152:153], s[4:5], 0, v[140:141]
	s_add_i32 m0, s38, 0xc000
	ds_read_b128 v[170:173], v156
	ds_read_b128 v[174:177], v156 offset:1024
	ds_read_b128 v[178:181], v156 offset:2048
	ds_read_b128 v[182:185], v156 offset:3072
	ds_read_b128 v[186:189], v156 offset:4096
	ds_read_b128 v[190:193], v156 offset:5120
	ds_read_b128 v[194:197], v156 offset:6144
	ds_read_b128 v[198:201], v156 offset:7168
	global_load_lds_dwordx4 v[152:153], off
	v_lshl_add_u64 v[152:153], s[4:5], 0, v[142:143]
	s_add_i32 m0, s38, 0xe000
	s_nop 0
	global_load_lds_dwordx4 v[152:153], off
	s_waitcnt lgkmcnt(8)
	s_barrier
	s_nop 0
	s_setprio 1
	s_nop 0
	s_waitcnt lgkmcnt(7)
	v_mfma_f32_16x16x32_bf16 v[126:129], v[148:151], v[170:173], v[126:129]
	v_mfma_f32_16x16x32_bf16 v[122:125], v[162:165], v[170:173], v[122:125]
	s_waitcnt lgkmcnt(5)
	v_mfma_f32_16x16x32_bf16 v[110:113], v[148:151], v[178:181], v[110:113]
	v_mfma_f32_16x16x32_bf16 v[106:109], v[162:165], v[178:181], v[106:109]
	s_waitcnt lgkmcnt(3)
	v_mfma_f32_16x16x32_bf16 v[94:97], v[148:151], v[186:189], v[94:97]
	v_mfma_f32_16x16x32_bf16 v[90:93], v[162:165], v[186:189], v[90:93]
	s_waitcnt lgkmcnt(1)
	v_mfma_f32_16x16x32_bf16 v[78:81], v[148:151], v[194:197], v[78:81]
	v_mfma_f32_16x16x32_bf16 v[74:77], v[162:165], v[194:197], v[74:77]
	v_mfma_f32_16x16x32_bf16 v[126:129], v[158:161], v[174:177], v[126:129]
	v_mfma_f32_16x16x32_bf16 v[122:125], v[166:169], v[174:177], v[122:125]
	v_mfma_f32_16x16x32_bf16 v[110:113], v[158:161], v[182:185], v[110:113]
	v_mfma_f32_16x16x32_bf16 v[106:109], v[166:169], v[182:185], v[106:109]
	v_mfma_f32_16x16x32_bf16 v[94:97], v[158:161], v[190:193], v[94:97]
	v_mfma_f32_16x16x32_bf16 v[90:93], v[166:169], v[190:193], v[90:93]
	s_waitcnt lgkmcnt(0)
	v_mfma_f32_16x16x32_bf16 v[78:81], v[158:161], v[198:201], v[78:81]
	v_mfma_f32_16x16x32_bf16 v[74:77], v[166:169], v[198:201], v[74:77]
	s_setprio 0
	s_barrier
	s_add_i32 s57, s46, s37
	v_lshl_add_u64 v[152:153], s[6:7], 0, v[134:135]
	s_mov_b32 m0, s57
	ds_read_b128 v[202:205], v157
	ds_read_b128 v[206:209], v157 offset:1024
	ds_read_b128 v[210:213], v157 offset:2048
	ds_read_b128 v[214:217], v157 offset:3072
	global_load_lds_dwordx4 v[152:153], off
	v_lshl_add_u64 v[218:219], s[6:7], 0, v[138:139]
	s_add_i32 m0, s57, 0x2000
	s_nop 0
	global_load_lds_dwordx4 v[218:219], off
	s_barrier
	s_nop 0
	s_setprio 1
	s_nop 0
	s_waitcnt lgkmcnt(3)
	v_mfma_f32_16x16x32_bf16 v[118:121], v[202:205], v[170:173], v[118:121]
	s_waitcnt lgkmcnt(1)
	v_mfma_f32_16x16x32_bf16 v[114:117], v[210:213], v[170:173], v[114:117]
	v_mfma_f32_16x16x32_bf16 v[102:105], v[202:205], v[178:181], v[102:105]
	v_mfma_f32_16x16x32_bf16 v[98:101], v[210:213], v[178:181], v[98:101]
	v_mfma_f32_16x16x32_bf16 v[86:89], v[202:205], v[186:189], v[86:89]
	v_mfma_f32_16x16x32_bf16 v[82:85], v[210:213], v[186:189], v[82:85]
	v_mfma_f32_16x16x32_bf16 v[70:73], v[202:205], v[194:197], v[70:73]
	v_mfma_f32_16x16x32_bf16 v[66:69], v[210:213], v[194:197], v[66:69]
	v_mfma_f32_16x16x32_bf16 v[118:121], v[206:209], v[174:177], v[118:121]
	s_waitcnt lgkmcnt(0)
	v_mfma_f32_16x16x32_bf16 v[114:117], v[214:217], v[174:177], v[114:117]
	v_mfma_f32_16x16x32_bf16 v[102:105], v[206:209], v[182:185], v[102:105]
	v_mfma_f32_16x16x32_bf16 v[98:101], v[214:217], v[182:185], v[98:101]
	v_mfma_f32_16x16x32_bf16 v[86:89], v[206:209], v[190:193], v[86:89]
	v_mfma_f32_16x16x32_bf16 v[82:85], v[214:217], v[190:193], v[82:85]
	v_mfma_f32_16x16x32_bf16 v[70:73], v[206:209], v[198:201], v[70:73]
	v_mfma_f32_16x16x32_bf16 v[66:69], v[214:217], v[198:201], v[66:69]
	s_setprio 0
	s_mov_b32 m0, s38
	v_lshl_add_u64 v[220:221], s[30:31], 0, v[132:133]
	s_barrier
	ds_read_b128 v[170:173], v156 offset:16384
	ds_read_b128 v[174:177], v156 offset:17408
	ds_read_b128 v[178:181], v156 offset:18432
	ds_read_b128 v[182:185], v156 offset:19456
	ds_read_b128 v[186:189], v156 offset:20480
	ds_read_b128 v[190:193], v156 offset:21504
	ds_read_b128 v[194:197], v156 offset:22528
	ds_read_b128 v[198:201], v156 offset:23552
	global_load_lds_dwordx4 v[220:221], off
	v_lshl_add_u64 v[222:223], s[30:31], 0, v[136:137]
	s_mov_b32 m0, s39
	s_nop 0
	global_load_lds_dwordx4 v[222:223], off
	s_barrier
	s_nop 0
	s_setprio 1
	s_nop 0
	s_waitcnt lgkmcnt(7)
	v_mfma_f32_16x16x32_bf16 v[62:65], v[148:151], v[170:173], v[62:65]
	v_mfma_f32_16x16x32_bf16 v[58:61], v[162:165], v[170:173], v[58:61]
	s_waitcnt lgkmcnt(5)
	v_mfma_f32_16x16x32_bf16 v[46:49], v[148:151], v[178:181], v[46:49]
	v_mfma_f32_16x16x32_bf16 v[42:45], v[162:165], v[178:181], v[42:45]
	s_waitcnt lgkmcnt(3)
	v_mfma_f32_16x16x32_bf16 v[30:33], v[148:151], v[186:189], v[30:33]
	v_mfma_f32_16x16x32_bf16 v[26:29], v[162:165], v[186:189], v[26:29]
	s_waitcnt lgkmcnt(1)
	v_mfma_f32_16x16x32_bf16 v[14:17], v[148:151], v[194:197], v[14:17]
	v_mfma_f32_16x16x32_bf16 v[10:13], v[162:165], v[194:197], v[10:13]
	v_mfma_f32_16x16x32_bf16 v[62:65], v[158:161], v[174:177], v[62:65]
	v_mfma_f32_16x16x32_bf16 v[58:61], v[166:169], v[174:177], v[58:61]
	v_mfma_f32_16x16x32_bf16 v[46:49], v[158:161], v[182:185], v[46:49]
	v_mfma_f32_16x16x32_bf16 v[42:45], v[166:169], v[182:185], v[42:45]
	v_mfma_f32_16x16x32_bf16 v[30:33], v[158:161], v[190:193], v[30:33]
	v_mfma_f32_16x16x32_bf16 v[26:29], v[166:169], v[190:193], v[26:29]
	s_waitcnt lgkmcnt(0)
	v_mfma_f32_16x16x32_bf16 v[14:17], v[158:161], v[198:201], v[14:17]
	v_mfma_f32_16x16x32_bf16 v[10:13], v[166:169], v[198:201], v[10:13]
	s_setprio 0
	s_barrier
; #define PG8_STAGE(bufoff, gbase, voff) do { _Pragma("unroll") for (int _i = 0; _i < 2; ++_i) \
;         __builtin_amdgcn_global_load_lds((const unsigned*)((const char*)(gbase) + (voff)[_i]), (PG8_LAS unsigned*)(lds + (bufoff) + ldsw + _i * 8192), 16, 0, 0); } while (0)
; #define PG8_LDA(dst, b, h) do { _Pragma("unroll") for (int m = 0; m < 4; ++m) _Pragma("unroll") for (int k = 0; k < 2; ++k) dst[m][k] = *(const PG8_LAS bf16x8*)(lds + PG8_SA(b, h) + aoff + m * 2048 + k * 1024); } while (0)
; #define PG8_LDB(dst, b, h) do { _Pragma("unroll") for (int n = 0; n < 2; ++n) _Pragma("unroll") for (int k = 0; k < 2; ++k) dst[n][k] = *(const PG8_LAS bf16x8*)(lds + PG8_SB(b, h) + boff + n * 2048 + k * 1024); } while (0)
; #define PG8_MMA(ai, bj, At, Bt) do { __builtin_amdgcn_s_setprio(1); _Pragma("unroll") for (int m = 0; m < 4; ++m) _Pragma("unroll") for (int n = 0; n < 2; ++n) _Pragma("unroll") for (int k = 0; k < 2; ++k) \
;         acc[ai][bj][m][n] = __builtin_amdgcn_mfma_f32_16x16x32_bf16(Bt[n][k], At[m][k], acc[ai][bj][m][n], 0, 0, 0); __builtin_amdgcn_s_setprio(0); } while (0)
; #define PG8_WAIT_V(n) asm volatile("s_waitcnt vmcnt(" #n ")" ::: "memory")
; #define PG8_WAIT_L(n) asm volatile("s_waitcnt lgkmcnt(" #n ")" ::: "memory")
; #define PG8_BAR __builtin_amdgcn_s_barrier()
; #define PG8_SCHED __builtin_amdgcn_sched_barrier(0)
; template <class Epi>
; __device__ __forceinline__ void gemm_phase(PG8_LAS unsigned char* lds, const Gemm g, const StaticOrder& S, const Epi& E) {
;     ...
;             PG8_STAGE(PG8_SB(0, 1), b2 + hstep, voffB);
;             PG8_WAIT_V(6); PG8_BAR; PG8_MMA(1, 1, At, B1); PG8_BAR;
;             PG8_LDB(B0, 1, 0); PG8_SCHED; PG8_LDA(At, 1, 0); PG8_STAGE(PG8_SA(0, 1), a2 + hstep, voffA);
;             PG8_WAIT_L(8); PG8_BAR; PG8_WAIT_L(0); PG8_MMA(0, 0, At, B0); PG8_BAR; PG8_SCHED;
;             PG8_LDB(B1, 1, 1); PG8_STAGE(PG8_SB(1, 0), b3, voffB);
;             PG8_BAR; PG8_WAIT_L(0); PG8_MMA(0, 1, At, B1); PG8_BAR;
	s_add_u32 s58, s6, 0x80000
	s_addc_u32 s59, s7, 0
	s_add_i32 s57, s47, s37
	v_lshl_add_u64 v[148:149], s[58:59], 0, v[134:135]
	s_mov_b32 m0, s57
	s_nop 0
	global_load_lds_dwordx4 v[148:149], off
	v_lshl_add_u64 v[148:149], s[58:59], 0, v[138:139]
	s_add_i32 m0, s57, 0x2000
	s_nop 0
	global_load_lds_dwordx4 v[148:149], off
	s_waitcnt vmcnt(6)
	s_barrier
	s_setprio 1
	v_mfma_f32_16x16x32_bf16 v[54:57], v[202:205], v[170:173], v[54:57]
	v_mfma_f32_16x16x32_bf16 v[50:53], v[210:213], v[170:173], v[50:53]
	v_mfma_f32_16x16x32_bf16 v[38:41], v[202:205], v[178:181], v[38:41]
	v_mfma_f32_16x16x32_bf16 v[34:37], v[210:213], v[178:181], v[34:37]
	v_mfma_f32_16x16x32_bf16 v[22:25], v[202:205], v[186:189], v[22:25]
	v_mfma_f32_16x16x32_bf16 v[18:21], v[210:213], v[186:189], v[18:21]
	v_mfma_f32_16x16x32_bf16 v[6:9], v[202:205], v[194:197], v[6:9]
	v_mfma_f32_16x16x32_bf16 v[2:5], v[210:213], v[194:197], v[2:5]
	v_mfma_f32_16x16x32_bf16 v[54:57], v[206:209], v[174:177], v[54:57]
	v_mfma_f32_16x16x32_bf16 v[50:53], v[214:217], v[174:177], v[50:53]
	v_mfma_f32_16x16x32_bf16 v[38:41], v[206:209], v[182:185], v[38:41]
	v_mfma_f32_16x16x32_bf16 v[34:37], v[214:217], v[182:185], v[34:37]
	v_mfma_f32_16x16x32_bf16 v[22:25], v[206:209], v[190:193], v[22:25]
	v_mfma_f32_16x16x32_bf16 v[18:21], v[214:217], v[190:193], v[18:21]
	v_mfma_f32_16x16x32_bf16 v[6:9], v[206:209], v[198:201], v[6:9]
	v_mfma_f32_16x16x32_bf16 v[2:5], v[214:217], v[198:201], v[2:5]
	s_setprio 0
	s_add_i32 s57, 0, 0x18000
	v_add_u32_e32 v166, s57, v131
	s_barrier
	ds_read_b128 v[148:151], v166
	ds_read_b128 v[158:161], v166 offset:1024
	ds_read_b128 v[162:165], v166 offset:2048
	ds_read_b128 v[166:169], v166 offset:3072
	s_add_u32 s30, s30, 0x80000
	s_addc_u32 s31, s31, 0
	s_mov_b32 m0, s40
	v_lshl_add_u64 v[202:203], s[30:31], 0, v[132:133]
	ds_read_b128 v[170:173], v156 offset:32768
	ds_read_b128 v[174:177], v156 offset:33792
	ds_read_b128 v[178:181], v156 offset:34816
	ds_read_b128 v[182:185], v156 offset:35840
	ds_read_b128 v[186:189], v156 offset:36864
	ds_read_b128 v[190:193], v156 offset:37888
	ds_read_b128 v[194:197], v156 offset:38912
	ds_read_b128 v[198:201], v156 offset:39936
	global_load_lds_dwordx4 v[202:203], off
	v_lshl_add_u64 v[202:203], s[30:31], 0, v[136:137]
	s_mov_b32 m0, s41
	s_nop 0
	global_load_lds_dwordx4 v[202:203], off
	s_waitcnt lgkmcnt(8)
	s_barrier
	s_nop 0
	s_setprio 1
	s_nop 0
	s_waitcnt lgkmcnt(7)
	v_mfma_f32_16x16x32_bf16 v[126:129], v[148:151], v[170:173], v[126:129]
	v_mfma_f32_16x16x32_bf16 v[122:125], v[162:165], v[170:173], v[122:125]
	s_waitcnt lgkmcnt(5)
	v_mfma_f32_16x16x32_bf16 v[110:113], v[148:151], v[178:181], v[110:113]
	v_mfma_f32_16x16x32_bf16 v[106:109], v[162:165], v[178:181], v[106:109]
	s_waitcnt lgkmcnt(3)
	v_mfma_f32_16x16x32_bf16 v[94:97], v[148:151], v[186:189], v[94:97]
	v_mfma_f32_16x16x32_bf16 v[90:93], v[162:165], v[186:189], v[90:93]
	s_waitcnt lgkmcnt(1)
	v_mfma_f32_16x16x32_bf16 v[78:81], v[148:151], v[194:197], v[78:81]
	v_mfma_f32_16x16x32_bf16 v[74:77], v[162:165], v[194:197], v[74:77]
	v_mfma_f32_16x16x32_bf16 v[126:129], v[158:161], v[174:177], v[126:129]
	v_mfma_f32_16x16x32_bf16 v[122:125], v[166:169], v[174:177], v[122:125]
	v_mfma_f32_16x16x32_bf16 v[110:113], v[158:161], v[182:185], v[110:113]
	v_mfma_f32_16x16x32_bf16 v[106:109], v[166:169], v[182:185], v[106:109]
	v_mfma_f32_16x16x32_bf16 v[94:97], v[158:161], v[190:193], v[94:97]
	v_mfma_f32_16x16x32_bf16 v[90:93], v[166:169], v[190:193], v[90:93]
	s_waitcnt lgkmcnt(0)
	v_mfma_f32_16x16x32_bf16 v[78:81], v[158:161], v[198:201], v[78:81]
	v_mfma_f32_16x16x32_bf16 v[74:77], v[166:169], v[198:201], v[74:77]
	s_setprio 0
	s_barrier
	s_add_i32 s30, 0, 0x1c000
	s_add_i32 s31, s57, s37
	v_add_u32_e32 v214, s30, v131
	v_lshl_add_u64 v[152:153], v[152:153], 0, s[12:13]
	s_mov_b32 m0, s31
	ds_read_b128 v[202:205], v214
	ds_read_b128 v[206:209], v214 offset:1024
	ds_read_b128 v[210:213], v214 offset:2048
	ds_read_b128 v[214:217], v214 offset:3072
	global_load_lds_dwordx4 v[152:153], off
	v_lshl_add_u64 v[152:153], v[218:219], 0, s[12:13]
	s_add_i32 m0, s31, 0x2000
	s_nop 0
	global_load_lds_dwordx4 v[152:153], off
	s_barrier
	s_nop 0
	s_setprio 1
	s_nop 0
	s_waitcnt lgkmcnt(3)
	v_mfma_f32_16x16x32_bf16 v[118:121], v[202:205], v[170:173], v[118:121]
	s_waitcnt lgkmcnt(1)
	v_mfma_f32_16x16x32_bf16 v[114:117], v[210:213], v[170:173], v[114:117]
	v_mfma_f32_16x16x32_bf16 v[102:105], v[202:205], v[178:181], v[102:105]
	v_mfma_f32_16x16x32_bf16 v[98:101], v[210:213], v[178:181], v[98:101]
	v_mfma_f32_16x16x32_bf16 v[86:89], v[202:205], v[186:189], v[86:89]
	v_mfma_f32_16x16x32_bf16 v[82:85], v[210:213], v[186:189], v[82:85]
	v_mfma_f32_16x16x32_bf16 v[70:73], v[202:205], v[194:197], v[70:73]
	v_mfma_f32_16x16x32_bf16 v[66:69], v[210:213], v[194:197], v[66:69]
	v_mfma_f32_16x16x32_bf16 v[118:121], v[206:209], v[174:177], v[118:121]
	s_waitcnt lgkmcnt(0)
	v_mfma_f32_16x16x32_bf16 v[114:117], v[214:217], v[174:177], v[114:117]
	v_mfma_f32_16x16x32_bf16 v[102:105], v[206:209], v[182:185], v[102:105]
	v_mfma_f32_16x16x32_bf16 v[98:101], v[214:217], v[182:185], v[98:101]
	v_mfma_f32_16x16x32_bf16 v[86:89], v[206:209], v[190:193], v[86:89]
	v_mfma_f32_16x16x32_bf16 v[82:85], v[214:217], v[190:193], v[82:85]
	v_mfma_f32_16x16x32_bf16 v[70:73], v[206:209], v[198:201], v[70:73]
	v_mfma_f32_16x16x32_bf16 v[66:69], v[214:217], v[198:201], v[66:69]
	s_setprio 0
	s_mov_b32 m0, s43
	v_lshl_add_u64 v[152:153], v[220:221], 0, s[12:13]
	s_barrier
; #define PG8_STAGE(bufoff, gbase, voff) do { _Pragma("unroll") for (int _i = 0; _i < 2; ++_i) \
;         __builtin_amdgcn_global_load_lds((const unsigned*)((const char*)(gbase) + (voff)[_i]), (PG8_LAS unsigned*)(lds + (bufoff) + ldsw + _i * 8192), 16, 0, 0); } while (0)
; #define PG8_LDA(dst, b, h) do { _Pragma("unroll") for (int m = 0; m < 4; ++m) _Pragma("unroll") for (int k = 0; k < 2; ++k) dst[m][k] = *(const PG8_LAS bf16x8*)(lds + PG8_SA(b, h) + aoff + m * 2048 + k * 1024); } while (0)
; #define PG8_MMA(ai, bj, At, Bt) do { __builtin_amdgcn_s_setprio(1); _Pragma("unroll") for (int m = 0; m < 4; ++m) _Pragma("unroll") for (int n = 0; n < 2; ++n) _Pragma("unroll") for (int k = 0; k < 2; ++k) \
;         acc[ai][bj][m][n] = __builtin_amdgcn_mfma_f32_16x16x32_bf16(Bt[n][k], At[m][k], acc[ai][bj][m][n], 0, 0, 0); __builtin_amdgcn_s_setprio(0); } while (0)
; #define PG8_WAIT_V(n) asm volatile("s_waitcnt vmcnt(" #n ")" ::: "memory")
; #define PG8_WAIT_L(n) asm volatile("s_waitcnt lgkmcnt(" #n ")" ::: "memory")
; #define PG8_BAR __builtin_amdgcn_s_barrier()
; #define PG8_SCHED __builtin_amdgcn_sched_barrier(0)
; template <class Epi>
; __device__ __forceinline__ void gemm_phase(PG8_LAS unsigned char* lds, const Gemm g, const StaticOrder& S, const Epi& E) {
;     ...
;             PG8_LDA(At, 1, 1); PG8_STAGE(PG8_SA(1, 0), a3, voffA);
;             PG8_BAR; PG8_WAIT_L(0); PG8_MMA(1, 0, At, B0); PG8_BAR; PG8_SCHED;
;             PG8_STAGE(PG8_SB(1, 1), b3 + hstep, voffB);
;             PG8_WAIT_V(6); PG8_BAR; PG8_MMA(1, 1, At, B1); PG8_BAR;
	ds_read_b128 v[170:173], v156 offset:49152
	ds_read_b128 v[174:177], v156 offset:50176
	ds_read_b128 v[178:181], v156 offset:51200
	ds_read_b128 v[182:185], v156 offset:52224
	ds_read_b128 v[186:189], v156 offset:53248
	ds_read_b128 v[190:193], v156 offset:54272
	ds_read_b128 v[194:197], v156 offset:55296
	ds_read_b128 v[198:201], v156 offset:56320
	global_load_lds_dwordx4 v[152:153], off
	v_lshl_add_u64 v[152:153], v[222:223], 0, s[12:13]
	s_mov_b32 m0, s44
	s_nop 0
	global_load_lds_dwordx4 v[152:153], off
	s_barrier
	s_nop 0
	s_setprio 1
	s_nop 0
	s_waitcnt lgkmcnt(7)
	v_mfma_f32_16x16x32_bf16 v[62:65], v[148:151], v[170:173], v[62:65]
	v_mfma_f32_16x16x32_bf16 v[58:61], v[162:165], v[170:173], v[58:61]
	s_waitcnt lgkmcnt(5)
	v_mfma_f32_16x16x32_bf16 v[46:49], v[148:151], v[178:181], v[46:49]
	v_mfma_f32_16x16x32_bf16 v[42:45], v[162:165], v[178:181], v[42:45]
	s_waitcnt lgkmcnt(3)
	v_mfma_f32_16x16x32_bf16 v[30:33], v[148:151], v[186:189], v[30:33]
	v_mfma_f32_16x16x32_bf16 v[26:29], v[162:165], v[186:189], v[26:29]
	s_waitcnt lgkmcnt(1)
	v_mfma_f32_16x16x32_bf16 v[14:17], v[148:151], v[194:197], v[14:17]
	v_mfma_f32_16x16x32_bf16 v[10:13], v[162:165], v[194:197], v[10:13]
	v_mfma_f32_16x16x32_bf16 v[62:65], v[158:161], v[174:177], v[62:65]
	v_mfma_f32_16x16x32_bf16 v[58:61], v[166:169], v[174:177], v[58:61]
	v_mfma_f32_16x16x32_bf16 v[46:49], v[158:161], v[182:185], v[46:49]
	v_mfma_f32_16x16x32_bf16 v[42:45], v[166:169], v[182:185], v[42:45]
	v_mfma_f32_16x16x32_bf16 v[30:33], v[158:161], v[190:193], v[30:33]
	v_mfma_f32_16x16x32_bf16 v[26:29], v[166:169], v[190:193], v[26:29]
	s_waitcnt lgkmcnt(0)
	v_mfma_f32_16x16x32_bf16 v[14:17], v[158:161], v[198:201], v[14:17]
	v_mfma_f32_16x16x32_bf16 v[10:13], v[166:169], v[198:201], v[10:13]
	s_setprio 0
	s_barrier
	s_add_u32 s6, s6, 0x80080
	s_addc_u32 s7, s7, 0
	s_add_i32 s30, s30, s37
	v_lshl_add_u64 v[148:149], s[6:7], 0, v[134:135]
	s_mov_b32 m0, s30
	s_nop 0
	global_load_lds_dwordx4 v[148:149], off
	v_lshl_add_u64 v[148:149], s[6:7], 0, v[138:139]
	s_add_i32 m0, s30, 0x2000
	s_nop 0
	global_load_lds_dwordx4 v[148:149], off
	s_waitcnt vmcnt(6)
	s_barrier
	s_setprio 1
	v_mfma_f32_16x16x32_bf16 v[54:57], v[202:205], v[170:173], v[54:57]
	v_mfma_f32_16x16x32_bf16 v[50:53], v[210:213], v[170:173], v[50:53]
	v_mfma_f32_16x16x32_bf16 v[38:41], v[202:205], v[178:181], v[38:41]
	v_mfma_f32_16x16x32_bf16 v[34:37], v[210:213], v[178:181], v[34:37]
	v_mfma_f32_16x16x32_bf16 v[22:25], v[202:205], v[186:189], v[22:25]
	v_mfma_f32_16x16x32_bf16 v[18:21], v[210:213], v[186:189], v[18:21]
	v_mfma_f32_16x16x32_bf16 v[6:9], v[202:205], v[194:197], v[6:9]
	v_mfma_f32_16x16x32_bf16 v[2:5], v[210:213], v[194:197], v[2:5]
	v_mfma_f32_16x16x32_bf16 v[54:57], v[206:209], v[174:177], v[54:57]
	v_mfma_f32_16x16x32_bf16 v[50:53], v[214:217], v[174:177], v[50:53]
	v_mfma_f32_16x16x32_bf16 v[38:41], v[206:209], v[182:185], v[38:41]
	v_mfma_f32_16x16x32_bf16 v[34:37], v[214:217], v[182:185], v[34:37]
	v_mfma_f32_16x16x32_bf16 v[22:25], v[206:209], v[190:193], v[22:25]
	v_mfma_f32_16x16x32_bf16 v[18:21], v[214:217], v[190:193], v[18:21]
	v_mfma_f32_16x16x32_bf16 v[6:9], v[206:209], v[198:201], v[6:9]
	v_mfma_f32_16x16x32_bf16 v[2:5], v[214:217], v[198:201], v[2:5]
	s_setprio 0
	s_add_i32 s56, s56, 2
	s_add_u32 s4, s4, 0x100
	s_addc_u32 s5, s5, 0
	s_add_u32 s54, s54, 0x100
	s_addc_u32 s55, s55, 0
	s_cmp_gt_u32 s56, 29
	s_barrier
	s_cbranch_scc0 .LBB0_1056
	v_lshl_add_u32 v150, s2, 8, v1
	v_lshl_or_b32 v148, s3, 8, v154
	v_ashrrev_i32_e32 v151, 31, v150
	v_lshlrev_b64 v[152:153], 13, v[150:151]
	v_ashrrev_i32_e32 v149, 31, v148
	v_lshl_add_u64 v[158:159], s[10:11], 0, v[152:153]
	v_lshlrev_b64 v[152:153], 1, v[148:149]
	v_lshl_add_u64 v[148:149], v[158:159], 0, v[152:153]
	s_mov_b64 s[98:99], 0x20000
	global_load_dwordx4 v[186:189], v[148:149], off
	global_load_dwordx4 v[190:193], v[148:149], off offset:256
	v_lshl_add_u64 v[252:253], v[148:149], 0, s[98:99]
	global_load_dwordx4 v[194:197], v[252:253], off
	global_load_dwordx4 v[198:201], v[252:253], off offset:256
	v_lshl_add_u64 v[254:255], v[252:253], 0, s[98:99]
	global_load_dwordx4 v[202:205], v[254:255], off
	global_load_dwordx4 v[206:209], v[254:255], off offset:256
	v_lshl_add_u64 v[252:253], v[254:255], 0, s[98:99]
	global_load_dwordx4 v[210:213], v[252:253], off
	global_load_dwordx4 v[214:217], v[252:253], off offset:256
	v_lshl_add_u64 v[254:255], v[148:149], 0, s[14:15]
	global_load_dwordx4 v[218:221], v[254:255], off
	global_load_dwordx4 v[222:225], v[254:255], off offset:256
	v_lshl_add_u64 v[252:253], v[148:149], 0, s[16:17]
	global_load_dwordx4 v[226:229], v[252:253], off
	global_load_dwordx4 v[230:233], v[252:253], off offset:256
	v_lshl_add_u64 v[254:255], v[148:149], 0, s[18:19]
	global_load_dwordx4 v[234:237], v[254:255], off
	global_load_dwordx4 v[238:241], v[254:255], off offset:256
	v_lshl_add_u64 v[252:253], v[148:149], 0, s[20:21]
	global_load_dwordx4 v[242:245], v[252:253], off
	global_load_dwordx4 v[246:249], v[252:253], off offset:256
	v_mul_f32_e32 v151, 0xbfb8aa3b, v126
	v_mul_f32_e32 v162, 0xbfb8aa3b, v122
	v_exp_f32_e32 v151, v151
	v_mul_f32_e32 v163, 0xbfb8aa3b, v127
	v_exp_f32_e32 v162, v162
	v_exp_f32_e32 v163, v163
	v_add_f32_e32 v151, 1.0, v151
	v_div_scale_f32 v166, s[2:3], v151, v151, v126
	v_add_f32_e32 v162, 1.0, v162
	v_add_f32_e32 v163, 1.0, v163
	v_div_scale_f32 v168, s[2:3], v162, v162, v122
	v_rcp_f32_e32 v174, v166
	v_mul_f32_e32 v164, 0xbfb8aa3b, v123
	v_div_scale_f32 v170, s[4:5], v163, v163, v127
	v_rcp_f32_e32 v175, v168
	v_exp_f32_e32 v164, v164
	v_rcp_f32_e32 v176, v170
	v_fma_f32 v178, -v166, v174, 1.0
	v_div_scale_f32 v167, vcc, v126, v151, v126
	v_fma_f32 v179, -v168, v175, 1.0
	v_fmac_f32_e32 v174, v178, v174
	v_add_f32_e32 v164, 1.0, v164
	v_div_scale_f32 v169, s[2:3], v122, v162, v122
	v_fma_f32 v180, -v170, v176, 1.0
	v_fmac_f32_e32 v175, v179, v175
	v_mul_f32_e32 v178, v167, v174
	v_div_scale_f32 v171, s[4:5], v127, v163, v127
	v_div_scale_f32 v172, s[6:7], v164, v164, v123
	v_fmac_f32_e32 v176, v180, v176
	v_mul_f32_e32 v179, v169, v175
	v_fma_f32 v182, -v166, v178, v167
	v_rcp_f32_e32 v177, v172
	v_mul_f32_e32 v180, v171, v176
	v_fma_f32 v183, -v168, v179, v169
	v_fmac_f32_e32 v178, v182, v174
	v_mul_f32_e32 v165, 0xbfb8aa3b, v128
	v_fma_f32 v184, -v170, v180, v171
	v_fmac_f32_e32 v179, v183, v175
	v_fma_f32 v166, -v166, v178, v167
	v_exp_f32_e32 v165, v165
	v_fmac_f32_e32 v180, v184, v176
	v_fma_f32 v167, -v168, v179, v169
	v_div_fmas_f32 v166, v166, v174, v178
	s_mov_b64 vcc, s[2:3]
	v_fma_f32 v168, -v170, v180, v171
	v_div_fixup_f32 v126, v166, v151, v126
	v_div_fmas_f32 v151, v167, v175, v179
	s_mov_b64 vcc, s[4:5]
	v_fma_f32 v181, -v172, v177, 1.0
	v_div_fixup_f32 v122, v151, v162, v122
	v_div_fmas_f32 v151, v168, v176, v180
	v_div_scale_f32 v173, s[6:7], v123, v164, v123
	v_fmac_f32_e32 v177, v181, v177
	v_div_fixup_f32 v127, v151, v163, v127
	v_mul_f32_e32 v181, v173, v177
	v_fma_f32 v185, -v172, v181, v173
	v_fmac_f32_e32 v181, v185, v177
	v_fma_f32 v169, -v172, v181, v173
	s_mov_b64 vcc, s[6:7]
	s_mov_b64 s[6:7], s[28:29]
	s_mov_b64 s[4:5], s[26:27]
	s_waitcnt vmcnt(14)
	v_mov_b32_e32 v158, v186
	v_mov_b32_e32 v159, v187
	v_mov_b32_e32 v160, v188
	v_mov_b32_e32 v161, v189
	v_lshlrev_b32_e32 v151, 16, v158
	v_and_b32_e32 v158, 0xffff0000, v158
	v_lshlrev_b32_e32 v163, 16, v160
	v_mul_f32_e32 v126, v126, v151
	v_mul_f32_e32 v151, v122, v163
	v_mul_f32_e32 v122, v127, v158
	v_add_f32_e32 v127, 1.0, v165
	v_div_scale_f32 v158, s[2:3], v127, v127, v128
	v_rcp_f32_e32 v163, v158
	v_div_fmas_f32 v165, v169, v177, v181
	v_and_b32_e32 v160, 0xffff0000, v160
	v_div_fixup_f32 v123, v165, v164, v123
	v_mul_f32_e32 v160, v123, v160
	v_fma_f32 v123, -v158, v163, 1.0
	v_mul_f32_e32 v165, 0xbfb8aa3b, v124
	v_fmac_f32_e32 v163, v123, v163
	v_div_scale_f32 v123, vcc, v128, v127, v128
	v_exp_f32_e32 v165, v165
	v_mul_f32_e32 v164, v123, v163
	v_fma_f32 v167, -v158, v164, v123
	v_fmac_f32_e32 v164, v167, v163
	v_fma_f32 v123, -v158, v164, v123
	v_add_f32_e32 v158, 1.0, v165
	v_div_scale_f32 v165, s[2:3], v158, v158, v124
	v_rcp_f32_e32 v167, v165
	v_div_fmas_f32 v123, v123, v163, v164
	v_lshlrev_b32_e32 v162, 16, v159
	v_div_fixup_f32 v123, v123, v127, v128
	v_mul_f32_e32 v123, v123, v162
	v_mul_f32_e32 v162, 0xbfb8aa3b, v129
	v_exp_f32_e32 v162, v162
	v_fma_f32 v127, -v165, v167, 1.0
	v_fmac_f32_e32 v167, v127, v167
	v_div_scale_f32 v127, vcc, v124, v158, v124
	v_mul_f32_e32 v128, v127, v167
	v_fma_f32 v163, -v165, v128, v127
	v_add_f32_e32 v162, 1.0, v162
	v_fmac_f32_e32 v128, v163, v167
	v_div_scale_f32 v163, s[2:3], v162, v162, v129
	v_rcp_f32_e32 v164, v163
	v_fma_f32 v127, -v165, v128, v127
	v_div_fmas_f32 v127, v127, v167, v128
	v_lshlrev_b32_e32 v166, 16, v161
	v_div_fixup_f32 v124, v127, v158, v124
	v_mul_f32_e32 v158, 0xbfb8aa3b, v125
	v_mul_f32_e32 v127, v124, v166
	v_fma_f32 v124, -v163, v164, 1.0
	v_exp_f32_e32 v158, v158
	v_fmac_f32_e32 v164, v124, v164
	v_div_scale_f32 v124, vcc, v129, v162, v129
	v_mul_f32_e32 v128, v124, v164
	v_fma_f32 v165, -v163, v128, v124
	v_fmac_f32_e32 v128, v165, v164
	v_add_f32_e32 v158, 1.0, v158
	v_fma_f32 v124, -v163, v128, v124
	v_div_scale_f32 v163, s[2:3], v158, v158, v125
	v_rcp_f32_e32 v165, v163
	v_div_fmas_f32 v124, v124, v164, v128
	v_and_b32_e32 v159, 0xffff0000, v159
	v_div_fixup_f32 v124, v124, v162, v129
	v_fma_f32 v128, -v163, v165, 1.0
	v_fmac_f32_e32 v165, v128, v165
	v_div_scale_f32 v128, vcc, v125, v158, v125
	v_mul_f32_e32 v129, v128, v165
	v_mul_f32_e32 v124, v124, v159
	v_fma_f32 v159, -v163, v129, v128
	v_fmac_f32_e32 v129, v159, v165
	v_fma_f32 v128, -v163, v129, v128
	v_div_fmas_f32 v128, v128, v165, v129
	v_and_b32_e32 v161, 0xffff0000, v161
	v_div_fixup_f32 v125, v128, v158, v125
	v_mul_f32_e32 v125, v125, v161
	v_cvt_pk_bf16_f32 v122, v126, v122
	v_cvt_pk_bf16_f32 v123, v123, v124
	v_cvt_pk_bf16_f32 v124, v151, v160
	v_cvt_pk_bf16_f32 v125, v127, v125
	v_mul_f32_e32 v162, 0xbfb8aa3b, v114
	global_store_dwordx4 v[148:149], v[122:125], off
	v_exp_f32_e32 v162, v162
	s_waitcnt vmcnt(14)
	v_mov_b32_e32 v126, v190
	v_mov_b32_e32 v127, v191
	v_mov_b32_e32 v128, v192
	v_mov_b32_e32 v129, v193
	v_lshlrev_b32_e32 v159, 16, v129
	v_mul_f32_e32 v124, 0xbfb8aa3b, v118
	v_exp_f32_e32 v124, v124
	v_lshlrev_b32_e32 v122, 16, v126
	v_and_b32_e32 v123, 0xffff0000, v126
	v_lshlrev_b32_e32 v125, 16, v127
	v_add_f32_e32 v124, 1.0, v124
	v_div_scale_f32 v151, s[2:3], v124, v124, v118
	v_rcp_f32_e32 v158, v151
	v_and_b32_e32 v126, 0xffff0000, v127
	v_lshlrev_b32_e32 v127, 16, v128
	v_and_b32_e32 v128, 0xffff0000, v128
	v_fma_f32 v160, -v151, v158, 1.0
	v_fmac_f32_e32 v158, v160, v158
	v_div_scale_f32 v160, vcc, v118, v124, v118
	v_mul_f32_e32 v161, v160, v158
	v_fma_f32 v163, -v151, v161, v160
	v_fmac_f32_e32 v161, v163, v158
	v_fma_f32 v151, -v151, v161, v160
	v_add_f32_e32 v160, 1.0, v162
	v_div_scale_f32 v162, s[2:3], v160, v160, v114
	v_rcp_f32_e32 v163, v162
	v_div_fmas_f32 v151, v151, v158, v161
	v_div_fixup_f32 v118, v151, v124, v118
	v_mul_f32_e32 v151, 0xbfb8aa3b, v119
	v_exp_f32_e32 v151, v151
	v_mul_f32_e32 v118, v118, v122
	v_fma_f32 v122, -v162, v163, 1.0
	v_fmac_f32_e32 v163, v122, v163
	v_div_scale_f32 v122, vcc, v114, v160, v114
	v_mul_f32_e32 v124, v122, v163
	v_fma_f32 v158, -v162, v124, v122
	v_add_f32_e32 v151, 1.0, v151
	v_fmac_f32_e32 v124, v158, v163
	v_div_scale_f32 v158, s[2:3], v151, v151, v119
	v_fma_f32 v122, -v162, v124, v122
	v_rcp_f32_e32 v161, v158
	v_div_fmas_f32 v122, v122, v163, v124
	v_div_fixup_f32 v114, v122, v160, v114
	v_mul_f32_e32 v114, v114, v127
	v_mul_f32_e32 v127, 0xbfb8aa3b, v115
	v_fma_f32 v122, -v158, v161, 1.0
	v_exp_f32_e32 v127, v127
	v_fmac_f32_e32 v161, v122, v161
	v_div_scale_f32 v122, vcc, v119, v151, v119
	v_mul_f32_e32 v124, v122, v161
	v_fma_f32 v160, -v158, v124, v122
	v_fmac_f32_e32 v124, v160, v161
	v_add_f32_e32 v127, 1.0, v127
	v_fma_f32 v122, -v158, v124, v122
	v_div_scale_f32 v158, s[2:3], v127, v127, v115
	v_rcp_f32_e32 v160, v158
	v_div_fmas_f32 v122, v122, v161, v124
	v_mul_f32_e32 v124, 0xbfb8aa3b, v120
	v_exp_f32_e32 v124, v124
	v_div_fixup_f32 v119, v122, v151, v119
	v_fma_f32 v122, -v158, v160, 1.0
	v_fmac_f32_e32 v160, v122, v160
	v_div_scale_f32 v122, vcc, v115, v127, v115
	v_mul_f32_e32 v119, v119, v123
	v_mul_f32_e32 v123, v122, v160
	v_fma_f32 v151, -v158, v123, v122
	v_add_f32_e32 v124, 1.0, v124
	v_fmac_f32_e32 v123, v151, v160
	v_div_scale_f32 v151, s[2:3], v124, v124, v120
	v_fma_f32 v122, -v158, v123, v122
	v_rcp_f32_e32 v158, v151
	v_div_fmas_f32 v122, v122, v160, v123
	v_div_fixup_f32 v115, v122, v127, v115
	v_mul_f32_e32 v127, 0xbfb8aa3b, v116
	v_exp_f32_e32 v127, v127
	v_fma_f32 v122, -v151, v158, 1.0
	v_fmac_f32_e32 v158, v122, v158
	v_div_scale_f32 v122, vcc, v120, v124, v120
	v_mul_f32_e32 v123, v122, v158
	v_mul_f32_e32 v115, v115, v128
	v_fma_f32 v128, -v151, v123, v122
	v_add_f32_e32 v127, 1.0, v127
	v_fmac_f32_e32 v123, v128, v158
	v_div_scale_f32 v128, s[2:3], v127, v127, v116
	v_fma_f32 v122, -v151, v123, v122
	v_rcp_f32_e32 v151, v128
	v_div_fmas_f32 v122, v122, v158, v123
	v_div_fixup_f32 v120, v122, v124, v120
	v_mul_f32_e32 v124, 0xbfb8aa3b, v121
	v_exp_f32_e32 v124, v124
	v_fma_f32 v122, -v128, v151, 1.0
	v_fmac_f32_e32 v151, v122, v151
	v_div_scale_f32 v122, vcc, v116, v127, v116
	v_mul_f32_e32 v123, v122, v151
	v_mul_f32_e32 v120, v120, v125
	v_fma_f32 v125, -v128, v123, v122
	v_add_f32_e32 v124, 1.0, v124
	v_fmac_f32_e32 v123, v125, v151
	v_div_scale_f32 v125, s[2:3], v124, v124, v121
	v_fma_f32 v122, -v128, v123, v122
	v_rcp_f32_e32 v128, v125
	v_div_fmas_f32 v122, v122, v151, v123
	v_div_fixup_f32 v116, v122, v127, v116
	v_mul_f32_e32 v122, v116, v159
	v_fma_f32 v116, -v125, v128, 1.0
	v_mul_f32_e32 v127, 0xbfb8aa3b, v117
	v_fmac_f32_e32 v128, v116, v128
	v_div_scale_f32 v116, vcc, v121, v124, v121
	v_exp_f32_e32 v127, v127
	v_mul_f32_e32 v123, v116, v128
	v_fma_f32 v151, -v125, v123, v116
	v_fmac_f32_e32 v123, v151, v128
	v_fma_f32 v116, -v125, v123, v116
	v_add_f32_e32 v125, 1.0, v127
	v_div_scale_f32 v127, s[2:3], v125, v125, v117
	v_rcp_f32_e32 v151, v127
	v_div_fmas_f32 v116, v116, v128, v123
	v_div_fixup_f32 v116, v116, v124, v121
	v_mul_f32_e32 v121, v116, v126
	v_fma_f32 v116, -v127, v151, 1.0
	v_fmac_f32_e32 v151, v116, v151
	v_div_scale_f32 v116, vcc, v117, v125, v117
	v_mul_f32_e32 v123, v116, v151
	v_fma_f32 v124, -v127, v123, v116
	v_fmac_f32_e32 v123, v124, v151
	v_fma_f32 v116, -v127, v123, v116
	v_div_fmas_f32 v116, v116, v151, v123
	v_and_b32_e32 v129, 0xffff0000, v129
	v_div_fixup_f32 v116, v116, v125, v117
	v_mul_f32_e32 v123, v116, v129
	v_cvt_pk_bf16_f32 v116, v118, v119
	v_cvt_pk_bf16_f32 v117, v120, v121
	v_cvt_pk_bf16_f32 v118, v114, v115
	v_or_b32_e32 v114, 16, v150
	v_ashrrev_i32_e32 v115, 31, v114
	v_lshlrev_b64 v[114:115], 13, v[114:115]
	v_lshl_add_u64 v[114:115], s[10:11], 0, v[114:115]
	v_lshl_add_u64 v[114:115], v[114:115], 0, v[152:153]
	v_cvt_pk_bf16_f32 v119, v122, v123
	v_mul_f32_e32 v129, 0xbfb8aa3b, v106
	global_store_dwordx4 v[148:149], v[116:119], off offset:256
	v_exp_f32_e32 v129, v129
	s_waitcnt vmcnt(14)
	v_mov_b32_e32 v120, v194
	v_mov_b32_e32 v121, v195
	v_mov_b32_e32 v122, v196
	v_mov_b32_e32 v123, v197
	v_lshlrev_b32_e32 v126, 16, v123
	v_mul_f32_e32 v118, 0xbfb8aa3b, v110
	v_exp_f32_e32 v118, v118
	v_lshlrev_b32_e32 v116, 16, v120
	v_and_b32_e32 v117, 0xffff0000, v120
	v_lshlrev_b32_e32 v119, 16, v121
	v_add_f32_e32 v118, 1.0, v118
	v_div_scale_f32 v124, s[2:3], v118, v118, v110
	v_rcp_f32_e32 v125, v124
	v_and_b32_e32 v120, 0xffff0000, v121
	v_lshlrev_b32_e32 v121, 16, v122
	v_and_b32_e32 v122, 0xffff0000, v122
	v_fma_f32 v127, -v124, v125, 1.0
	v_fmac_f32_e32 v125, v127, v125
	v_div_scale_f32 v127, vcc, v110, v118, v110
	v_mul_f32_e32 v128, v127, v125
	v_fma_f32 v151, -v124, v128, v127
	v_fmac_f32_e32 v128, v151, v125
	v_fma_f32 v124, -v124, v128, v127
	v_add_f32_e32 v127, 1.0, v129
	v_div_scale_f32 v129, s[2:3], v127, v127, v106
	v_rcp_f32_e32 v151, v129
	v_div_fmas_f32 v124, v124, v125, v128
	v_div_fixup_f32 v110, v124, v118, v110
	v_mul_f32_e32 v124, 0xbfb8aa3b, v111
	v_exp_f32_e32 v124, v124
	v_mul_f32_e32 v110, v110, v116
	v_fma_f32 v116, -v129, v151, 1.0
	v_fmac_f32_e32 v151, v116, v151
	v_div_scale_f32 v116, vcc, v106, v127, v106
	v_mul_f32_e32 v118, v116, v151
	v_fma_f32 v125, -v129, v118, v116
	v_add_f32_e32 v124, 1.0, v124
	v_fmac_f32_e32 v118, v125, v151
	v_div_scale_f32 v125, s[2:3], v124, v124, v111
	v_fma_f32 v116, -v129, v118, v116
	v_rcp_f32_e32 v128, v125
	v_div_fmas_f32 v116, v116, v151, v118
	v_div_fixup_f32 v106, v116, v127, v106
	v_mul_f32_e32 v116, v106, v121
	v_mul_f32_e32 v121, 0xbfb8aa3b, v107
	v_fma_f32 v106, -v125, v128, 1.0
	v_exp_f32_e32 v121, v121
	v_fmac_f32_e32 v128, v106, v128
	v_div_scale_f32 v106, vcc, v111, v124, v111
	v_mul_f32_e32 v118, v106, v128
	v_fma_f32 v127, -v125, v118, v106
	v_fmac_f32_e32 v118, v127, v128
	v_add_f32_e32 v121, 1.0, v121
	v_fma_f32 v106, -v125, v118, v106
	v_div_scale_f32 v125, s[2:3], v121, v121, v107
	v_rcp_f32_e32 v127, v125
	v_div_fmas_f32 v106, v106, v128, v118
	v_mul_f32_e32 v118, 0xbfb8aa3b, v112
	v_exp_f32_e32 v118, v118
	v_div_fixup_f32 v106, v106, v124, v111
	v_fma_f32 v111, -v125, v127, 1.0
	v_fmac_f32_e32 v127, v111, v127
	v_div_scale_f32 v111, vcc, v107, v121, v107
	v_mul_f32_e32 v106, v106, v117
	v_mul_f32_e32 v117, v111, v127
	v_fma_f32 v124, -v125, v117, v111
	v_add_f32_e32 v118, 1.0, v118
	v_fmac_f32_e32 v117, v124, v127
	v_div_scale_f32 v124, s[2:3], v118, v118, v112
	v_fma_f32 v111, -v125, v117, v111
	v_rcp_f32_e32 v125, v124
	v_div_fmas_f32 v111, v111, v127, v117
	v_div_fixup_f32 v107, v111, v121, v107
	v_mul_f32_e32 v121, 0xbfb8aa3b, v108
	v_exp_f32_e32 v121, v121
	v_mul_f32_e32 v111, v107, v122
	v_fma_f32 v107, -v124, v125, 1.0
	v_fmac_f32_e32 v125, v107, v125
	v_div_scale_f32 v107, vcc, v112, v118, v112
	v_mul_f32_e32 v117, v107, v125
	v_fma_f32 v122, -v124, v117, v107
	v_add_f32_e32 v121, 1.0, v121
	v_fmac_f32_e32 v117, v122, v125
	v_div_scale_f32 v122, s[2:3], v121, v121, v108
	v_fma_f32 v107, -v124, v117, v107
	v_rcp_f32_e32 v124, v122
	v_div_fmas_f32 v107, v107, v125, v117
	v_div_fixup_f32 v107, v107, v118, v112
	v_mul_f32_e32 v118, 0xbfb8aa3b, v113
	v_exp_f32_e32 v118, v118
	v_fma_f32 v112, -v122, v124, 1.0
	v_fmac_f32_e32 v124, v112, v124
	v_div_scale_f32 v112, vcc, v108, v121, v108
	v_mul_f32_e32 v117, v112, v124
	v_mul_f32_e32 v107, v107, v119
	v_fma_f32 v119, -v122, v117, v112
	v_add_f32_e32 v118, 1.0, v118
	v_fmac_f32_e32 v117, v119, v124
	v_div_scale_f32 v119, s[2:3], v118, v118, v113
	v_fma_f32 v112, -v122, v117, v112
	v_rcp_f32_e32 v122, v119
	v_div_fmas_f32 v112, v112, v124, v117
	v_div_fixup_f32 v108, v112, v121, v108
	v_mul_f32_e32 v112, v108, v126
	v_fma_f32 v108, -v119, v122, 1.0
	v_mul_f32_e32 v121, 0xbfb8aa3b, v109
	v_fmac_f32_e32 v122, v108, v122
	v_div_scale_f32 v108, vcc, v113, v118, v113
	v_exp_f32_e32 v121, v121
	v_mul_f32_e32 v117, v108, v122
	v_fma_f32 v124, -v119, v117, v108
	v_fmac_f32_e32 v117, v124, v122
	v_fma_f32 v108, -v119, v117, v108
	v_add_f32_e32 v119, 1.0, v121
	v_div_scale_f32 v121, s[2:3], v119, v119, v109
	v_rcp_f32_e32 v124, v121
	v_div_fmas_f32 v108, v108, v122, v117
	v_div_fixup_f32 v108, v108, v118, v113
	v_and_b32_e32 v123, 0xffff0000, v123
	v_fma_f32 v113, -v121, v124, 1.0
	v_fmac_f32_e32 v124, v113, v124
	v_div_scale_f32 v113, vcc, v109, v119, v109
	v_mul_f32_e32 v117, v113, v124
	v_fma_f32 v118, -v121, v117, v113
	v_fmac_f32_e32 v117, v118, v124
	v_fma_f32 v113, -v121, v117, v113
	v_div_fmas_f32 v113, v113, v124, v117
	v_div_fixup_f32 v109, v113, v119, v109
	v_mul_f32_e32 v108, v108, v120
	v_mul_f32_e32 v109, v109, v123
	v_cvt_pk_bf16_f32 v106, v110, v106
	v_cvt_pk_bf16_f32 v107, v107, v108
	v_cvt_pk_bf16_f32 v108, v116, v111
	v_cvt_pk_bf16_f32 v109, v112, v109
	v_mul_f32_e32 v121, 0xbfb8aa3b, v98
	global_store_dwordx4 v[114:115], v[106:109], off
	v_exp_f32_e32 v121, v121
	s_waitcnt vmcnt(14)
	v_mov_b32_e32 v110, v198
	v_mov_b32_e32 v111, v199
	v_mov_b32_e32 v112, v200
	v_mov_b32_e32 v113, v201
	v_lshlrev_b32_e32 v118, 16, v113
	v_mul_f32_e32 v108, 0xbfb8aa3b, v102
	v_exp_f32_e32 v108, v108
	v_lshlrev_b32_e32 v106, 16, v110
	v_and_b32_e32 v107, 0xffff0000, v110
	v_lshlrev_b32_e32 v109, 16, v111
	v_add_f32_e32 v108, 1.0, v108
	v_div_scale_f32 v116, s[2:3], v108, v108, v102
	v_rcp_f32_e32 v117, v116
	v_and_b32_e32 v110, 0xffff0000, v111
	v_lshlrev_b32_e32 v111, 16, v112
	v_and_b32_e32 v112, 0xffff0000, v112
	v_fma_f32 v119, -v116, v117, 1.0
	v_fmac_f32_e32 v117, v119, v117
	v_div_scale_f32 v119, vcc, v102, v108, v102
	v_mul_f32_e32 v120, v119, v117
	v_fma_f32 v122, -v116, v120, v119
	v_fmac_f32_e32 v120, v122, v117
	v_fma_f32 v116, -v116, v120, v119
	v_add_f32_e32 v119, 1.0, v121
	v_div_scale_f32 v121, s[2:3], v119, v119, v98
	v_rcp_f32_e32 v122, v121
	v_div_fmas_f32 v116, v116, v117, v120
	v_div_fixup_f32 v102, v116, v108, v102
	v_mul_f32_e32 v116, 0xbfb8aa3b, v103
	v_exp_f32_e32 v116, v116
	v_mul_f32_e32 v102, v102, v106
	v_fma_f32 v106, -v121, v122, 1.0
	v_fmac_f32_e32 v122, v106, v122
	v_div_scale_f32 v106, vcc, v98, v119, v98
	v_mul_f32_e32 v108, v106, v122
	v_fma_f32 v117, -v121, v108, v106
	v_add_f32_e32 v116, 1.0, v116
	v_fmac_f32_e32 v108, v117, v122
	v_div_scale_f32 v117, s[2:3], v116, v116, v103
	v_fma_f32 v106, -v121, v108, v106
	v_rcp_f32_e32 v120, v117
	v_div_fmas_f32 v106, v106, v122, v108
	v_div_fixup_f32 v98, v106, v119, v98
	v_mul_f32_e32 v98, v98, v111
	v_mul_f32_e32 v111, 0xbfb8aa3b, v99
	v_fma_f32 v106, -v117, v120, 1.0
	v_exp_f32_e32 v111, v111
	v_fmac_f32_e32 v120, v106, v120
	v_div_scale_f32 v106, vcc, v103, v116, v103
	v_mul_f32_e32 v108, v106, v120
	v_fma_f32 v119, -v117, v108, v106
	v_fmac_f32_e32 v108, v119, v120
	v_add_f32_e32 v111, 1.0, v111
	v_fma_f32 v106, -v117, v108, v106
	v_div_scale_f32 v117, s[2:3], v111, v111, v99
	v_rcp_f32_e32 v119, v117
	v_div_fmas_f32 v106, v106, v120, v108
	v_mul_f32_e32 v108, 0xbfb8aa3b, v104
	v_exp_f32_e32 v108, v108
	v_div_fixup_f32 v103, v106, v116, v103
	v_fma_f32 v106, -v117, v119, 1.0
	v_fmac_f32_e32 v119, v106, v119
	v_div_scale_f32 v106, vcc, v99, v111, v99
	v_mul_f32_e32 v103, v103, v107
	v_mul_f32_e32 v107, v106, v119
	v_fma_f32 v116, -v117, v107, v106
	v_add_f32_e32 v108, 1.0, v108
	v_fmac_f32_e32 v107, v116, v119
	v_div_scale_f32 v116, s[2:3], v108, v108, v104
	v_fma_f32 v106, -v117, v107, v106
	v_rcp_f32_e32 v117, v116
	v_div_fmas_f32 v106, v106, v119, v107
	v_div_fixup_f32 v99, v106, v111, v99
	v_mul_f32_e32 v111, 0xbfb8aa3b, v100
	v_exp_f32_e32 v111, v111
	v_fma_f32 v106, -v116, v117, 1.0
	v_fmac_f32_e32 v117, v106, v117
	v_div_scale_f32 v106, vcc, v104, v108, v104
	v_mul_f32_e32 v107, v106, v117
	v_mul_f32_e32 v99, v99, v112
	v_fma_f32 v112, -v116, v107, v106
	v_add_f32_e32 v111, 1.0, v111
	v_fmac_f32_e32 v107, v112, v117
	v_div_scale_f32 v112, s[2:3], v111, v111, v100
	v_fma_f32 v106, -v116, v107, v106
	v_rcp_f32_e32 v116, v112
	v_div_fmas_f32 v106, v106, v117, v107
	v_div_fixup_f32 v104, v106, v108, v104
	v_mul_f32_e32 v108, 0xbfb8aa3b, v105
	v_exp_f32_e32 v108, v108
	v_fma_f32 v106, -v112, v116, 1.0
	v_fmac_f32_e32 v116, v106, v116
	v_div_scale_f32 v106, vcc, v100, v111, v100
	v_mul_f32_e32 v107, v106, v116
	v_mul_f32_e32 v104, v104, v109
	v_fma_f32 v109, -v112, v107, v106
	v_add_f32_e32 v108, 1.0, v108
	v_fmac_f32_e32 v107, v109, v116
	v_div_scale_f32 v109, s[2:3], v108, v108, v105
	v_fma_f32 v106, -v112, v107, v106
	v_rcp_f32_e32 v112, v109
	v_div_fmas_f32 v106, v106, v116, v107
	v_div_fixup_f32 v100, v106, v111, v100
	v_mul_f32_e32 v106, v100, v118
	v_fma_f32 v100, -v109, v112, 1.0
	v_mul_f32_e32 v111, 0xbfb8aa3b, v101
	v_fmac_f32_e32 v112, v100, v112
	v_div_scale_f32 v100, vcc, v105, v108, v105
	v_exp_f32_e32 v111, v111
	v_mul_f32_e32 v107, v100, v112
	v_fma_f32 v116, -v109, v107, v100
	v_fmac_f32_e32 v107, v116, v112
	v_fma_f32 v100, -v109, v107, v100
	v_add_f32_e32 v109, 1.0, v111
	v_div_scale_f32 v111, s[2:3], v109, v109, v101
	v_rcp_f32_e32 v116, v111
	v_div_fmas_f32 v100, v100, v112, v107
	v_div_fixup_f32 v100, v100, v108, v105
	v_mul_f32_e32 v105, v100, v110
	v_fma_f32 v100, -v111, v116, 1.0
	v_fmac_f32_e32 v116, v100, v116
	v_div_scale_f32 v100, vcc, v101, v109, v101
	v_mul_f32_e32 v107, v100, v116
	v_fma_f32 v108, -v111, v107, v100
	v_fmac_f32_e32 v107, v108, v116
	v_fma_f32 v100, -v111, v107, v100
	v_div_fmas_f32 v100, v100, v116, v107
	v_and_b32_e32 v113, 0xffff0000, v113
	v_div_fixup_f32 v100, v100, v109, v101
	v_mul_f32_e32 v107, v100, v113
	v_cvt_pk_bf16_f32 v100, v102, v103
	v_cvt_pk_bf16_f32 v101, v104, v105
	v_cvt_pk_bf16_f32 v102, v98, v99
	v_or_b32_e32 v98, 32, v150
	v_ashrrev_i32_e32 v99, 31, v98
	v_lshlrev_b64 v[98:99], 13, v[98:99]
	v_lshl_add_u64 v[98:99], s[10:11], 0, v[98:99]
	v_lshl_add_u64 v[98:99], v[98:99], 0, v[152:153]
	v_cvt_pk_bf16_f32 v103, v106, v107
	v_mul_f32_e32 v113, 0xbfb8aa3b, v90
	global_store_dwordx4 v[114:115], v[100:103], off offset:256
	v_exp_f32_e32 v113, v113
	s_waitcnt vmcnt(14)
	v_mov_b32_e32 v104, v202
	v_mov_b32_e32 v105, v203
	v_mov_b32_e32 v106, v204
	v_mov_b32_e32 v107, v205
	v_lshlrev_b32_e32 v110, 16, v107
	v_mul_f32_e32 v102, 0xbfb8aa3b, v94
	v_exp_f32_e32 v102, v102
	v_lshlrev_b32_e32 v100, 16, v104
	v_and_b32_e32 v101, 0xffff0000, v104
	v_lshlrev_b32_e32 v103, 16, v105
	v_add_f32_e32 v102, 1.0, v102
	v_div_scale_f32 v108, s[2:3], v102, v102, v94
	v_rcp_f32_e32 v109, v108
	v_and_b32_e32 v104, 0xffff0000, v105
	v_lshlrev_b32_e32 v105, 16, v106
	v_and_b32_e32 v106, 0xffff0000, v106
	v_fma_f32 v111, -v108, v109, 1.0
	v_fmac_f32_e32 v109, v111, v109
	v_div_scale_f32 v111, vcc, v94, v102, v94
	v_mul_f32_e32 v112, v111, v109
	v_fma_f32 v114, -v108, v112, v111
	v_fmac_f32_e32 v112, v114, v109
	v_fma_f32 v108, -v108, v112, v111
	v_add_f32_e32 v111, 1.0, v113
	v_div_scale_f32 v113, s[2:3], v111, v111, v90
	v_rcp_f32_e32 v114, v113
	v_div_fmas_f32 v108, v108, v109, v112
	v_div_fixup_f32 v94, v108, v102, v94
	v_mul_f32_e32 v108, 0xbfb8aa3b, v95
	v_exp_f32_e32 v108, v108
	v_mul_f32_e32 v94, v94, v100
	v_fma_f32 v100, -v113, v114, 1.0
	v_fmac_f32_e32 v114, v100, v114
	v_div_scale_f32 v100, vcc, v90, v111, v90
	v_mul_f32_e32 v102, v100, v114
	v_fma_f32 v109, -v113, v102, v100
	v_add_f32_e32 v108, 1.0, v108
	v_fmac_f32_e32 v102, v109, v114
	v_div_scale_f32 v109, s[2:3], v108, v108, v95
	v_fma_f32 v100, -v113, v102, v100
	v_rcp_f32_e32 v112, v109
	v_div_fmas_f32 v100, v100, v114, v102
	v_div_fixup_f32 v90, v100, v111, v90
	v_mul_f32_e32 v100, v90, v105
	v_mul_f32_e32 v105, 0xbfb8aa3b, v91
	v_fma_f32 v90, -v109, v112, 1.0
	v_exp_f32_e32 v105, v105
	v_fmac_f32_e32 v112, v90, v112
	v_div_scale_f32 v90, vcc, v95, v108, v95
	v_mul_f32_e32 v102, v90, v112
	v_fma_f32 v111, -v109, v102, v90
	v_fmac_f32_e32 v102, v111, v112
	v_add_f32_e32 v105, 1.0, v105
	v_fma_f32 v90, -v109, v102, v90
	v_div_scale_f32 v109, s[2:3], v105, v105, v91
	v_rcp_f32_e32 v111, v109
	v_div_fmas_f32 v90, v90, v112, v102
	v_mul_f32_e32 v102, 0xbfb8aa3b, v96
	v_exp_f32_e32 v102, v102
	v_div_fixup_f32 v90, v90, v108, v95
	v_fma_f32 v95, -v109, v111, 1.0
	v_fmac_f32_e32 v111, v95, v111
	v_div_scale_f32 v95, vcc, v91, v105, v91
	v_mul_f32_e32 v90, v90, v101
	v_mul_f32_e32 v101, v95, v111
	v_fma_f32 v108, -v109, v101, v95
	v_add_f32_e32 v102, 1.0, v102
	v_fmac_f32_e32 v101, v108, v111
	v_div_scale_f32 v108, s[2:3], v102, v102, v96
	v_fma_f32 v95, -v109, v101, v95
	v_rcp_f32_e32 v109, v108
	v_div_fmas_f32 v95, v95, v111, v101
	v_div_fixup_f32 v91, v95, v105, v91
	v_mul_f32_e32 v105, 0xbfb8aa3b, v92
	v_exp_f32_e32 v105, v105
	v_mul_f32_e32 v95, v91, v106
	v_fma_f32 v91, -v108, v109, 1.0
	v_fmac_f32_e32 v109, v91, v109
	v_div_scale_f32 v91, vcc, v96, v102, v96
	v_mul_f32_e32 v101, v91, v109
	v_fma_f32 v106, -v108, v101, v91
	v_add_f32_e32 v105, 1.0, v105
	v_fmac_f32_e32 v101, v106, v109
	v_div_scale_f32 v106, s[2:3], v105, v105, v92
	v_fma_f32 v91, -v108, v101, v91
	v_rcp_f32_e32 v108, v106
	v_div_fmas_f32 v91, v91, v109, v101
	v_div_fixup_f32 v91, v91, v102, v96
	v_mul_f32_e32 v102, 0xbfb8aa3b, v97
	v_exp_f32_e32 v102, v102
	v_fma_f32 v96, -v106, v108, 1.0
	v_fmac_f32_e32 v108, v96, v108
	v_div_scale_f32 v96, vcc, v92, v105, v92
	v_mul_f32_e32 v101, v96, v108
	v_mul_f32_e32 v91, v91, v103
	v_fma_f32 v103, -v106, v101, v96
	v_add_f32_e32 v102, 1.0, v102
	v_fmac_f32_e32 v101, v103, v108
	v_div_scale_f32 v103, s[2:3], v102, v102, v97
	v_fma_f32 v96, -v106, v101, v96
	v_rcp_f32_e32 v106, v103
	v_div_fmas_f32 v96, v96, v108, v101
	v_div_fixup_f32 v92, v96, v105, v92
	v_mul_f32_e32 v96, v92, v110
	v_fma_f32 v92, -v103, v106, 1.0
	v_mul_f32_e32 v105, 0xbfb8aa3b, v93
	v_fmac_f32_e32 v106, v92, v106
	v_div_scale_f32 v92, vcc, v97, v102, v97
	v_exp_f32_e32 v105, v105
	v_mul_f32_e32 v101, v92, v106
	v_fma_f32 v108, -v103, v101, v92
	v_fmac_f32_e32 v101, v108, v106
	v_fma_f32 v92, -v103, v101, v92
	v_add_f32_e32 v103, 1.0, v105
	v_div_scale_f32 v105, s[2:3], v103, v103, v93
	v_rcp_f32_e32 v108, v105
	v_div_fmas_f32 v92, v92, v106, v101
	v_div_fixup_f32 v92, v92, v102, v97
	v_and_b32_e32 v107, 0xffff0000, v107
	v_fma_f32 v97, -v105, v108, 1.0
	v_fmac_f32_e32 v108, v97, v108
	v_div_scale_f32 v97, vcc, v93, v103, v93
	v_mul_f32_e32 v101, v97, v108
	v_fma_f32 v102, -v105, v101, v97
	v_fmac_f32_e32 v101, v102, v108
	v_fma_f32 v97, -v105, v101, v97
	v_div_fmas_f32 v97, v97, v108, v101
	v_div_fixup_f32 v93, v97, v103, v93
	v_mul_f32_e32 v92, v92, v104
	v_mul_f32_e32 v93, v93, v107
	v_cvt_pk_bf16_f32 v90, v94, v90
	v_cvt_pk_bf16_f32 v91, v91, v92
	v_cvt_pk_bf16_f32 v92, v100, v95
	v_cvt_pk_bf16_f32 v93, v96, v93
	v_mul_f32_e32 v105, 0xbfb8aa3b, v82
	global_store_dwordx4 v[98:99], v[90:93], off
	v_exp_f32_e32 v105, v105
	s_waitcnt vmcnt(14)
	v_mov_b32_e32 v94, v206
	v_mov_b32_e32 v95, v207
	v_mov_b32_e32 v96, v208
	v_mov_b32_e32 v97, v209
	v_lshlrev_b32_e32 v102, 16, v97
	v_mul_f32_e32 v92, 0xbfb8aa3b, v86
	v_exp_f32_e32 v92, v92
	v_lshlrev_b32_e32 v90, 16, v94
	v_and_b32_e32 v91, 0xffff0000, v94
	v_lshlrev_b32_e32 v93, 16, v95
	v_add_f32_e32 v92, 1.0, v92
	v_div_scale_f32 v100, s[2:3], v92, v92, v86
	v_rcp_f32_e32 v101, v100
	v_and_b32_e32 v94, 0xffff0000, v95
	v_lshlrev_b32_e32 v95, 16, v96
	v_and_b32_e32 v96, 0xffff0000, v96
	v_fma_f32 v103, -v100, v101, 1.0
	v_fmac_f32_e32 v101, v103, v101
	v_div_scale_f32 v103, vcc, v86, v92, v86
	v_mul_f32_e32 v104, v103, v101
	v_fma_f32 v106, -v100, v104, v103
	v_fmac_f32_e32 v104, v106, v101
	v_fma_f32 v100, -v100, v104, v103
	v_add_f32_e32 v103, 1.0, v105
	v_div_scale_f32 v105, s[2:3], v103, v103, v82
	v_rcp_f32_e32 v106, v105
	v_div_fmas_f32 v100, v100, v101, v104
	v_div_fixup_f32 v86, v100, v92, v86
	v_mul_f32_e32 v100, 0xbfb8aa3b, v87
	v_exp_f32_e32 v100, v100
	v_mul_f32_e32 v86, v86, v90
	v_fma_f32 v90, -v105, v106, 1.0
	v_fmac_f32_e32 v106, v90, v106
	v_div_scale_f32 v90, vcc, v82, v103, v82
	v_mul_f32_e32 v92, v90, v106
	v_fma_f32 v101, -v105, v92, v90
	v_add_f32_e32 v100, 1.0, v100
	v_fmac_f32_e32 v92, v101, v106
	v_div_scale_f32 v101, s[2:3], v100, v100, v87
	v_fma_f32 v90, -v105, v92, v90
	v_rcp_f32_e32 v104, v101
	v_div_fmas_f32 v90, v90, v106, v92
	v_div_fixup_f32 v82, v90, v103, v82
	v_mul_f32_e32 v82, v82, v95
	v_mul_f32_e32 v95, 0xbfb8aa3b, v83
	v_fma_f32 v90, -v101, v104, 1.0
	v_exp_f32_e32 v95, v95
	v_fmac_f32_e32 v104, v90, v104
	v_div_scale_f32 v90, vcc, v87, v100, v87
	v_mul_f32_e32 v92, v90, v104
	v_fma_f32 v103, -v101, v92, v90
	v_fmac_f32_e32 v92, v103, v104
	v_add_f32_e32 v95, 1.0, v95
	v_fma_f32 v90, -v101, v92, v90
	v_div_scale_f32 v101, s[2:3], v95, v95, v83
	v_rcp_f32_e32 v103, v101
	v_div_fmas_f32 v90, v90, v104, v92
	v_mul_f32_e32 v92, 0xbfb8aa3b, v88
	v_exp_f32_e32 v92, v92
	v_div_fixup_f32 v87, v90, v100, v87
	v_fma_f32 v90, -v101, v103, 1.0
	v_fmac_f32_e32 v103, v90, v103
	v_div_scale_f32 v90, vcc, v83, v95, v83
	v_mul_f32_e32 v87, v87, v91
	v_mul_f32_e32 v91, v90, v103
	v_fma_f32 v100, -v101, v91, v90
	v_add_f32_e32 v92, 1.0, v92
	v_fmac_f32_e32 v91, v100, v103
	v_div_scale_f32 v100, s[2:3], v92, v92, v88
	v_fma_f32 v90, -v101, v91, v90
	v_rcp_f32_e32 v101, v100
	v_div_fmas_f32 v90, v90, v103, v91
	v_div_fixup_f32 v83, v90, v95, v83
	v_mul_f32_e32 v95, 0xbfb8aa3b, v84
	v_exp_f32_e32 v95, v95
	v_fma_f32 v90, -v100, v101, 1.0
	v_fmac_f32_e32 v101, v90, v101
	v_div_scale_f32 v90, vcc, v88, v92, v88
	v_mul_f32_e32 v91, v90, v101
	v_mul_f32_e32 v83, v83, v96
	v_fma_f32 v96, -v100, v91, v90
	v_add_f32_e32 v95, 1.0, v95
	v_fmac_f32_e32 v91, v96, v101
	v_div_scale_f32 v96, s[2:3], v95, v95, v84
	v_fma_f32 v90, -v100, v91, v90
	v_rcp_f32_e32 v100, v96
	v_div_fmas_f32 v90, v90, v101, v91
	v_div_fixup_f32 v88, v90, v92, v88
	v_mul_f32_e32 v92, 0xbfb8aa3b, v89
	v_exp_f32_e32 v92, v92
	v_fma_f32 v90, -v96, v100, 1.0
	v_fmac_f32_e32 v100, v90, v100
	v_div_scale_f32 v90, vcc, v84, v95, v84
	v_mul_f32_e32 v91, v90, v100
	v_mul_f32_e32 v88, v88, v93
	v_fma_f32 v93, -v96, v91, v90
	v_add_f32_e32 v92, 1.0, v92
	v_fmac_f32_e32 v91, v93, v100
	v_div_scale_f32 v93, s[2:3], v92, v92, v89
	v_fma_f32 v90, -v96, v91, v90
	v_rcp_f32_e32 v96, v93
	v_div_fmas_f32 v90, v90, v100, v91
	v_div_fixup_f32 v84, v90, v95, v84
	v_mul_f32_e32 v90, v84, v102
	v_fma_f32 v84, -v93, v96, 1.0
	v_mul_f32_e32 v95, 0xbfb8aa3b, v85
	v_fmac_f32_e32 v96, v84, v96
	v_div_scale_f32 v84, vcc, v89, v92, v89
	v_exp_f32_e32 v95, v95
	v_mul_f32_e32 v91, v84, v96
	v_fma_f32 v100, -v93, v91, v84
	v_fmac_f32_e32 v91, v100, v96
	v_fma_f32 v84, -v93, v91, v84
	v_add_f32_e32 v93, 1.0, v95
	v_div_scale_f32 v95, s[2:3], v93, v93, v85
	v_rcp_f32_e32 v100, v95
	v_div_fmas_f32 v84, v84, v96, v91
	v_div_fixup_f32 v84, v84, v92, v89
	v_mul_f32_e32 v89, v84, v94
	v_fma_f32 v84, -v95, v100, 1.0
	v_fmac_f32_e32 v100, v84, v100
	v_div_scale_f32 v84, vcc, v85, v93, v85
	v_mul_f32_e32 v91, v84, v100
	v_fma_f32 v92, -v95, v91, v84
	v_fmac_f32_e32 v91, v92, v100
	v_fma_f32 v84, -v95, v91, v84
	v_div_fmas_f32 v84, v84, v100, v91
	v_and_b32_e32 v97, 0xffff0000, v97
	v_div_fixup_f32 v84, v84, v93, v85
	v_mul_f32_e32 v91, v84, v97
	v_cvt_pk_bf16_f32 v84, v86, v87
	v_cvt_pk_bf16_f32 v85, v88, v89
	v_cvt_pk_bf16_f32 v86, v82, v83
	v_or_b32_e32 v82, 48, v150
	v_ashrrev_i32_e32 v83, 31, v82
	v_lshlrev_b64 v[82:83], 13, v[82:83]
	v_lshl_add_u64 v[82:83], s[10:11], 0, v[82:83]
	v_lshl_add_u64 v[82:83], v[82:83], 0, v[152:153]
	v_cvt_pk_bf16_f32 v87, v90, v91
	v_mul_f32_e32 v97, 0xbfb8aa3b, v74
	global_store_dwordx4 v[98:99], v[84:87], off offset:256
	v_exp_f32_e32 v97, v97
	s_waitcnt vmcnt(14)
	v_mov_b32_e32 v88, v210
	v_mov_b32_e32 v89, v211
	v_mov_b32_e32 v90, v212
	v_mov_b32_e32 v91, v213
	v_lshlrev_b32_e32 v94, 16, v91
	v_mul_f32_e32 v86, 0xbfb8aa3b, v78
	v_exp_f32_e32 v86, v86
	v_lshlrev_b32_e32 v84, 16, v88
	v_and_b32_e32 v85, 0xffff0000, v88
	v_lshlrev_b32_e32 v87, 16, v89
	v_add_f32_e32 v86, 1.0, v86
	v_div_scale_f32 v92, s[2:3], v86, v86, v78
	v_rcp_f32_e32 v93, v92
	v_and_b32_e32 v88, 0xffff0000, v89
	v_lshlrev_b32_e32 v89, 16, v90
	v_and_b32_e32 v90, 0xffff0000, v90
	v_fma_f32 v95, -v92, v93, 1.0
	v_fmac_f32_e32 v93, v95, v93
	v_div_scale_f32 v95, vcc, v78, v86, v78
	v_mul_f32_e32 v96, v95, v93
	v_fma_f32 v98, -v92, v96, v95
	v_fmac_f32_e32 v96, v98, v93
	v_fma_f32 v92, -v92, v96, v95
	v_add_f32_e32 v95, 1.0, v97
	v_div_scale_f32 v97, s[2:3], v95, v95, v74
	v_rcp_f32_e32 v98, v97
	v_div_fmas_f32 v92, v92, v93, v96
	v_div_fixup_f32 v78, v92, v86, v78
	v_mul_f32_e32 v92, 0xbfb8aa3b, v79
	v_exp_f32_e32 v92, v92
	v_mul_f32_e32 v78, v78, v84
	v_fma_f32 v84, -v97, v98, 1.0
	v_fmac_f32_e32 v98, v84, v98
	v_div_scale_f32 v84, vcc, v74, v95, v74
	v_mul_f32_e32 v86, v84, v98
	v_fma_f32 v93, -v97, v86, v84
	v_add_f32_e32 v92, 1.0, v92
	v_fmac_f32_e32 v86, v93, v98
	v_div_scale_f32 v93, s[2:3], v92, v92, v79
	v_fma_f32 v84, -v97, v86, v84
	v_rcp_f32_e32 v96, v93
	v_div_fmas_f32 v84, v84, v98, v86
	v_div_fixup_f32 v74, v84, v95, v74
	v_mul_f32_e32 v84, v74, v89
	v_mul_f32_e32 v89, 0xbfb8aa3b, v75
	v_fma_f32 v74, -v93, v96, 1.0
	v_exp_f32_e32 v89, v89
	v_fmac_f32_e32 v96, v74, v96
	v_div_scale_f32 v74, vcc, v79, v92, v79
	v_mul_f32_e32 v86, v74, v96
	v_fma_f32 v95, -v93, v86, v74
	v_fmac_f32_e32 v86, v95, v96
	v_add_f32_e32 v89, 1.0, v89
	v_fma_f32 v74, -v93, v86, v74
	v_div_scale_f32 v93, s[2:3], v89, v89, v75
	v_rcp_f32_e32 v95, v93
	v_div_fmas_f32 v74, v74, v96, v86
	v_mul_f32_e32 v86, 0xbfb8aa3b, v80
	v_exp_f32_e32 v86, v86
	v_div_fixup_f32 v74, v74, v92, v79
	v_fma_f32 v79, -v93, v95, 1.0
	v_fmac_f32_e32 v95, v79, v95
	v_div_scale_f32 v79, vcc, v75, v89, v75
	v_mul_f32_e32 v74, v74, v85
	v_mul_f32_e32 v85, v79, v95
	v_fma_f32 v92, -v93, v85, v79
	v_add_f32_e32 v86, 1.0, v86
	v_fmac_f32_e32 v85, v92, v95
	v_div_scale_f32 v92, s[2:3], v86, v86, v80
	v_fma_f32 v79, -v93, v85, v79
	v_rcp_f32_e32 v93, v92
	v_div_fmas_f32 v79, v79, v95, v85
	v_div_fixup_f32 v75, v79, v89, v75
	v_mul_f32_e32 v89, 0xbfb8aa3b, v76
	v_exp_f32_e32 v89, v89
	v_mul_f32_e32 v79, v75, v90
	v_fma_f32 v75, -v92, v93, 1.0
	v_fmac_f32_e32 v93, v75, v93
	v_div_scale_f32 v75, vcc, v80, v86, v80
	v_mul_f32_e32 v85, v75, v93
	v_fma_f32 v90, -v92, v85, v75
	v_add_f32_e32 v89, 1.0, v89
	v_fmac_f32_e32 v85, v90, v93
	v_div_scale_f32 v90, s[2:3], v89, v89, v76
	v_fma_f32 v75, -v92, v85, v75
	v_rcp_f32_e32 v92, v90
	v_div_fmas_f32 v75, v75, v93, v85
	v_div_fixup_f32 v75, v75, v86, v80
	v_mul_f32_e32 v86, 0xbfb8aa3b, v81
	v_exp_f32_e32 v86, v86
	v_fma_f32 v80, -v90, v92, 1.0
	v_fmac_f32_e32 v92, v80, v92
	v_div_scale_f32 v80, vcc, v76, v89, v76
	v_mul_f32_e32 v85, v80, v92
	v_mul_f32_e32 v75, v75, v87
	v_fma_f32 v87, -v90, v85, v80
	v_add_f32_e32 v86, 1.0, v86
	v_fmac_f32_e32 v85, v87, v92
	v_div_scale_f32 v87, s[2:3], v86, v86, v81
	v_fma_f32 v80, -v90, v85, v80
	v_rcp_f32_e32 v90, v87
	v_div_fmas_f32 v80, v80, v92, v85
	v_div_fixup_f32 v76, v80, v89, v76
	v_mul_f32_e32 v80, v76, v94
	v_fma_f32 v76, -v87, v90, 1.0
	v_mul_f32_e32 v89, 0xbfb8aa3b, v77
	v_fmac_f32_e32 v90, v76, v90
	v_div_scale_f32 v76, vcc, v81, v86, v81
	v_exp_f32_e32 v89, v89
	v_mul_f32_e32 v85, v76, v90
	v_fma_f32 v92, -v87, v85, v76
	v_fmac_f32_e32 v85, v92, v90
	v_fma_f32 v76, -v87, v85, v76
	v_add_f32_e32 v87, 1.0, v89
	v_div_scale_f32 v89, s[2:3], v87, v87, v77
	v_rcp_f32_e32 v92, v89
	v_div_fmas_f32 v76, v76, v90, v85
	v_div_fixup_f32 v76, v76, v86, v81
	v_and_b32_e32 v91, 0xffff0000, v91
	v_fma_f32 v81, -v89, v92, 1.0
	v_fmac_f32_e32 v92, v81, v92
	v_div_scale_f32 v81, vcc, v77, v87, v77
	v_mul_f32_e32 v85, v81, v92
	v_fma_f32 v86, -v89, v85, v81
	v_fmac_f32_e32 v85, v86, v92
	v_fma_f32 v81, -v89, v85, v81
	v_div_fmas_f32 v81, v81, v92, v85
	v_div_fixup_f32 v77, v81, v87, v77
	v_mul_f32_e32 v76, v76, v88
	v_mul_f32_e32 v77, v77, v91
	v_cvt_pk_bf16_f32 v74, v78, v74
	v_cvt_pk_bf16_f32 v75, v75, v76
	v_cvt_pk_bf16_f32 v76, v84, v79
	v_cvt_pk_bf16_f32 v77, v80, v77
	v_mul_f32_e32 v89, 0xbfb8aa3b, v66
	global_store_dwordx4 v[82:83], v[74:77], off
	v_exp_f32_e32 v89, v89
	s_waitcnt vmcnt(14)
	v_mov_b32_e32 v78, v214
	v_mov_b32_e32 v79, v215
	v_mov_b32_e32 v80, v216
	v_mov_b32_e32 v81, v217
	v_lshlrev_b32_e32 v86, 16, v81
	v_mul_f32_e32 v76, 0xbfb8aa3b, v70
	v_exp_f32_e32 v76, v76
	v_lshlrev_b32_e32 v74, 16, v78
	v_and_b32_e32 v75, 0xffff0000, v78
	v_lshlrev_b32_e32 v77, 16, v79
	v_add_f32_e32 v76, 1.0, v76
	v_div_scale_f32 v84, s[2:3], v76, v76, v70
	v_rcp_f32_e32 v85, v84
	v_and_b32_e32 v78, 0xffff0000, v79
	v_lshlrev_b32_e32 v79, 16, v80
	v_and_b32_e32 v80, 0xffff0000, v80
	v_fma_f32 v87, -v84, v85, 1.0
	v_fmac_f32_e32 v85, v87, v85
	v_div_scale_f32 v87, vcc, v70, v76, v70
	v_mul_f32_e32 v88, v87, v85
	v_fma_f32 v90, -v84, v88, v87
	v_fmac_f32_e32 v88, v90, v85
	v_fma_f32 v84, -v84, v88, v87
	v_add_f32_e32 v87, 1.0, v89
	v_div_scale_f32 v89, s[2:3], v87, v87, v66
	v_rcp_f32_e32 v90, v89
	v_div_fmas_f32 v84, v84, v85, v88
	v_div_fixup_f32 v70, v84, v76, v70
	v_mul_f32_e32 v84, 0xbfb8aa3b, v71
	v_exp_f32_e32 v84, v84
	v_mul_f32_e32 v70, v70, v74
	v_fma_f32 v74, -v89, v90, 1.0
	v_fmac_f32_e32 v90, v74, v90
	v_div_scale_f32 v74, vcc, v66, v87, v66
	v_mul_f32_e32 v76, v74, v90
	v_fma_f32 v85, -v89, v76, v74
	v_add_f32_e32 v84, 1.0, v84
	v_fmac_f32_e32 v76, v85, v90
	v_div_scale_f32 v85, s[2:3], v84, v84, v71
	v_fma_f32 v74, -v89, v76, v74
	v_rcp_f32_e32 v88, v85
	v_div_fmas_f32 v74, v74, v90, v76
	v_div_fixup_f32 v66, v74, v87, v66
	v_mul_f32_e32 v74, v66, v79
	v_mul_f32_e32 v79, 0xbfb8aa3b, v67
	v_fma_f32 v66, -v85, v88, 1.0
	v_exp_f32_e32 v79, v79
	v_fmac_f32_e32 v88, v66, v88
	v_div_scale_f32 v66, vcc, v71, v84, v71
	v_mul_f32_e32 v76, v66, v88
	v_fma_f32 v87, -v85, v76, v66
	v_fmac_f32_e32 v76, v87, v88
	v_add_f32_e32 v79, 1.0, v79
	v_fma_f32 v66, -v85, v76, v66
	v_div_scale_f32 v85, s[2:3], v79, v79, v67
	v_rcp_f32_e32 v87, v85
	v_div_fmas_f32 v66, v66, v88, v76
	v_mul_f32_e32 v76, 0xbfb8aa3b, v72
	v_exp_f32_e32 v76, v76
	v_div_fixup_f32 v66, v66, v84, v71
	v_fma_f32 v71, -v85, v87, 1.0
	v_fmac_f32_e32 v87, v71, v87
	v_div_scale_f32 v71, vcc, v67, v79, v67
	v_mul_f32_e32 v66, v66, v75
	v_mul_f32_e32 v75, v71, v87
	v_fma_f32 v84, -v85, v75, v71
	v_add_f32_e32 v76, 1.0, v76
	v_fmac_f32_e32 v75, v84, v87
	v_div_scale_f32 v84, s[2:3], v76, v76, v72
	v_fma_f32 v71, -v85, v75, v71
	v_rcp_f32_e32 v85, v84
	v_div_fmas_f32 v71, v71, v87, v75
	v_div_fixup_f32 v67, v71, v79, v67
	v_mul_f32_e32 v79, 0xbfb8aa3b, v68
	v_exp_f32_e32 v79, v79
	v_mul_f32_e32 v71, v67, v80
	v_fma_f32 v67, -v84, v85, 1.0
	v_fmac_f32_e32 v85, v67, v85
	v_div_scale_f32 v67, vcc, v72, v76, v72
	v_mul_f32_e32 v75, v67, v85
	v_fma_f32 v80, -v84, v75, v67
	v_add_f32_e32 v79, 1.0, v79
	v_fmac_f32_e32 v75, v80, v85
	v_div_scale_f32 v80, s[2:3], v79, v79, v68
	v_fma_f32 v67, -v84, v75, v67
	v_rcp_f32_e32 v84, v80
	v_div_fmas_f32 v67, v67, v85, v75
	v_div_fixup_f32 v67, v67, v76, v72
	v_mul_f32_e32 v76, 0xbfb8aa3b, v73
	v_exp_f32_e32 v76, v76
	v_fma_f32 v72, -v80, v84, 1.0
	v_fmac_f32_e32 v84, v72, v84
	v_div_scale_f32 v72, vcc, v68, v79, v68
	v_mul_f32_e32 v75, v72, v84
	v_mul_f32_e32 v67, v67, v77
	v_fma_f32 v77, -v80, v75, v72
	v_add_f32_e32 v76, 1.0, v76
	v_fmac_f32_e32 v75, v77, v84
	v_div_scale_f32 v77, s[2:3], v76, v76, v73
	v_fma_f32 v72, -v80, v75, v72
	v_rcp_f32_e32 v80, v77
	v_div_fmas_f32 v72, v72, v84, v75
	v_div_fixup_f32 v68, v72, v79, v68
	v_mul_f32_e32 v72, v68, v86
	v_fma_f32 v68, -v77, v80, 1.0
	v_mul_f32_e32 v79, 0xbfb8aa3b, v69
	v_fmac_f32_e32 v80, v68, v80
	v_div_scale_f32 v68, vcc, v73, v76, v73
	v_exp_f32_e32 v79, v79
	v_mul_f32_e32 v75, v68, v80
	v_fma_f32 v84, -v77, v75, v68
	v_fmac_f32_e32 v75, v84, v80
	v_fma_f32 v68, -v77, v75, v68
	v_add_f32_e32 v77, 1.0, v79
	v_div_scale_f32 v79, s[2:3], v77, v77, v69
	v_rcp_f32_e32 v84, v79
	v_div_fmas_f32 v68, v68, v80, v75
	v_div_fixup_f32 v68, v68, v76, v73
	v_mul_f32_e32 v68, v68, v78
	v_fma_f32 v73, -v79, v84, 1.0
	v_fmac_f32_e32 v84, v73, v84
	v_div_scale_f32 v73, vcc, v69, v77, v69
	v_mul_f32_e32 v75, v73, v84
	v_fma_f32 v76, -v79, v75, v73
	v_fmac_f32_e32 v75, v76, v84
	v_fma_f32 v73, -v79, v75, v73
	v_div_fmas_f32 v73, v73, v84, v75
	v_and_b32_e32 v81, 0xffff0000, v81
	v_div_fixup_f32 v69, v73, v77, v69
	v_cvt_pk_bf16_f32 v66, v70, v66
	v_cvt_pk_bf16_f32 v67, v67, v68
	v_cvt_pk_bf16_f32 v68, v74, v71
	v_add_co_u32_e32 v74, vcc, s48, v148
	v_mul_f32_e32 v69, v69, v81
	s_nop 0
	v_addc_co_u32_e32 v75, vcc, 0, v149, vcc
	v_cvt_pk_bf16_f32 v69, v72, v69
	s_waitcnt vmcnt(14)
	v_mov_b32_e32 v70, v218
	v_mov_b32_e32 v71, v219
	v_mov_b32_e32 v72, v220
	v_mov_b32_e32 v73, v221
	v_lshlrev_b32_e32 v77, 16, v72
	global_store_dwordx4 v[82:83], v[66:69], off offset:256
	v_mul_f32_e32 v83, 0xbfb8aa3b, v58
	v_exp_f32_e32 v83, v83
	v_lshlrev_b32_e32 v68, 16, v70
	v_and_b32_e32 v69, 0xffff0000, v70
	v_mul_f32_e32 v70, 0xbfb8aa3b, v62
	v_exp_f32_e32 v70, v70
	v_and_b32_e32 v72, 0xffff0000, v72
	v_lshlrev_b32_e32 v76, 16, v71
	v_lshlrev_b32_e32 v80, 16, v73
	v_add_f32_e32 v70, 1.0, v70
	v_div_scale_f32 v78, s[2:3], v70, v70, v62
	v_rcp_f32_e32 v79, v78
	v_and_b32_e32 v71, 0xffff0000, v71
	v_and_b32_e32 v73, 0xffff0000, v73
	v_lshl_add_u64 v[66:67], v[148:149], 0, s[14:15]
	v_fma_f32 v81, -v78, v79, 1.0
	v_fmac_f32_e32 v79, v81, v79
	v_div_scale_f32 v81, vcc, v62, v70, v62
	v_mul_f32_e32 v82, v81, v79
	v_fma_f32 v84, -v78, v82, v81
	v_fmac_f32_e32 v82, v84, v79
	v_fma_f32 v78, -v78, v82, v81
	v_add_f32_e32 v81, 1.0, v83
	v_div_scale_f32 v83, s[2:3], v81, v81, v58
	v_rcp_f32_e32 v84, v83
	v_div_fmas_f32 v78, v78, v79, v82
	v_div_fixup_f32 v62, v78, v70, v62
	v_mul_f32_e32 v78, 0xbfb8aa3b, v63
	v_exp_f32_e32 v78, v78
	v_mul_f32_e32 v62, v62, v68
	v_fma_f32 v68, -v83, v84, 1.0
	v_fmac_f32_e32 v84, v68, v84
	v_div_scale_f32 v68, vcc, v58, v81, v58
	v_mul_f32_e32 v70, v68, v84
	v_fma_f32 v79, -v83, v70, v68
	v_add_f32_e32 v78, 1.0, v78
	v_fmac_f32_e32 v70, v79, v84
	v_div_scale_f32 v79, s[2:3], v78, v78, v63
	v_fma_f32 v68, -v83, v70, v68
	v_rcp_f32_e32 v82, v79
	v_div_fmas_f32 v68, v68, v84, v70
	v_div_fixup_f32 v58, v68, v81, v58
	v_mul_f32_e32 v68, v58, v77
	v_mul_f32_e32 v77, 0xbfb8aa3b, v59
	v_fma_f32 v58, -v79, v82, 1.0
	v_exp_f32_e32 v77, v77
	v_fmac_f32_e32 v82, v58, v82
	v_div_scale_f32 v58, vcc, v63, v78, v63
	v_mul_f32_e32 v70, v58, v82
	v_fma_f32 v81, -v79, v70, v58
	v_fmac_f32_e32 v70, v81, v82
	v_add_f32_e32 v77, 1.0, v77
	v_fma_f32 v58, -v79, v70, v58
	v_div_scale_f32 v79, s[2:3], v77, v77, v59
	v_rcp_f32_e32 v81, v79
	v_div_fmas_f32 v58, v58, v82, v70
	v_mul_f32_e32 v70, 0xbfb8aa3b, v64
	v_div_fixup_f32 v58, v58, v78, v63
	v_fma_f32 v63, -v79, v81, 1.0
	v_exp_f32_e32 v70, v70
	v_fmac_f32_e32 v81, v63, v81
	v_div_scale_f32 v63, vcc, v59, v77, v59
	v_mul_f32_e32 v58, v58, v69
	v_mul_f32_e32 v69, v63, v81
	v_fma_f32 v78, -v79, v69, v63
	v_fmac_f32_e32 v69, v78, v81
	v_add_f32_e32 v70, 1.0, v70
	v_fma_f32 v63, -v79, v69, v63
	v_div_scale_f32 v78, s[2:3], v70, v70, v64
	v_rcp_f32_e32 v79, v78
	v_div_fmas_f32 v63, v63, v81, v69
	v_div_fixup_f32 v59, v63, v77, v59
	v_mul_f32_e32 v63, v59, v72
	v_mul_f32_e32 v72, 0xbfb8aa3b, v60
	v_exp_f32_e32 v72, v72
	v_fma_f32 v59, -v78, v79, 1.0
	v_fmac_f32_e32 v79, v59, v79
	v_div_scale_f32 v59, vcc, v64, v70, v64
	v_mul_f32_e32 v69, v59, v79
	v_fma_f32 v77, -v78, v69, v59
	v_add_f32_e32 v72, 1.0, v72
	v_fmac_f32_e32 v69, v77, v79
	v_div_scale_f32 v77, s[2:3], v72, v72, v60
	v_fma_f32 v59, -v78, v69, v59
	v_rcp_f32_e32 v78, v77
	v_div_fmas_f32 v59, v59, v79, v69
	v_div_fixup_f32 v59, v59, v70, v64
	v_mul_f32_e32 v70, 0xbfb8aa3b, v65
	v_exp_f32_e32 v70, v70
	v_fma_f32 v64, -v77, v78, 1.0
	v_fmac_f32_e32 v78, v64, v78
	v_div_scale_f32 v64, vcc, v60, v72, v60
	v_mul_f32_e32 v69, v64, v78
	v_mul_f32_e32 v59, v59, v76
	v_fma_f32 v76, -v77, v69, v64
	v_add_f32_e32 v70, 1.0, v70
	v_fmac_f32_e32 v69, v76, v78
	v_div_scale_f32 v76, s[2:3], v70, v70, v65
	v_fma_f32 v64, -v77, v69, v64
	v_rcp_f32_e32 v77, v76
	v_div_fmas_f32 v64, v64, v78, v69
	v_div_fixup_f32 v60, v64, v72, v60
	v_mul_f32_e32 v72, 0xbfb8aa3b, v61
	v_mul_f32_e32 v64, v60, v80
	v_fma_f32 v60, -v76, v77, 1.0
	v_exp_f32_e32 v72, v72
	v_fmac_f32_e32 v77, v60, v77
	v_div_scale_f32 v60, vcc, v65, v70, v65
	v_mul_f32_e32 v69, v60, v77
	v_fma_f32 v78, -v76, v69, v60
	v_fmac_f32_e32 v69, v78, v77
	v_add_f32_e32 v72, 1.0, v72
	v_fma_f32 v60, -v76, v69, v60
	v_div_scale_f32 v76, s[2:3], v72, v72, v61
	v_rcp_f32_e32 v78, v76
	v_div_fmas_f32 v60, v60, v77, v69
	v_div_fixup_f32 v60, v60, v70, v65
	v_mul_f32_e32 v60, v60, v71
	v_fma_f32 v65, -v76, v78, 1.0
	v_fmac_f32_e32 v78, v65, v78
	v_div_scale_f32 v65, vcc, v61, v72, v61
	v_mul_f32_e32 v69, v65, v78
	v_fma_f32 v70, -v76, v69, v65
	v_fmac_f32_e32 v69, v70, v78
	v_fma_f32 v65, -v76, v69, v65
	v_div_fmas_f32 v65, v65, v78, v69
	v_div_fixup_f32 v61, v65, v72, v61
	v_mul_f32_e32 v61, v61, v73
	v_cvt_pk_bf16_f32 v58, v62, v58
	v_cvt_pk_bf16_f32 v59, v59, v60
	v_cvt_pk_bf16_f32 v60, v68, v63
	v_cvt_pk_bf16_f32 v61, v64, v61
	v_mul_f32_e32 v73, 0xbfb8aa3b, v50
	global_store_dwordx4 v[74:75], v[58:61], off
	v_exp_f32_e32 v73, v73
	s_waitcnt vmcnt(14)
	v_mov_b32_e32 v62, v222
	v_mov_b32_e32 v63, v223
	v_mov_b32_e32 v64, v224
	v_mov_b32_e32 v65, v225
	v_lshlrev_b32_e32 v70, 16, v65
	v_mul_f32_e32 v60, 0xbfb8aa3b, v54
	v_exp_f32_e32 v60, v60
	v_lshlrev_b32_e32 v58, 16, v62
	v_and_b32_e32 v59, 0xffff0000, v62
	v_lshlrev_b32_e32 v61, 16, v63
	v_add_f32_e32 v60, 1.0, v60
	v_div_scale_f32 v68, s[2:3], v60, v60, v54
	v_rcp_f32_e32 v69, v68
	v_and_b32_e32 v62, 0xffff0000, v63
	v_lshlrev_b32_e32 v63, 16, v64
	v_and_b32_e32 v64, 0xffff0000, v64
	v_fma_f32 v71, -v68, v69, 1.0
	v_fmac_f32_e32 v69, v71, v69
	v_div_scale_f32 v71, vcc, v54, v60, v54
	v_mul_f32_e32 v72, v71, v69
	v_fma_f32 v74, -v68, v72, v71
	v_fmac_f32_e32 v72, v74, v69
	v_fma_f32 v68, -v68, v72, v71
	v_add_f32_e32 v71, 1.0, v73
	v_div_scale_f32 v73, s[2:3], v71, v71, v50
	v_rcp_f32_e32 v74, v73
	v_div_fmas_f32 v68, v68, v69, v72
	v_div_fixup_f32 v54, v68, v60, v54
	v_mul_f32_e32 v68, 0xbfb8aa3b, v55
	v_exp_f32_e32 v68, v68
	v_mul_f32_e32 v54, v54, v58
	v_fma_f32 v58, -v73, v74, 1.0
	v_fmac_f32_e32 v74, v58, v74
	v_div_scale_f32 v58, vcc, v50, v71, v50
	v_mul_f32_e32 v60, v58, v74
	v_fma_f32 v69, -v73, v60, v58
	v_add_f32_e32 v68, 1.0, v68
	v_fmac_f32_e32 v60, v69, v74
	v_div_scale_f32 v69, s[2:3], v68, v68, v55
	v_fma_f32 v58, -v73, v60, v58
	v_rcp_f32_e32 v72, v69
	v_div_fmas_f32 v58, v58, v74, v60
	v_div_fixup_f32 v50, v58, v71, v50
	v_mul_f32_e32 v58, v50, v63
	v_mul_f32_e32 v63, 0xbfb8aa3b, v51
	v_fma_f32 v50, -v69, v72, 1.0
	v_exp_f32_e32 v63, v63
	v_fmac_f32_e32 v72, v50, v72
	v_div_scale_f32 v50, vcc, v55, v68, v55
	v_mul_f32_e32 v60, v50, v72
	v_fma_f32 v71, -v69, v60, v50
	v_fmac_f32_e32 v60, v71, v72
	v_add_f32_e32 v63, 1.0, v63
	v_fma_f32 v50, -v69, v60, v50
	v_div_scale_f32 v69, s[2:3], v63, v63, v51
	v_rcp_f32_e32 v71, v69
	v_div_fmas_f32 v50, v50, v72, v60
	v_mul_f32_e32 v60, 0xbfb8aa3b, v56
	v_exp_f32_e32 v60, v60
	v_div_fixup_f32 v50, v50, v68, v55
	v_fma_f32 v55, -v69, v71, 1.0
	v_fmac_f32_e32 v71, v55, v71
	v_div_scale_f32 v55, vcc, v51, v63, v51
	v_mul_f32_e32 v50, v50, v59
	v_mul_f32_e32 v59, v55, v71
	v_fma_f32 v68, -v69, v59, v55
	v_add_f32_e32 v60, 1.0, v60
	v_fmac_f32_e32 v59, v68, v71
	v_div_scale_f32 v68, s[2:3], v60, v60, v56
	v_fma_f32 v55, -v69, v59, v55
	v_rcp_f32_e32 v69, v68
	v_div_fmas_f32 v55, v55, v71, v59
	v_div_fixup_f32 v51, v55, v63, v51
	v_mul_f32_e32 v63, 0xbfb8aa3b, v52
	v_exp_f32_e32 v63, v63
	v_mul_f32_e32 v55, v51, v64
	v_fma_f32 v51, -v68, v69, 1.0
	v_fmac_f32_e32 v69, v51, v69
	v_div_scale_f32 v51, vcc, v56, v60, v56
	v_mul_f32_e32 v59, v51, v69
	v_fma_f32 v64, -v68, v59, v51
	v_add_f32_e32 v63, 1.0, v63
	v_fmac_f32_e32 v59, v64, v69
	v_div_scale_f32 v64, s[2:3], v63, v63, v52
	v_fma_f32 v51, -v68, v59, v51
	v_rcp_f32_e32 v68, v64
	v_div_fmas_f32 v51, v51, v69, v59
	v_div_fixup_f32 v51, v51, v60, v56
	v_mul_f32_e32 v60, 0xbfb8aa3b, v57
	v_exp_f32_e32 v60, v60
	v_fma_f32 v56, -v64, v68, 1.0
	v_fmac_f32_e32 v68, v56, v68
	v_div_scale_f32 v56, vcc, v52, v63, v52
	v_mul_f32_e32 v59, v56, v68
	v_mul_f32_e32 v51, v51, v61
	v_fma_f32 v61, -v64, v59, v56
	v_add_f32_e32 v60, 1.0, v60
	v_fmac_f32_e32 v59, v61, v68
	v_div_scale_f32 v61, s[2:3], v60, v60, v57
	v_fma_f32 v56, -v64, v59, v56
	v_rcp_f32_e32 v64, v61
	v_div_fmas_f32 v56, v56, v68, v59
	v_div_fixup_f32 v52, v56, v63, v52
	v_mul_f32_e32 v56, v52, v70
	v_fma_f32 v52, -v61, v64, 1.0
	v_mul_f32_e32 v63, 0xbfb8aa3b, v53
	v_fmac_f32_e32 v64, v52, v64
	v_div_scale_f32 v52, vcc, v57, v60, v57
	v_exp_f32_e32 v63, v63
	v_mul_f32_e32 v59, v52, v64
	v_fma_f32 v68, -v61, v59, v52
	v_fmac_f32_e32 v59, v68, v64
	v_fma_f32 v52, -v61, v59, v52
	v_add_f32_e32 v61, 1.0, v63
	v_div_scale_f32 v63, s[2:3], v61, v61, v53
	v_rcp_f32_e32 v68, v63
	v_div_fmas_f32 v52, v52, v64, v59
	v_div_fixup_f32 v52, v52, v60, v57
	v_mul_f32_e32 v52, v52, v62
	v_fma_f32 v57, -v63, v68, 1.0
	v_fmac_f32_e32 v68, v57, v68
	v_div_scale_f32 v57, vcc, v53, v61, v53
	v_mul_f32_e32 v59, v57, v68
	v_fma_f32 v60, -v63, v59, v57
	v_fmac_f32_e32 v59, v60, v68
	v_fma_f32 v57, -v63, v59, v57
	v_div_fmas_f32 v57, v57, v68, v59
	v_and_b32_e32 v65, 0xffff0000, v65
	v_div_fixup_f32 v53, v57, v61, v53
	v_cvt_pk_bf16_f32 v50, v54, v50
	v_cvt_pk_bf16_f32 v51, v51, v52
	v_cvt_pk_bf16_f32 v52, v58, v55
	v_add_co_u32_e32 v58, vcc, s49, v148
	v_mul_f32_e32 v53, v53, v65
	s_nop 0
	v_addc_co_u32_e32 v59, vcc, 0, v149, vcc
	v_cvt_pk_bf16_f32 v53, v56, v53
	s_waitcnt vmcnt(14)
	v_mov_b32_e32 v54, v226
	v_mov_b32_e32 v55, v227
	v_mov_b32_e32 v56, v228
	v_mov_b32_e32 v57, v229
	v_lshlrev_b32_e32 v61, 16, v56
	global_store_dwordx4 v[66:67], v[50:53], off offset:256
	v_mul_f32_e32 v67, 0xbfb8aa3b, v42
	v_exp_f32_e32 v67, v67
	v_lshlrev_b32_e32 v52, 16, v54
	v_and_b32_e32 v53, 0xffff0000, v54
	v_mul_f32_e32 v54, 0xbfb8aa3b, v46
	v_exp_f32_e32 v54, v54
	v_and_b32_e32 v56, 0xffff0000, v56
	v_lshlrev_b32_e32 v60, 16, v55
	v_lshlrev_b32_e32 v64, 16, v57
	v_add_f32_e32 v54, 1.0, v54
	v_div_scale_f32 v62, s[2:3], v54, v54, v46
	v_rcp_f32_e32 v63, v62
	v_and_b32_e32 v55, 0xffff0000, v55
	v_and_b32_e32 v57, 0xffff0000, v57
	v_lshl_add_u64 v[50:51], v[148:149], 0, s[16:17]
	v_fma_f32 v65, -v62, v63, 1.0
	v_fmac_f32_e32 v63, v65, v63
	v_div_scale_f32 v65, vcc, v46, v54, v46
	v_mul_f32_e32 v66, v65, v63
	v_fma_f32 v68, -v62, v66, v65
	v_fmac_f32_e32 v66, v68, v63
	v_fma_f32 v62, -v62, v66, v65
	v_add_f32_e32 v65, 1.0, v67
	v_div_scale_f32 v67, s[2:3], v65, v65, v42
	v_rcp_f32_e32 v68, v67
	v_div_fmas_f32 v62, v62, v63, v66
	v_div_fixup_f32 v46, v62, v54, v46
	v_mul_f32_e32 v62, 0xbfb8aa3b, v47
	v_exp_f32_e32 v62, v62
	v_mul_f32_e32 v46, v46, v52
	v_fma_f32 v52, -v67, v68, 1.0
	v_fmac_f32_e32 v68, v52, v68
	v_div_scale_f32 v52, vcc, v42, v65, v42
	v_mul_f32_e32 v54, v52, v68
	v_fma_f32 v63, -v67, v54, v52
	v_add_f32_e32 v62, 1.0, v62
	v_fmac_f32_e32 v54, v63, v68
	v_div_scale_f32 v63, s[2:3], v62, v62, v47
	v_fma_f32 v52, -v67, v54, v52
	v_rcp_f32_e32 v66, v63
	v_div_fmas_f32 v52, v52, v68, v54
	v_div_fixup_f32 v42, v52, v65, v42
	v_mul_f32_e32 v52, v42, v61
	v_mul_f32_e32 v61, 0xbfb8aa3b, v43
	v_fma_f32 v42, -v63, v66, 1.0
	v_exp_f32_e32 v61, v61
	v_fmac_f32_e32 v66, v42, v66
	v_div_scale_f32 v42, vcc, v47, v62, v47
	v_mul_f32_e32 v54, v42, v66
	v_fma_f32 v65, -v63, v54, v42
	v_fmac_f32_e32 v54, v65, v66
	v_add_f32_e32 v61, 1.0, v61
	v_fma_f32 v42, -v63, v54, v42
	v_div_scale_f32 v63, s[2:3], v61, v61, v43
	v_rcp_f32_e32 v65, v63
	v_div_fmas_f32 v42, v42, v66, v54
	v_mul_f32_e32 v54, 0xbfb8aa3b, v48
	v_div_fixup_f32 v42, v42, v62, v47
	v_fma_f32 v47, -v63, v65, 1.0
	v_exp_f32_e32 v54, v54
	v_fmac_f32_e32 v65, v47, v65
	v_div_scale_f32 v47, vcc, v43, v61, v43
	v_mul_f32_e32 v42, v42, v53
	v_mul_f32_e32 v53, v47, v65
	v_fma_f32 v62, -v63, v53, v47
	v_fmac_f32_e32 v53, v62, v65
	v_add_f32_e32 v54, 1.0, v54
	v_fma_f32 v47, -v63, v53, v47
	v_div_scale_f32 v62, s[2:3], v54, v54, v48
	v_rcp_f32_e32 v63, v62
	v_div_fmas_f32 v47, v47, v65, v53
	v_div_fixup_f32 v43, v47, v61, v43
	v_mul_f32_e32 v47, v43, v56
	v_mul_f32_e32 v56, 0xbfb8aa3b, v44
	v_exp_f32_e32 v56, v56
	v_fma_f32 v43, -v62, v63, 1.0
	v_fmac_f32_e32 v63, v43, v63
	v_div_scale_f32 v43, vcc, v48, v54, v48
	v_mul_f32_e32 v53, v43, v63
	v_fma_f32 v61, -v62, v53, v43
	v_add_f32_e32 v56, 1.0, v56
	v_fmac_f32_e32 v53, v61, v63
	v_div_scale_f32 v61, s[2:3], v56, v56, v44
	v_fma_f32 v43, -v62, v53, v43
	v_rcp_f32_e32 v62, v61
	v_div_fmas_f32 v43, v43, v63, v53
	v_div_fixup_f32 v43, v43, v54, v48
	v_mul_f32_e32 v54, 0xbfb8aa3b, v49
	v_exp_f32_e32 v54, v54
	v_fma_f32 v48, -v61, v62, 1.0
	v_fmac_f32_e32 v62, v48, v62
	v_div_scale_f32 v48, vcc, v44, v56, v44
	v_mul_f32_e32 v53, v48, v62
	v_mul_f32_e32 v43, v43, v60
	v_fma_f32 v60, -v61, v53, v48
	v_add_f32_e32 v54, 1.0, v54
	v_fmac_f32_e32 v53, v60, v62
	v_div_scale_f32 v60, s[2:3], v54, v54, v49
	v_fma_f32 v48, -v61, v53, v48
	v_rcp_f32_e32 v61, v60
	v_div_fmas_f32 v48, v48, v62, v53
	v_div_fixup_f32 v44, v48, v56, v44
	v_mul_f32_e32 v56, 0xbfb8aa3b, v45
	v_mul_f32_e32 v48, v44, v64
	v_fma_f32 v44, -v60, v61, 1.0
	v_exp_f32_e32 v56, v56
	v_fmac_f32_e32 v61, v44, v61
	v_div_scale_f32 v44, vcc, v49, v54, v49
	v_mul_f32_e32 v53, v44, v61
	v_fma_f32 v62, -v60, v53, v44
	v_fmac_f32_e32 v53, v62, v61
	v_add_f32_e32 v56, 1.0, v56
	v_fma_f32 v44, -v60, v53, v44
	v_div_scale_f32 v60, s[2:3], v56, v56, v45
	v_rcp_f32_e32 v62, v60
	v_div_fmas_f32 v44, v44, v61, v53
	v_div_fixup_f32 v44, v44, v54, v49
	v_mul_f32_e32 v44, v44, v55
	v_fma_f32 v49, -v60, v62, 1.0
	v_fmac_f32_e32 v62, v49, v62
	v_div_scale_f32 v49, vcc, v45, v56, v45
	v_mul_f32_e32 v53, v49, v62
	v_fma_f32 v54, -v60, v53, v49
	v_fmac_f32_e32 v53, v54, v62
	v_fma_f32 v49, -v60, v53, v49
	v_div_fmas_f32 v49, v49, v62, v53
	v_div_fixup_f32 v45, v49, v56, v45
	v_mul_f32_e32 v45, v45, v57
	v_cvt_pk_bf16_f32 v42, v46, v42
	v_cvt_pk_bf16_f32 v43, v43, v44
	v_cvt_pk_bf16_f32 v44, v52, v47
	v_cvt_pk_bf16_f32 v45, v48, v45
	v_mul_f32_e32 v57, 0xbfb8aa3b, v34
	global_store_dwordx4 v[58:59], v[42:45], off
	v_exp_f32_e32 v57, v57
	s_waitcnt vmcnt(14)
	v_mov_b32_e32 v46, v230
	v_mov_b32_e32 v47, v231
	v_mov_b32_e32 v48, v232
	v_mov_b32_e32 v49, v233
	v_lshlrev_b32_e32 v54, 16, v49
	v_mul_f32_e32 v44, 0xbfb8aa3b, v38
	v_exp_f32_e32 v44, v44
	v_lshlrev_b32_e32 v42, 16, v46
	v_and_b32_e32 v43, 0xffff0000, v46
	v_lshlrev_b32_e32 v45, 16, v47
	v_add_f32_e32 v44, 1.0, v44
	v_div_scale_f32 v52, s[2:3], v44, v44, v38
	v_rcp_f32_e32 v53, v52
	v_and_b32_e32 v46, 0xffff0000, v47
	v_lshlrev_b32_e32 v47, 16, v48
	v_and_b32_e32 v48, 0xffff0000, v48
	v_fma_f32 v55, -v52, v53, 1.0
	v_fmac_f32_e32 v53, v55, v53
	v_div_scale_f32 v55, vcc, v38, v44, v38
	v_mul_f32_e32 v56, v55, v53
	v_fma_f32 v58, -v52, v56, v55
	v_fmac_f32_e32 v56, v58, v53
	v_fma_f32 v52, -v52, v56, v55
	v_add_f32_e32 v55, 1.0, v57
	v_div_scale_f32 v57, s[2:3], v55, v55, v34
	v_rcp_f32_e32 v58, v57
	v_div_fmas_f32 v52, v52, v53, v56
	v_div_fixup_f32 v38, v52, v44, v38
	v_mul_f32_e32 v52, 0xbfb8aa3b, v39
	v_exp_f32_e32 v52, v52
	v_mul_f32_e32 v38, v38, v42
	v_fma_f32 v42, -v57, v58, 1.0
	v_fmac_f32_e32 v58, v42, v58
	v_div_scale_f32 v42, vcc, v34, v55, v34
	v_mul_f32_e32 v44, v42, v58
	v_fma_f32 v53, -v57, v44, v42
	v_add_f32_e32 v52, 1.0, v52
	v_fmac_f32_e32 v44, v53, v58
	v_div_scale_f32 v53, s[2:3], v52, v52, v39
	v_fma_f32 v42, -v57, v44, v42
	v_rcp_f32_e32 v56, v53
	v_div_fmas_f32 v42, v42, v58, v44
	v_div_fixup_f32 v34, v42, v55, v34
	v_mul_f32_e32 v42, v34, v47
	v_mul_f32_e32 v47, 0xbfb8aa3b, v35
	v_fma_f32 v34, -v53, v56, 1.0
	v_exp_f32_e32 v47, v47
	v_fmac_f32_e32 v56, v34, v56
	v_div_scale_f32 v34, vcc, v39, v52, v39
	v_mul_f32_e32 v44, v34, v56
	v_fma_f32 v55, -v53, v44, v34
	v_fmac_f32_e32 v44, v55, v56
	v_add_f32_e32 v47, 1.0, v47
	v_fma_f32 v34, -v53, v44, v34
	v_div_scale_f32 v53, s[2:3], v47, v47, v35
	v_rcp_f32_e32 v55, v53
	v_div_fmas_f32 v34, v34, v56, v44
	v_mul_f32_e32 v44, 0xbfb8aa3b, v40
	v_exp_f32_e32 v44, v44
	v_div_fixup_f32 v34, v34, v52, v39
	v_fma_f32 v39, -v53, v55, 1.0
	v_fmac_f32_e32 v55, v39, v55
	v_div_scale_f32 v39, vcc, v35, v47, v35
	v_mul_f32_e32 v34, v34, v43
	v_mul_f32_e32 v43, v39, v55
	v_fma_f32 v52, -v53, v43, v39
	v_add_f32_e32 v44, 1.0, v44
	v_fmac_f32_e32 v43, v52, v55
	v_div_scale_f32 v52, s[2:3], v44, v44, v40
	v_fma_f32 v39, -v53, v43, v39
	v_rcp_f32_e32 v53, v52
	v_div_fmas_f32 v39, v39, v55, v43
	v_div_fixup_f32 v35, v39, v47, v35
	v_mul_f32_e32 v47, 0xbfb8aa3b, v36
	v_exp_f32_e32 v47, v47
	v_mul_f32_e32 v39, v35, v48
	v_fma_f32 v35, -v52, v53, 1.0
	v_fmac_f32_e32 v53, v35, v53
	v_div_scale_f32 v35, vcc, v40, v44, v40
	v_mul_f32_e32 v43, v35, v53
	v_fma_f32 v48, -v52, v43, v35
	v_add_f32_e32 v47, 1.0, v47
	v_fmac_f32_e32 v43, v48, v53
	v_div_scale_f32 v48, s[2:3], v47, v47, v36
	v_fma_f32 v35, -v52, v43, v35
	v_rcp_f32_e32 v52, v48
	v_div_fmas_f32 v35, v35, v53, v43
	v_div_fixup_f32 v35, v35, v44, v40
	v_mul_f32_e32 v44, 0xbfb8aa3b, v41
	v_exp_f32_e32 v44, v44
	v_fma_f32 v40, -v48, v52, 1.0
	v_fmac_f32_e32 v52, v40, v52
	v_div_scale_f32 v40, vcc, v36, v47, v36
	v_mul_f32_e32 v43, v40, v52
	v_mul_f32_e32 v35, v35, v45
	v_fma_f32 v45, -v48, v43, v40
	v_add_f32_e32 v44, 1.0, v44
	v_fmac_f32_e32 v43, v45, v52
	v_div_scale_f32 v45, s[2:3], v44, v44, v41
	v_fma_f32 v40, -v48, v43, v40
	v_rcp_f32_e32 v48, v45
	v_div_fmas_f32 v40, v40, v52, v43
	v_div_fixup_f32 v36, v40, v47, v36
	v_mul_f32_e32 v40, v36, v54
	v_fma_f32 v36, -v45, v48, 1.0
	v_mul_f32_e32 v47, 0xbfb8aa3b, v37
	v_fmac_f32_e32 v48, v36, v48
	v_div_scale_f32 v36, vcc, v41, v44, v41
	v_exp_f32_e32 v47, v47
	v_mul_f32_e32 v43, v36, v48
	v_fma_f32 v52, -v45, v43, v36
	v_fmac_f32_e32 v43, v52, v48
	v_fma_f32 v36, -v45, v43, v36
	v_add_f32_e32 v45, 1.0, v47
	v_div_scale_f32 v47, s[2:3], v45, v45, v37
	v_rcp_f32_e32 v52, v47
	v_div_fmas_f32 v36, v36, v48, v43
	v_div_fixup_f32 v36, v36, v44, v41
	v_mul_f32_e32 v36, v36, v46
	v_fma_f32 v41, -v47, v52, 1.0
	v_fmac_f32_e32 v52, v41, v52
	v_div_scale_f32 v41, vcc, v37, v45, v37
	v_mul_f32_e32 v43, v41, v52
	v_fma_f32 v44, -v47, v43, v41
	v_fmac_f32_e32 v43, v44, v52
	v_fma_f32 v41, -v47, v43, v41
	v_div_fmas_f32 v41, v41, v52, v43
	v_and_b32_e32 v49, 0xffff0000, v49
	v_div_fixup_f32 v37, v41, v45, v37
	v_cvt_pk_bf16_f32 v34, v38, v34
	v_cvt_pk_bf16_f32 v35, v35, v36
	v_cvt_pk_bf16_f32 v36, v42, v39
	v_add_co_u32_e32 v42, vcc, s50, v148
	v_mul_f32_e32 v37, v37, v49
	s_nop 0
	v_addc_co_u32_e32 v43, vcc, 0, v149, vcc
	v_cvt_pk_bf16_f32 v37, v40, v37
	s_waitcnt vmcnt(14)
	v_mov_b32_e32 v38, v234
	v_mov_b32_e32 v39, v235
	v_mov_b32_e32 v40, v236
	v_mov_b32_e32 v41, v237
	v_lshlrev_b32_e32 v45, 16, v40
	global_store_dwordx4 v[50:51], v[34:37], off offset:256
	v_mul_f32_e32 v51, 0xbfb8aa3b, v26
	v_exp_f32_e32 v51, v51
	v_lshlrev_b32_e32 v36, 16, v38
	v_and_b32_e32 v37, 0xffff0000, v38
	v_mul_f32_e32 v38, 0xbfb8aa3b, v30
	v_exp_f32_e32 v38, v38
	v_and_b32_e32 v40, 0xffff0000, v40
	v_lshlrev_b32_e32 v44, 16, v39
	v_lshlrev_b32_e32 v48, 16, v41
	v_add_f32_e32 v38, 1.0, v38
	v_div_scale_f32 v46, s[2:3], v38, v38, v30
	v_rcp_f32_e32 v47, v46
	v_and_b32_e32 v39, 0xffff0000, v39
	v_and_b32_e32 v41, 0xffff0000, v41
	v_lshl_add_u64 v[34:35], v[148:149], 0, s[18:19]
	v_fma_f32 v49, -v46, v47, 1.0
	v_fmac_f32_e32 v47, v49, v47
	v_div_scale_f32 v49, vcc, v30, v38, v30
	v_mul_f32_e32 v50, v49, v47
	v_fma_f32 v52, -v46, v50, v49
	v_fmac_f32_e32 v50, v52, v47
	v_fma_f32 v46, -v46, v50, v49
	v_add_f32_e32 v49, 1.0, v51
	v_div_scale_f32 v51, s[2:3], v49, v49, v26
	v_rcp_f32_e32 v52, v51
	v_div_fmas_f32 v46, v46, v47, v50
	v_div_fixup_f32 v30, v46, v38, v30
	v_mul_f32_e32 v46, 0xbfb8aa3b, v31
	v_exp_f32_e32 v46, v46
	v_mul_f32_e32 v30, v30, v36
	v_fma_f32 v36, -v51, v52, 1.0
	v_fmac_f32_e32 v52, v36, v52
	v_div_scale_f32 v36, vcc, v26, v49, v26
	v_mul_f32_e32 v38, v36, v52
	v_fma_f32 v47, -v51, v38, v36
	v_add_f32_e32 v46, 1.0, v46
	v_fmac_f32_e32 v38, v47, v52
	v_div_scale_f32 v47, s[2:3], v46, v46, v31
	v_fma_f32 v36, -v51, v38, v36
	v_rcp_f32_e32 v50, v47
	v_div_fmas_f32 v36, v36, v52, v38
	v_div_fixup_f32 v26, v36, v49, v26
	v_mul_f32_e32 v36, v26, v45
	v_mul_f32_e32 v45, 0xbfb8aa3b, v27
	v_fma_f32 v26, -v47, v50, 1.0
	v_exp_f32_e32 v45, v45
	v_fmac_f32_e32 v50, v26, v50
	v_div_scale_f32 v26, vcc, v31, v46, v31
	v_mul_f32_e32 v38, v26, v50
	v_fma_f32 v49, -v47, v38, v26
	v_fmac_f32_e32 v38, v49, v50
	v_add_f32_e32 v45, 1.0, v45
	v_fma_f32 v26, -v47, v38, v26
	v_div_scale_f32 v47, s[2:3], v45, v45, v27
	v_rcp_f32_e32 v49, v47
	v_div_fmas_f32 v26, v26, v50, v38
	v_mul_f32_e32 v38, 0xbfb8aa3b, v32
	v_div_fixup_f32 v26, v26, v46, v31
	v_fma_f32 v31, -v47, v49, 1.0
	v_exp_f32_e32 v38, v38
	v_fmac_f32_e32 v49, v31, v49
	v_div_scale_f32 v31, vcc, v27, v45, v27
	v_mul_f32_e32 v26, v26, v37
	v_mul_f32_e32 v37, v31, v49
	v_fma_f32 v46, -v47, v37, v31
	v_fmac_f32_e32 v37, v46, v49
	v_add_f32_e32 v38, 1.0, v38
	v_fma_f32 v31, -v47, v37, v31
	v_div_scale_f32 v46, s[2:3], v38, v38, v32
	v_rcp_f32_e32 v47, v46
	v_div_fmas_f32 v31, v31, v49, v37
	v_div_fixup_f32 v27, v31, v45, v27
	v_mul_f32_e32 v31, v27, v40
	v_mul_f32_e32 v40, 0xbfb8aa3b, v28
	v_exp_f32_e32 v40, v40
	v_fma_f32 v27, -v46, v47, 1.0
	v_fmac_f32_e32 v47, v27, v47
	v_div_scale_f32 v27, vcc, v32, v38, v32
	v_mul_f32_e32 v37, v27, v47
	v_fma_f32 v45, -v46, v37, v27
	v_add_f32_e32 v40, 1.0, v40
	v_fmac_f32_e32 v37, v45, v47
	v_div_scale_f32 v45, s[2:3], v40, v40, v28
	v_fma_f32 v27, -v46, v37, v27
	v_rcp_f32_e32 v46, v45
	v_div_fmas_f32 v27, v27, v47, v37
	v_div_fixup_f32 v27, v27, v38, v32
	v_mul_f32_e32 v38, 0xbfb8aa3b, v33
	v_exp_f32_e32 v38, v38
	v_fma_f32 v32, -v45, v46, 1.0
	v_fmac_f32_e32 v46, v32, v46
	v_div_scale_f32 v32, vcc, v28, v40, v28
	v_mul_f32_e32 v37, v32, v46
	v_mul_f32_e32 v27, v27, v44
	v_fma_f32 v44, -v45, v37, v32
	v_add_f32_e32 v38, 1.0, v38
	v_fmac_f32_e32 v37, v44, v46
	v_div_scale_f32 v44, s[2:3], v38, v38, v33
	v_fma_f32 v32, -v45, v37, v32
	v_rcp_f32_e32 v45, v44
	v_div_fmas_f32 v32, v32, v46, v37
	v_div_fixup_f32 v28, v32, v40, v28
	v_mul_f32_e32 v40, 0xbfb8aa3b, v29
	v_mul_f32_e32 v32, v28, v48
	v_fma_f32 v28, -v44, v45, 1.0
	v_exp_f32_e32 v40, v40
	v_fmac_f32_e32 v45, v28, v45
	v_div_scale_f32 v28, vcc, v33, v38, v33
	v_mul_f32_e32 v37, v28, v45
	v_fma_f32 v46, -v44, v37, v28
	v_fmac_f32_e32 v37, v46, v45
	v_add_f32_e32 v40, 1.0, v40
	v_fma_f32 v28, -v44, v37, v28
	v_div_scale_f32 v44, s[2:3], v40, v40, v29
	v_rcp_f32_e32 v46, v44
	v_div_fmas_f32 v28, v28, v45, v37
	v_div_fixup_f32 v28, v28, v38, v33
	v_mul_f32_e32 v28, v28, v39
	v_fma_f32 v33, -v44, v46, 1.0
	v_fmac_f32_e32 v46, v33, v46
	v_div_scale_f32 v33, vcc, v29, v40, v29
	v_mul_f32_e32 v37, v33, v46
	v_fma_f32 v38, -v44, v37, v33
	v_fmac_f32_e32 v37, v38, v46
	v_fma_f32 v33, -v44, v37, v33
	v_div_fmas_f32 v33, v33, v46, v37
	v_div_fixup_f32 v29, v33, v40, v29
	v_mul_f32_e32 v29, v29, v41
	v_cvt_pk_bf16_f32 v26, v30, v26
	v_cvt_pk_bf16_f32 v27, v27, v28
	v_cvt_pk_bf16_f32 v28, v36, v31
	v_cvt_pk_bf16_f32 v29, v32, v29
	v_mul_f32_e32 v41, 0xbfb8aa3b, v18
	global_store_dwordx4 v[42:43], v[26:29], off
	v_exp_f32_e32 v41, v41
	s_waitcnt vmcnt(14)
	v_mov_b32_e32 v30, v238
	v_mov_b32_e32 v31, v239
	v_mov_b32_e32 v32, v240
	v_mov_b32_e32 v33, v241
	v_lshlrev_b32_e32 v38, 16, v33
	v_mul_f32_e32 v28, 0xbfb8aa3b, v22
	v_exp_f32_e32 v28, v28
	v_lshlrev_b32_e32 v26, 16, v30
	v_and_b32_e32 v27, 0xffff0000, v30
	v_lshlrev_b32_e32 v29, 16, v31
	v_add_f32_e32 v28, 1.0, v28
	v_div_scale_f32 v36, s[2:3], v28, v28, v22
	v_rcp_f32_e32 v37, v36
	v_and_b32_e32 v30, 0xffff0000, v31
	v_lshlrev_b32_e32 v31, 16, v32
	v_and_b32_e32 v32, 0xffff0000, v32
	v_fma_f32 v39, -v36, v37, 1.0
	v_fmac_f32_e32 v37, v39, v37
	v_div_scale_f32 v39, vcc, v22, v28, v22
	v_mul_f32_e32 v40, v39, v37
	v_fma_f32 v42, -v36, v40, v39
	v_fmac_f32_e32 v40, v42, v37
	v_fma_f32 v36, -v36, v40, v39
	v_add_f32_e32 v39, 1.0, v41
	v_div_scale_f32 v41, s[2:3], v39, v39, v18
	v_rcp_f32_e32 v42, v41
	v_div_fmas_f32 v36, v36, v37, v40
	v_div_fixup_f32 v22, v36, v28, v22
	v_mul_f32_e32 v36, 0xbfb8aa3b, v23
	v_exp_f32_e32 v36, v36
	v_mul_f32_e32 v22, v22, v26
	v_fma_f32 v26, -v41, v42, 1.0
	v_fmac_f32_e32 v42, v26, v42
	v_div_scale_f32 v26, vcc, v18, v39, v18
	v_mul_f32_e32 v28, v26, v42
	v_fma_f32 v37, -v41, v28, v26
	v_add_f32_e32 v36, 1.0, v36
	v_fmac_f32_e32 v28, v37, v42
	v_div_scale_f32 v37, s[2:3], v36, v36, v23
	v_fma_f32 v26, -v41, v28, v26
	v_rcp_f32_e32 v40, v37
	v_div_fmas_f32 v26, v26, v42, v28
	v_div_fixup_f32 v18, v26, v39, v18
	v_mul_f32_e32 v26, v18, v31
	v_mul_f32_e32 v31, 0xbfb8aa3b, v19
	v_fma_f32 v18, -v37, v40, 1.0
	v_exp_f32_e32 v31, v31
	v_fmac_f32_e32 v40, v18, v40
	v_div_scale_f32 v18, vcc, v23, v36, v23
	v_mul_f32_e32 v28, v18, v40
	v_fma_f32 v39, -v37, v28, v18
	v_fmac_f32_e32 v28, v39, v40
	v_add_f32_e32 v31, 1.0, v31
	v_fma_f32 v18, -v37, v28, v18
	v_div_scale_f32 v37, s[2:3], v31, v31, v19
	v_rcp_f32_e32 v39, v37
	v_div_fmas_f32 v18, v18, v40, v28
	v_mul_f32_e32 v28, 0xbfb8aa3b, v24
	v_exp_f32_e32 v28, v28
	v_div_fixup_f32 v18, v18, v36, v23
	v_fma_f32 v23, -v37, v39, 1.0
	v_fmac_f32_e32 v39, v23, v39
	v_div_scale_f32 v23, vcc, v19, v31, v19
	v_mul_f32_e32 v18, v18, v27
	v_mul_f32_e32 v27, v23, v39
	v_fma_f32 v36, -v37, v27, v23
	v_add_f32_e32 v28, 1.0, v28
	v_fmac_f32_e32 v27, v36, v39
	v_div_scale_f32 v36, s[2:3], v28, v28, v24
	v_fma_f32 v23, -v37, v27, v23
	v_rcp_f32_e32 v37, v36
	v_div_fmas_f32 v23, v23, v39, v27
	v_div_fixup_f32 v19, v23, v31, v19
	v_mul_f32_e32 v31, 0xbfb8aa3b, v20
	v_exp_f32_e32 v31, v31
	v_mul_f32_e32 v23, v19, v32
	v_fma_f32 v19, -v36, v37, 1.0
	v_fmac_f32_e32 v37, v19, v37
	v_div_scale_f32 v19, vcc, v24, v28, v24
	v_mul_f32_e32 v27, v19, v37
	v_fma_f32 v32, -v36, v27, v19
	v_add_f32_e32 v31, 1.0, v31
	v_fmac_f32_e32 v27, v32, v37
	v_div_scale_f32 v32, s[2:3], v31, v31, v20
	v_fma_f32 v19, -v36, v27, v19
	v_rcp_f32_e32 v36, v32
	v_div_fmas_f32 v19, v19, v37, v27
	v_div_fixup_f32 v19, v19, v28, v24
	v_mul_f32_e32 v28, 0xbfb8aa3b, v25
	v_exp_f32_e32 v28, v28
	v_fma_f32 v24, -v32, v36, 1.0
	v_fmac_f32_e32 v36, v24, v36
	v_div_scale_f32 v24, vcc, v20, v31, v20
	v_mul_f32_e32 v27, v24, v36
	v_mul_f32_e32 v19, v19, v29
	v_fma_f32 v29, -v32, v27, v24
	v_add_f32_e32 v28, 1.0, v28
	v_fmac_f32_e32 v27, v29, v36
	v_div_scale_f32 v29, s[2:3], v28, v28, v25
	v_fma_f32 v24, -v32, v27, v24
	v_rcp_f32_e32 v32, v29
	v_div_fmas_f32 v24, v24, v36, v27
	v_div_fixup_f32 v20, v24, v31, v20
	v_mul_f32_e32 v24, v20, v38
	v_fma_f32 v20, -v29, v32, 1.0
	v_mul_f32_e32 v31, 0xbfb8aa3b, v21
	v_fmac_f32_e32 v32, v20, v32
	v_div_scale_f32 v20, vcc, v25, v28, v25
	v_exp_f32_e32 v31, v31
	v_mul_f32_e32 v27, v20, v32
	v_fma_f32 v36, -v29, v27, v20
	v_fmac_f32_e32 v27, v36, v32
	v_fma_f32 v20, -v29, v27, v20
	v_add_f32_e32 v29, 1.0, v31
	v_div_scale_f32 v31, s[2:3], v29, v29, v21
	v_rcp_f32_e32 v36, v31
	v_div_fmas_f32 v20, v20, v32, v27
	v_div_fixup_f32 v20, v20, v28, v25
	v_mul_f32_e32 v20, v20, v30
	v_fma_f32 v25, -v31, v36, 1.0
	v_fmac_f32_e32 v36, v25, v36
	v_div_scale_f32 v25, vcc, v21, v29, v21
	v_mul_f32_e32 v27, v25, v36
	v_fma_f32 v28, -v31, v27, v25
	v_fmac_f32_e32 v27, v28, v36
	v_fma_f32 v25, -v31, v27, v25
	v_div_fmas_f32 v25, v25, v36, v27
	v_and_b32_e32 v33, 0xffff0000, v33
	v_div_fixup_f32 v21, v25, v29, v21
	v_cvt_pk_bf16_f32 v18, v22, v18
	v_cvt_pk_bf16_f32 v19, v19, v20
	v_cvt_pk_bf16_f32 v20, v26, v23
	v_add_co_u32_e32 v26, vcc, s51, v148
	v_mul_f32_e32 v21, v21, v33
	s_nop 0
	v_addc_co_u32_e32 v27, vcc, 0, v149, vcc
	v_cvt_pk_bf16_f32 v21, v24, v21
	s_waitcnt vmcnt(14)
	v_mov_b32_e32 v22, v242
	v_mov_b32_e32 v23, v243
	v_mov_b32_e32 v24, v244
	v_mov_b32_e32 v25, v245
	v_lshlrev_b32_e32 v29, 16, v24
	global_store_dwordx4 v[34:35], v[18:21], off offset:256
	v_mul_f32_e32 v35, 0xbfb8aa3b, v10
	v_exp_f32_e32 v35, v35
	v_lshlrev_b32_e32 v20, 16, v22
	v_and_b32_e32 v21, 0xffff0000, v22
	v_mul_f32_e32 v22, 0xbfb8aa3b, v14
	v_exp_f32_e32 v22, v22
	v_and_b32_e32 v24, 0xffff0000, v24
	v_lshlrev_b32_e32 v28, 16, v23
	v_lshlrev_b32_e32 v32, 16, v25
	v_add_f32_e32 v22, 1.0, v22
	v_div_scale_f32 v30, s[2:3], v22, v22, v14
	v_rcp_f32_e32 v31, v30
	v_and_b32_e32 v23, 0xffff0000, v23
	v_and_b32_e32 v25, 0xffff0000, v25
	v_lshl_add_u64 v[18:19], v[148:149], 0, s[20:21]
	v_fma_f32 v33, -v30, v31, 1.0
	v_fmac_f32_e32 v31, v33, v31
	v_div_scale_f32 v33, vcc, v14, v22, v14
	v_mul_f32_e32 v34, v33, v31
	v_fma_f32 v36, -v30, v34, v33
	v_fmac_f32_e32 v34, v36, v31
	v_fma_f32 v30, -v30, v34, v33
	v_add_f32_e32 v33, 1.0, v35
	v_div_scale_f32 v35, s[2:3], v33, v33, v10
	v_rcp_f32_e32 v36, v35
	v_div_fmas_f32 v30, v30, v31, v34
	v_div_fixup_f32 v14, v30, v22, v14
	v_mul_f32_e32 v30, 0xbfb8aa3b, v15
	v_exp_f32_e32 v30, v30
	v_mul_f32_e32 v14, v14, v20
	v_fma_f32 v20, -v35, v36, 1.0
	v_fmac_f32_e32 v36, v20, v36
	v_div_scale_f32 v20, vcc, v10, v33, v10
	v_mul_f32_e32 v22, v20, v36
	v_fma_f32 v31, -v35, v22, v20
	v_add_f32_e32 v30, 1.0, v30
	v_fmac_f32_e32 v22, v31, v36
	v_div_scale_f32 v31, s[2:3], v30, v30, v15
	v_fma_f32 v20, -v35, v22, v20
	v_rcp_f32_e32 v34, v31
	v_div_fmas_f32 v20, v20, v36, v22
	v_div_fixup_f32 v10, v20, v33, v10
	v_mul_f32_e32 v20, v10, v29
	v_mul_f32_e32 v29, 0xbfb8aa3b, v11
	v_fma_f32 v10, -v31, v34, 1.0
	v_exp_f32_e32 v29, v29
	v_fmac_f32_e32 v34, v10, v34
	v_div_scale_f32 v10, vcc, v15, v30, v15
	v_mul_f32_e32 v22, v10, v34
	v_fma_f32 v33, -v31, v22, v10
	v_fmac_f32_e32 v22, v33, v34
	v_add_f32_e32 v29, 1.0, v29
	v_fma_f32 v10, -v31, v22, v10
	v_div_scale_f32 v31, s[2:3], v29, v29, v11
	v_rcp_f32_e32 v33, v31
	v_div_fmas_f32 v10, v10, v34, v22
	v_mul_f32_e32 v22, 0xbfb8aa3b, v16
	v_div_fixup_f32 v10, v10, v30, v15
	v_fma_f32 v15, -v31, v33, 1.0
	v_exp_f32_e32 v22, v22
	v_fmac_f32_e32 v33, v15, v33
	v_div_scale_f32 v15, vcc, v11, v29, v11
	v_mul_f32_e32 v10, v10, v21
	v_mul_f32_e32 v21, v15, v33
	v_fma_f32 v30, -v31, v21, v15
	v_fmac_f32_e32 v21, v30, v33
	v_add_f32_e32 v22, 1.0, v22
	v_fma_f32 v15, -v31, v21, v15
	v_div_scale_f32 v30, s[2:3], v22, v22, v16
	v_rcp_f32_e32 v31, v30
	v_div_fmas_f32 v15, v15, v33, v21
	v_div_fixup_f32 v11, v15, v29, v11
	v_mul_f32_e32 v15, v11, v24
	v_mul_f32_e32 v24, 0xbfb8aa3b, v12
	v_exp_f32_e32 v24, v24
	v_fma_f32 v11, -v30, v31, 1.0
	v_fmac_f32_e32 v31, v11, v31
	v_div_scale_f32 v11, vcc, v16, v22, v16
	v_mul_f32_e32 v21, v11, v31
	v_fma_f32 v29, -v30, v21, v11
	v_add_f32_e32 v24, 1.0, v24
	v_fmac_f32_e32 v21, v29, v31
	v_div_scale_f32 v29, s[2:3], v24, v24, v12
	v_fma_f32 v11, -v30, v21, v11
	v_rcp_f32_e32 v30, v29
	v_div_fmas_f32 v11, v11, v31, v21
	v_div_fixup_f32 v11, v11, v22, v16
	v_mul_f32_e32 v22, 0xbfb8aa3b, v17
	v_exp_f32_e32 v22, v22
	v_fma_f32 v16, -v29, v30, 1.0
	v_fmac_f32_e32 v30, v16, v30
	v_div_scale_f32 v16, vcc, v12, v24, v12
	v_mul_f32_e32 v21, v16, v30
	v_mul_f32_e32 v11, v11, v28
	v_fma_f32 v28, -v29, v21, v16
	v_add_f32_e32 v22, 1.0, v22
	v_fmac_f32_e32 v21, v28, v30
	v_div_scale_f32 v28, s[2:3], v22, v22, v17
	v_fma_f32 v16, -v29, v21, v16
	v_rcp_f32_e32 v29, v28
	v_div_fmas_f32 v16, v16, v30, v21
	v_div_fixup_f32 v12, v16, v24, v12
	v_mul_f32_e32 v24, 0xbfb8aa3b, v13
	v_mul_f32_e32 v16, v12, v32
	v_fma_f32 v12, -v28, v29, 1.0
	v_exp_f32_e32 v24, v24
	v_fmac_f32_e32 v29, v12, v29
	v_div_scale_f32 v12, vcc, v17, v22, v17
	v_mul_f32_e32 v21, v12, v29
	v_fma_f32 v30, -v28, v21, v12
	v_fmac_f32_e32 v21, v30, v29
	v_add_f32_e32 v24, 1.0, v24
	v_fma_f32 v12, -v28, v21, v12
	v_div_scale_f32 v28, s[2:3], v24, v24, v13
	v_rcp_f32_e32 v30, v28
	v_div_fmas_f32 v12, v12, v29, v21
	v_div_fixup_f32 v12, v12, v22, v17
	v_mul_f32_e32 v12, v12, v23
	v_fma_f32 v17, -v28, v30, 1.0
	v_fmac_f32_e32 v30, v17, v30
	v_div_scale_f32 v17, vcc, v13, v24, v13
	v_mul_f32_e32 v21, v17, v30
	v_fma_f32 v22, -v28, v21, v17
	v_fmac_f32_e32 v21, v22, v30
	v_fma_f32 v17, -v28, v21, v17
	v_div_fmas_f32 v17, v17, v30, v21
	v_div_fixup_f32 v13, v17, v24, v13
	v_mul_f32_e32 v13, v13, v25
	v_cvt_pk_bf16_f32 v10, v14, v10
	v_cvt_pk_bf16_f32 v11, v11, v12
	v_cvt_pk_bf16_f32 v12, v20, v15
	v_cvt_pk_bf16_f32 v13, v16, v13
	v_mul_f32_e32 v25, 0xbfb8aa3b, v2
	global_store_dwordx4 v[26:27], v[10:13], off
	v_exp_f32_e32 v25, v25
	s_waitcnt vmcnt(14)
; #define PG8_WAIT_V(n) asm volatile("s_waitcnt vmcnt(" #n ")" ::: "memory")
; #define PG8_BAR __builtin_amdgcn_s_barrier()
; template <class Epi>
; __device__ __forceinline__ void gemm_phase(PG8_LAS unsigned char* lds, const Gemm g, const StaticOrder& S, const Epi& E) {
;     ...
;         if (!has_next) break;
;     ...
;     PG8_WAIT_V(0);
;     if (wr == 0) PG8_BAR;
;     PG8_BAR;
	v_mov_b32_e32 v14, v246
	v_mov_b32_e32 v15, v247
	v_mov_b32_e32 v16, v248
	v_mov_b32_e32 v17, v249
	v_lshlrev_b32_e32 v22, 16, v17
	v_mul_f32_e32 v12, 0xbfb8aa3b, v6
	v_exp_f32_e32 v12, v12
	v_lshlrev_b32_e32 v10, 16, v14
	v_and_b32_e32 v11, 0xffff0000, v14
	v_lshlrev_b32_e32 v13, 16, v15
	v_add_f32_e32 v12, 1.0, v12
	v_div_scale_f32 v20, s[2:3], v12, v12, v6
	v_rcp_f32_e32 v21, v20
	v_and_b32_e32 v14, 0xffff0000, v15
	v_lshlrev_b32_e32 v15, 16, v16
	v_and_b32_e32 v16, 0xffff0000, v16
	v_fma_f32 v23, -v20, v21, 1.0
	v_fmac_f32_e32 v21, v23, v21
	v_div_scale_f32 v23, vcc, v6, v12, v6
	v_mul_f32_e32 v24, v23, v21
	v_fma_f32 v26, -v20, v24, v23
	v_fmac_f32_e32 v24, v26, v21
	v_fma_f32 v20, -v20, v24, v23
	v_add_f32_e32 v23, 1.0, v25
	v_div_scale_f32 v25, s[2:3], v23, v23, v2
	v_rcp_f32_e32 v26, v25
	v_div_fmas_f32 v20, v20, v21, v24
	v_div_fixup_f32 v6, v20, v12, v6
	v_mul_f32_e32 v20, 0xbfb8aa3b, v7
	v_exp_f32_e32 v20, v20
	v_mul_f32_e32 v6, v6, v10
	v_fma_f32 v10, -v25, v26, 1.0
	v_fmac_f32_e32 v26, v10, v26
	v_div_scale_f32 v10, vcc, v2, v23, v2
	v_mul_f32_e32 v12, v10, v26
	v_fma_f32 v21, -v25, v12, v10
	v_add_f32_e32 v20, 1.0, v20
	v_fmac_f32_e32 v12, v21, v26
	v_div_scale_f32 v21, s[2:3], v20, v20, v7
	v_fma_f32 v10, -v25, v12, v10
	v_rcp_f32_e32 v24, v21
	v_div_fmas_f32 v10, v10, v26, v12
	v_div_fixup_f32 v2, v10, v23, v2
	v_mul_f32_e32 v10, v2, v15
	v_mul_f32_e32 v15, 0xbfb8aa3b, v3
	v_fma_f32 v2, -v21, v24, 1.0
	v_exp_f32_e32 v15, v15
	v_fmac_f32_e32 v24, v2, v24
	v_div_scale_f32 v2, vcc, v7, v20, v7
	v_mul_f32_e32 v12, v2, v24
	v_fma_f32 v23, -v21, v12, v2
	v_fmac_f32_e32 v12, v23, v24
	v_add_f32_e32 v15, 1.0, v15
	v_fma_f32 v2, -v21, v12, v2
	v_div_scale_f32 v21, s[2:3], v15, v15, v3
	v_rcp_f32_e32 v23, v21
	v_div_fmas_f32 v2, v2, v24, v12
	v_mul_f32_e32 v12, 0xbfb8aa3b, v8
	v_exp_f32_e32 v12, v12
	v_div_fixup_f32 v2, v2, v20, v7
	v_fma_f32 v7, -v21, v23, 1.0
	v_fmac_f32_e32 v23, v7, v23
	v_div_scale_f32 v7, vcc, v3, v15, v3
	v_mul_f32_e32 v2, v2, v11
	v_mul_f32_e32 v11, v7, v23
	v_fma_f32 v20, -v21, v11, v7
	v_add_f32_e32 v12, 1.0, v12
	v_fmac_f32_e32 v11, v20, v23
	v_div_scale_f32 v20, s[2:3], v12, v12, v8
	v_fma_f32 v7, -v21, v11, v7
	v_rcp_f32_e32 v21, v20
	v_div_fmas_f32 v7, v7, v23, v11
	v_div_fixup_f32 v3, v7, v15, v3
	v_mul_f32_e32 v15, 0xbfb8aa3b, v4
	v_exp_f32_e32 v15, v15
	v_mul_f32_e32 v7, v3, v16
	v_fma_f32 v3, -v20, v21, 1.0
	v_fmac_f32_e32 v21, v3, v21
	v_div_scale_f32 v3, vcc, v8, v12, v8
	v_mul_f32_e32 v11, v3, v21
	v_fma_f32 v16, -v20, v11, v3
	v_add_f32_e32 v15, 1.0, v15
	v_fmac_f32_e32 v11, v16, v21
	v_div_scale_f32 v16, s[2:3], v15, v15, v4
	v_fma_f32 v3, -v20, v11, v3
	v_rcp_f32_e32 v20, v16
	v_div_fmas_f32 v3, v3, v21, v11
	v_div_fixup_f32 v3, v3, v12, v8
	v_mul_f32_e32 v12, 0xbfb8aa3b, v9
	v_exp_f32_e32 v12, v12
	v_fma_f32 v8, -v16, v20, 1.0
	v_fmac_f32_e32 v20, v8, v20
	v_div_scale_f32 v8, vcc, v4, v15, v4
	v_mul_f32_e32 v11, v8, v20
	v_mul_f32_e32 v3, v3, v13
	v_fma_f32 v13, -v16, v11, v8
	v_add_f32_e32 v12, 1.0, v12
	v_fmac_f32_e32 v11, v13, v20
	v_div_scale_f32 v13, s[2:3], v12, v12, v9
	v_fma_f32 v8, -v16, v11, v8
	v_rcp_f32_e32 v16, v13
	v_div_fmas_f32 v8, v8, v20, v11
	v_div_fixup_f32 v4, v8, v15, v4
	v_mul_f32_e32 v8, v4, v22
	v_fma_f32 v4, -v13, v16, 1.0
	v_mul_f32_e32 v15, 0xbfb8aa3b, v5
	v_fmac_f32_e32 v16, v4, v16
	v_div_scale_f32 v4, vcc, v9, v12, v9
	v_exp_f32_e32 v15, v15
	v_mul_f32_e32 v11, v4, v16
	v_fma_f32 v20, -v13, v11, v4
	v_fmac_f32_e32 v11, v20, v16
	v_fma_f32 v4, -v13, v11, v4
	v_add_f32_e32 v13, 1.0, v15
	v_div_scale_f32 v15, s[2:3], v13, v13, v5
	v_rcp_f32_e32 v20, v15
	v_div_fmas_f32 v4, v4, v16, v11
	v_div_fixup_f32 v4, v4, v12, v9
	v_and_b32_e32 v17, 0xffff0000, v17
	v_fma_f32 v9, -v15, v20, 1.0
	v_fmac_f32_e32 v20, v9, v20
	v_div_scale_f32 v9, vcc, v5, v13, v5
	v_mul_f32_e32 v11, v9, v20
	v_fma_f32 v12, -v15, v11, v9
	v_fmac_f32_e32 v11, v12, v20
	v_fma_f32 v9, -v15, v11, v9
	v_div_fmas_f32 v9, v9, v20, v11
	v_div_fixup_f32 v5, v9, v13, v5
	v_mul_f32_e32 v4, v4, v14
	v_mul_f32_e32 v5, v5, v17
	s_and_b64 vcc, exec, s[0:1]
	s_mov_b32 s3, s22
	s_mov_b32 s2, s24
	v_cvt_pk_bf16_f32 v2, v6, v2
	v_cvt_pk_bf16_f32 v3, v3, v4
	v_cvt_pk_bf16_f32 v4, v10, v7
	v_cvt_pk_bf16_f32 v5, v8, v5
	global_store_dwordx4 v[18:19], v[2:5], off offset:256
	s_cbranch_vccz .LBB0_1049
	s_waitcnt vmcnt(0)
	s_cmpk_gt_u32 s33, 0xff
	s_cbranch_scc1 .LBB0_1060
	s_barrier

; #define PG8_STAGE(bufoff, gbase, voff) do { _Pragma("unroll") for (int _i = 0; _i < 2; ++_i) \
;         __builtin_amdgcn_global_load_lds((const unsigned*)((const char*)(gbase) + (voff)[_i]), (PG8_LAS unsigned*)(lds + (bufoff) + ldsw + _i * 8192), 16, 0, 0); } while (0)
; #define PG8_LDA(dst, b, h) do { _Pragma("unroll") for (int m = 0; m < 4; ++m) _Pragma("unroll") for (int k = 0; k < 2; ++k) dst[m][k] = *(const PG8_LAS bf16x8*)(lds + PG8_SA(b, h) + aoff + m * 2048 + k * 1024); } while (0)
; #define PG8_LDB(dst, b, h) do { _Pragma("unroll") for (int n = 0; n < 2; ++n) _Pragma("unroll") for (int k = 0; k < 2; ++k) dst[n][k] = *(const PG8_LAS bf16x8*)(lds + PG8_SB(b, h) + boff + n * 2048 + k * 1024); } while (0)
; #define PG8_MMA(ai, bj, At, Bt) do { __builtin_amdgcn_s_setprio(1); _Pragma("unroll") for (int m = 0; m < 4; ++m) _Pragma("unroll") for (int n = 0; n < 2; ++n) _Pragma("unroll") for (int k = 0; k < 2; ++k) \
;         acc[ai][bj][m][n] = __builtin_amdgcn_mfma_f32_16x16x32_bf16(Bt[n][k], At[m][k], acc[ai][bj][m][n], 0, 0, 0); __builtin_amdgcn_s_setprio(0); } while (0)
; #define PG8_WAIT_L(n) asm volatile("s_waitcnt lgkmcnt(" #n ")" ::: "memory")
; #define PG8_BAR __builtin_amdgcn_s_barrier()
; #define PG8_SCHED __builtin_amdgcn_sched_barrier(0)
; template <class Epi>
; __device__ __forceinline__ void gemm_phase(PG8_LAS unsigned char* lds, const Gemm g, const StaticOrder& S, const Epi& E) {
;     ...
;             PG8_LDB(B0, 0, 0); PG8_SCHED; PG8_LDA(At, 0, 0); PG8_STAGE(PG8_SA(1, 1), a1 + hstep, voffA);
;             PG8_WAIT_L(8); PG8_BAR; PG8_WAIT_L(0); PG8_MMA(0, 0, At, B0); PG8_BAR; PG8_SCHED;
;             PG8_LDB(B1, 0, 1); PG8_STAGE(PG8_SB(0, 0), b2, voffB);
;             PG8_BAR; PG8_WAIT_L(0); PG8_MMA(0, 1, At, B1); PG8_BAR;
;             PG8_LDA(At, 0, 1); PG8_STAGE(PG8_SA(0, 0), a2, voffA);
;             PG8_BAR; PG8_WAIT_L(0); PG8_MMA(1, 0, At, B0); PG8_BAR; PG8_SCHED;
.LBB0_1089:
	ds_read_b128 v[154:157], v151
	ds_read_b128 v[158:161], v151 offset:1024
	ds_read_b128 v[162:165], v151 offset:2048
	ds_read_b128 v[166:169], v151 offset:3072
	s_add_u32 s28, s26, 0xfff00080
	s_addc_u32 s29, s27, -1
	s_cmp_eq_u32 s58, 60
	s_cselect_b32 s31, s19, s29
	s_cselect_b32 s30, s54, s28
	s_cselect_b32 s29, s17, s57
	s_cselect_b32 s28, s55, s56
	v_lshl_add_u64 v[148:149], s[26:27], 0, v[140:141]
	s_add_i32 m0, s25, 0xc000
	ds_read_b128 v[170:173], v152
	ds_read_b128 v[174:177], v152 offset:1024
	ds_read_b128 v[178:181], v152 offset:2048
	ds_read_b128 v[182:185], v152 offset:3072
	ds_read_b128 v[186:189], v152 offset:4096
	ds_read_b128 v[190:193], v152 offset:5120
	ds_read_b128 v[194:197], v152 offset:6144
	ds_read_b128 v[198:201], v152 offset:7168
	global_load_lds_dwordx4 v[148:149], off
	v_lshl_add_u64 v[148:149], s[26:27], 0, v[142:143]
	s_add_i32 m0, s25, 0xe000
	s_nop 0
	global_load_lds_dwordx4 v[148:149], off
	s_waitcnt lgkmcnt(8)
	s_barrier
	s_nop 0
	s_setprio 1
	s_nop 0
	s_waitcnt lgkmcnt(7)
	v_mfma_f32_16x16x32_bf16 v[126:129], v[154:157], v[170:173], v[126:129]
	v_mfma_f32_16x16x32_bf16 v[122:125], v[162:165], v[170:173], v[122:125]
	s_waitcnt lgkmcnt(5)
	v_mfma_f32_16x16x32_bf16 v[114:117], v[154:157], v[178:181], v[114:117]
	v_mfma_f32_16x16x32_bf16 v[106:109], v[162:165], v[178:181], v[106:109]
	s_waitcnt lgkmcnt(3)
	v_mfma_f32_16x16x32_bf16 v[98:101], v[154:157], v[186:189], v[98:101]
	v_mfma_f32_16x16x32_bf16 v[90:93], v[162:165], v[186:189], v[90:93]
	s_waitcnt lgkmcnt(1)
	v_mfma_f32_16x16x32_bf16 v[82:85], v[154:157], v[194:197], v[82:85]
	v_mfma_f32_16x16x32_bf16 v[74:77], v[162:165], v[194:197], v[74:77]
	v_mfma_f32_16x16x32_bf16 v[126:129], v[158:161], v[174:177], v[126:129]
	v_mfma_f32_16x16x32_bf16 v[122:125], v[166:169], v[174:177], v[122:125]
	v_mfma_f32_16x16x32_bf16 v[114:117], v[158:161], v[182:185], v[114:117]
	v_mfma_f32_16x16x32_bf16 v[106:109], v[166:169], v[182:185], v[106:109]
	v_mfma_f32_16x16x32_bf16 v[98:101], v[158:161], v[190:193], v[98:101]
	v_mfma_f32_16x16x32_bf16 v[90:93], v[166:169], v[190:193], v[90:93]
	s_waitcnt lgkmcnt(0)
	v_mfma_f32_16x16x32_bf16 v[82:85], v[158:161], v[198:201], v[82:85]
	v_mfma_f32_16x16x32_bf16 v[74:77], v[166:169], v[198:201], v[74:77]
	s_setprio 0
	s_barrier
	s_add_i32 s59, s47, s39
	v_lshl_add_u64 v[148:149], s[28:29], 0, v[134:135]
	s_mov_b32 m0, s59
	ds_read_b128 v[202:205], v153
	ds_read_b128 v[206:209], v153 offset:1024
	ds_read_b128 v[210:213], v153 offset:2048
	ds_read_b128 v[214:217], v153 offset:3072
	global_load_lds_dwordx4 v[148:149], off
	v_lshl_add_u64 v[218:219], s[28:29], 0, v[138:139]
	s_add_i32 m0, s59, 0x2000
	s_nop 0
	global_load_lds_dwordx4 v[218:219], off
	s_barrier
	s_nop 0
	s_setprio 1
	s_nop 0
	s_waitcnt lgkmcnt(3)
	v_mfma_f32_16x16x32_bf16 v[118:121], v[202:205], v[170:173], v[118:121]
	s_waitcnt lgkmcnt(1)
	v_mfma_f32_16x16x32_bf16 v[110:113], v[210:213], v[170:173], v[110:113]
	v_mfma_f32_16x16x32_bf16 v[102:105], v[202:205], v[178:181], v[102:105]
	v_mfma_f32_16x16x32_bf16 v[94:97], v[210:213], v[178:181], v[94:97]
	v_mfma_f32_16x16x32_bf16 v[86:89], v[202:205], v[186:189], v[86:89]
	v_mfma_f32_16x16x32_bf16 v[78:81], v[210:213], v[186:189], v[78:81]
	v_mfma_f32_16x16x32_bf16 v[70:73], v[202:205], v[194:197], v[70:73]
	v_mfma_f32_16x16x32_bf16 v[66:69], v[210:213], v[194:197], v[66:69]
	v_mfma_f32_16x16x32_bf16 v[118:121], v[206:209], v[174:177], v[118:121]
	s_waitcnt lgkmcnt(0)
	v_mfma_f32_16x16x32_bf16 v[110:113], v[214:217], v[174:177], v[110:113]
	v_mfma_f32_16x16x32_bf16 v[102:105], v[206:209], v[182:185], v[102:105]
	v_mfma_f32_16x16x32_bf16 v[94:97], v[214:217], v[182:185], v[94:97]
	v_mfma_f32_16x16x32_bf16 v[86:89], v[206:209], v[190:193], v[86:89]
	v_mfma_f32_16x16x32_bf16 v[78:81], v[214:217], v[190:193], v[78:81]
	v_mfma_f32_16x16x32_bf16 v[70:73], v[206:209], v[198:201], v[70:73]
	v_mfma_f32_16x16x32_bf16 v[66:69], v[214:217], v[198:201], v[66:69]
	s_setprio 0
	s_mov_b32 m0, s25
	v_lshl_add_u64 v[220:221], s[30:31], 0, v[132:133]
	s_barrier
	ds_read_b128 v[170:173], v152 offset:16384
	ds_read_b128 v[174:177], v152 offset:17408
	ds_read_b128 v[178:181], v152 offset:18432
	ds_read_b128 v[182:185], v152 offset:19456
	ds_read_b128 v[186:189], v152 offset:20480
	ds_read_b128 v[190:193], v152 offset:21504
	ds_read_b128 v[194:197], v152 offset:22528
	ds_read_b128 v[198:201], v152 offset:23552
	global_load_lds_dwordx4 v[220:221], off
	v_lshl_add_u64 v[222:223], s[30:31], 0, v[136:137]
	s_mov_b32 m0, s40
	s_nop 0
	global_load_lds_dwordx4 v[222:223], off
	s_barrier
	s_nop 0
	s_setprio 1
	s_nop 0
	s_waitcnt lgkmcnt(7)
	v_mfma_f32_16x16x32_bf16 v[62:65], v[154:157], v[170:173], v[62:65]
	v_mfma_f32_16x16x32_bf16 v[58:61], v[162:165], v[170:173], v[58:61]
	s_waitcnt lgkmcnt(5)
	v_mfma_f32_16x16x32_bf16 v[54:57], v[154:157], v[178:181], v[54:57]
	v_mfma_f32_16x16x32_bf16 v[46:49], v[162:165], v[178:181], v[46:49]
	s_waitcnt lgkmcnt(3)
	v_mfma_f32_16x16x32_bf16 v[38:41], v[154:157], v[186:189], v[38:41]
	v_mfma_f32_16x16x32_bf16 v[30:33], v[162:165], v[186:189], v[30:33]
	s_waitcnt lgkmcnt(1)
	v_mfma_f32_16x16x32_bf16 v[22:25], v[154:157], v[194:197], v[22:25]
	v_mfma_f32_16x16x32_bf16 v[14:17], v[162:165], v[194:197], v[14:17]
	v_mfma_f32_16x16x32_bf16 v[62:65], v[158:161], v[174:177], v[62:65]
	v_mfma_f32_16x16x32_bf16 v[58:61], v[166:169], v[174:177], v[58:61]
	v_mfma_f32_16x16x32_bf16 v[54:57], v[158:161], v[182:185], v[54:57]
	v_mfma_f32_16x16x32_bf16 v[46:49], v[166:169], v[182:185], v[46:49]
	v_mfma_f32_16x16x32_bf16 v[38:41], v[158:161], v[190:193], v[38:41]
	v_mfma_f32_16x16x32_bf16 v[30:33], v[166:169], v[190:193], v[30:33]
	s_waitcnt lgkmcnt(0)
	v_mfma_f32_16x16x32_bf16 v[22:25], v[158:161], v[198:201], v[22:25]
	v_mfma_f32_16x16x32_bf16 v[14:17], v[166:169], v[198:201], v[14:17]
	s_setprio 0
	s_barrier
; #define PG8_STAGE(bufoff, gbase, voff) do { _Pragma("unroll") for (int _i = 0; _i < 2; ++_i) \
;         __builtin_amdgcn_global_load_lds((const unsigned*)((const char*)(gbase) + (voff)[_i]), (PG8_LAS unsigned*)(lds + (bufoff) + ldsw + _i * 8192), 16, 0, 0); } while (0)
; #define PG8_LDA(dst, b, h) do { _Pragma("unroll") for (int m = 0; m < 4; ++m) _Pragma("unroll") for (int k = 0; k < 2; ++k) dst[m][k] = *(const PG8_LAS bf16x8*)(lds + PG8_SA(b, h) + aoff + m * 2048 + k * 1024); } while (0)
; #define PG8_LDB(dst, b, h) do { _Pragma("unroll") for (int n = 0; n < 2; ++n) _Pragma("unroll") for (int k = 0; k < 2; ++k) dst[n][k] = *(const PG8_LAS bf16x8*)(lds + PG8_SB(b, h) + boff + n * 2048 + k * 1024); } while (0)
; #define PG8_MMA(ai, bj, At, Bt) do { __builtin_amdgcn_s_setprio(1); _Pragma("unroll") for (int m = 0; m < 4; ++m) _Pragma("unroll") for (int n = 0; n < 2; ++n) _Pragma("unroll") for (int k = 0; k < 2; ++k) \
;         acc[ai][bj][m][n] = __builtin_amdgcn_mfma_f32_16x16x32_bf16(Bt[n][k], At[m][k], acc[ai][bj][m][n], 0, 0, 0); __builtin_amdgcn_s_setprio(0); } while (0)
; #define PG8_WAIT_V(n) asm volatile("s_waitcnt vmcnt(" #n ")" ::: "memory")
; #define PG8_WAIT_L(n) asm volatile("s_waitcnt lgkmcnt(" #n ")" ::: "memory")
; #define PG8_BAR __builtin_amdgcn_s_barrier()
; #define PG8_SCHED __builtin_amdgcn_sched_barrier(0)
; template <class Epi>
; __device__ __forceinline__ void gemm_phase(PG8_LAS unsigned char* lds, const Gemm g, const StaticOrder& S, const Epi& E) {
;     ...
;             PG8_STAGE(PG8_SB(0, 1), b2 + hstep, voffB);
;             PG8_WAIT_V(6); PG8_BAR; PG8_MMA(1, 1, At, B1); PG8_BAR;
;             PG8_LDB(B0, 1, 0); PG8_SCHED; PG8_LDA(At, 1, 0); PG8_STAGE(PG8_SA(0, 1), a2 + hstep, voffA);
;             PG8_WAIT_L(8); PG8_BAR; PG8_WAIT_L(0); PG8_MMA(0, 0, At, B0); PG8_BAR; PG8_SCHED;
;             PG8_LDB(B1, 1, 1); PG8_STAGE(PG8_SB(1, 0), b3, voffB);
;             PG8_BAR; PG8_WAIT_L(0); PG8_MMA(0, 1, At, B1); PG8_BAR;
	s_add_u32 s60, s28, 0x100000
	s_addc_u32 s61, s29, 0
	s_add_i32 s59, s48, s39
	v_lshl_add_u64 v[154:155], s[60:61], 0, v[134:135]
	s_mov_b32 m0, s59
	s_nop 0
	global_load_lds_dwordx4 v[154:155], off
	v_lshl_add_u64 v[154:155], s[60:61], 0, v[138:139]
	s_add_i32 m0, s59, 0x2000
	s_nop 0
	global_load_lds_dwordx4 v[154:155], off
	s_waitcnt vmcnt(6)
	s_barrier
	s_setprio 1
	v_mfma_f32_16x16x32_bf16 v[50:53], v[202:205], v[170:173], v[50:53]
	v_mfma_f32_16x16x32_bf16 v[42:45], v[210:213], v[170:173], v[42:45]
	v_mfma_f32_16x16x32_bf16 v[34:37], v[202:205], v[178:181], v[34:37]
	v_mfma_f32_16x16x32_bf16 v[26:29], v[210:213], v[178:181], v[26:29]
	v_mfma_f32_16x16x32_bf16 v[18:21], v[202:205], v[186:189], v[18:21]
	v_mfma_f32_16x16x32_bf16 v[10:13], v[210:213], v[186:189], v[10:13]
	v_mfma_f32_16x16x32_bf16 v[6:9], v[202:205], v[194:197], v[6:9]
	v_mfma_f32_16x16x32_bf16 v[2:5], v[210:213], v[194:197], v[2:5]
	v_mfma_f32_16x16x32_bf16 v[50:53], v[206:209], v[174:177], v[50:53]
	v_mfma_f32_16x16x32_bf16 v[42:45], v[214:217], v[174:177], v[42:45]
	v_mfma_f32_16x16x32_bf16 v[34:37], v[206:209], v[182:185], v[34:37]
	v_mfma_f32_16x16x32_bf16 v[26:29], v[214:217], v[182:185], v[26:29]
	v_mfma_f32_16x16x32_bf16 v[18:21], v[206:209], v[190:193], v[18:21]
	v_mfma_f32_16x16x32_bf16 v[10:13], v[214:217], v[190:193], v[10:13]
	v_mfma_f32_16x16x32_bf16 v[6:9], v[206:209], v[198:201], v[6:9]
	v_mfma_f32_16x16x32_bf16 v[2:5], v[214:217], v[198:201], v[2:5]
	s_setprio 0
	s_add_i32 s59, 0, 0x18000
	v_add_u32_e32 v166, s59, v131
	s_barrier
	ds_read_b128 v[154:157], v166
	ds_read_b128 v[158:161], v166 offset:1024
	ds_read_b128 v[162:165], v166 offset:2048
	ds_read_b128 v[166:169], v166 offset:3072
	s_add_u32 s30, s30, 0x100000
	s_addc_u32 s31, s31, 0
	s_mov_b32 m0, s41
	v_lshl_add_u64 v[202:203], s[30:31], 0, v[132:133]
	ds_read_b128 v[170:173], v152 offset:32768
	ds_read_b128 v[174:177], v152 offset:33792
	ds_read_b128 v[178:181], v152 offset:34816
	ds_read_b128 v[182:185], v152 offset:35840
	ds_read_b128 v[186:189], v152 offset:36864
	ds_read_b128 v[190:193], v152 offset:37888
	ds_read_b128 v[194:197], v152 offset:38912
	ds_read_b128 v[198:201], v152 offset:39936
	global_load_lds_dwordx4 v[202:203], off
	v_lshl_add_u64 v[202:203], s[30:31], 0, v[136:137]
	s_mov_b32 m0, s42
	s_nop 0
	global_load_lds_dwordx4 v[202:203], off
	s_waitcnt lgkmcnt(8)
	s_barrier
	s_nop 0
	s_setprio 1
	s_nop 0
	s_waitcnt lgkmcnt(7)
	v_mfma_f32_16x16x32_bf16 v[126:129], v[154:157], v[170:173], v[126:129]
	v_mfma_f32_16x16x32_bf16 v[122:125], v[162:165], v[170:173], v[122:125]
	s_waitcnt lgkmcnt(5)
	v_mfma_f32_16x16x32_bf16 v[114:117], v[154:157], v[178:181], v[114:117]
	v_mfma_f32_16x16x32_bf16 v[106:109], v[162:165], v[178:181], v[106:109]
	s_waitcnt lgkmcnt(3)
	v_mfma_f32_16x16x32_bf16 v[98:101], v[154:157], v[186:189], v[98:101]
	v_mfma_f32_16x16x32_bf16 v[90:93], v[162:165], v[186:189], v[90:93]
	s_waitcnt lgkmcnt(1)
	v_mfma_f32_16x16x32_bf16 v[82:85], v[154:157], v[194:197], v[82:85]
	v_mfma_f32_16x16x32_bf16 v[74:77], v[162:165], v[194:197], v[74:77]
	v_mfma_f32_16x16x32_bf16 v[126:129], v[158:161], v[174:177], v[126:129]
	v_mfma_f32_16x16x32_bf16 v[122:125], v[166:169], v[174:177], v[122:125]
	v_mfma_f32_16x16x32_bf16 v[114:117], v[158:161], v[182:185], v[114:117]
	v_mfma_f32_16x16x32_bf16 v[106:109], v[166:169], v[182:185], v[106:109]
	v_mfma_f32_16x16x32_bf16 v[98:101], v[158:161], v[190:193], v[98:101]
	v_mfma_f32_16x16x32_bf16 v[90:93], v[166:169], v[190:193], v[90:93]
	s_waitcnt lgkmcnt(0)
	v_mfma_f32_16x16x32_bf16 v[82:85], v[158:161], v[198:201], v[82:85]
	v_mfma_f32_16x16x32_bf16 v[74:77], v[166:169], v[198:201], v[74:77]
	s_setprio 0
	s_barrier
	s_add_i32 s30, 0, 0x1c000
	s_add_i32 s31, s59, s39
	v_add_u32_e32 v214, s30, v131
	v_lshl_add_u64 v[148:149], v[148:149], 0, s[6:7]
	s_mov_b32 m0, s31
	ds_read_b128 v[202:205], v214
	ds_read_b128 v[206:209], v214 offset:1024
	ds_read_b128 v[210:213], v214 offset:2048
	ds_read_b128 v[214:217], v214 offset:3072
	global_load_lds_dwordx4 v[148:149], off
	v_lshl_add_u64 v[148:149], v[218:219], 0, s[6:7]
	s_add_i32 m0, s31, 0x2000
	s_nop 0
	global_load_lds_dwordx4 v[148:149], off
	s_barrier
	s_nop 0
	s_setprio 1
	s_nop 0
	s_waitcnt lgkmcnt(3)
	v_mfma_f32_16x16x32_bf16 v[118:121], v[202:205], v[170:173], v[118:121]
	s_waitcnt lgkmcnt(1)
	v_mfma_f32_16x16x32_bf16 v[110:113], v[210:213], v[170:173], v[110:113]
	v_mfma_f32_16x16x32_bf16 v[102:105], v[202:205], v[178:181], v[102:105]
	v_mfma_f32_16x16x32_bf16 v[94:97], v[210:213], v[178:181], v[94:97]
	v_mfma_f32_16x16x32_bf16 v[86:89], v[202:205], v[186:189], v[86:89]
	v_mfma_f32_16x16x32_bf16 v[78:81], v[210:213], v[186:189], v[78:81]
	v_mfma_f32_16x16x32_bf16 v[70:73], v[202:205], v[194:197], v[70:73]
	v_mfma_f32_16x16x32_bf16 v[66:69], v[210:213], v[194:197], v[66:69]
	v_mfma_f32_16x16x32_bf16 v[118:121], v[206:209], v[174:177], v[118:121]
	s_waitcnt lgkmcnt(0)
	v_mfma_f32_16x16x32_bf16 v[110:113], v[214:217], v[174:177], v[110:113]
	v_mfma_f32_16x16x32_bf16 v[102:105], v[206:209], v[182:185], v[102:105]
	v_mfma_f32_16x16x32_bf16 v[94:97], v[214:217], v[182:185], v[94:97]
	v_mfma_f32_16x16x32_bf16 v[86:89], v[206:209], v[190:193], v[86:89]
	v_mfma_f32_16x16x32_bf16 v[78:81], v[214:217], v[190:193], v[78:81]
	v_mfma_f32_16x16x32_bf16 v[70:73], v[206:209], v[198:201], v[70:73]
	v_mfma_f32_16x16x32_bf16 v[66:69], v[214:217], v[198:201], v[66:69]
	s_setprio 0
	s_mov_b32 m0, s44
	v_lshl_add_u64 v[148:149], v[220:221], 0, s[6:7]
	s_barrier
; #define PG8_STAGE(bufoff, gbase, voff) do { _Pragma("unroll") for (int _i = 0; _i < 2; ++_i) \
;         __builtin_amdgcn_global_load_lds((const unsigned*)((const char*)(gbase) + (voff)[_i]), (PG8_LAS unsigned*)(lds + (bufoff) + ldsw + _i * 8192), 16, 0, 0); } while (0)
; #define PG8_LDA(dst, b, h) do { _Pragma("unroll") for (int m = 0; m < 4; ++m) _Pragma("unroll") for (int k = 0; k < 2; ++k) dst[m][k] = *(const PG8_LAS bf16x8*)(lds + PG8_SA(b, h) + aoff + m * 2048 + k * 1024); } while (0)
; #define PG8_MMA(ai, bj, At, Bt) do { __builtin_amdgcn_s_setprio(1); _Pragma("unroll") for (int m = 0; m < 4; ++m) _Pragma("unroll") for (int n = 0; n < 2; ++n) _Pragma("unroll") for (int k = 0; k < 2; ++k) \
;         acc[ai][bj][m][n] = __builtin_amdgcn_mfma_f32_16x16x32_bf16(Bt[n][k], At[m][k], acc[ai][bj][m][n], 0, 0, 0); __builtin_amdgcn_s_setprio(0); } while (0)
; #define PG8_WAIT_V(n) asm volatile("s_waitcnt vmcnt(" #n ")" ::: "memory")
; #define PG8_WAIT_L(n) asm volatile("s_waitcnt lgkmcnt(" #n ")" ::: "memory")
; #define PG8_BAR __builtin_amdgcn_s_barrier()
; #define PG8_SCHED __builtin_amdgcn_sched_barrier(0)
; template <class Epi>
; __device__ __forceinline__ void gemm_phase(PG8_LAS unsigned char* lds, const Gemm g, const StaticOrder& S, const Epi& E) {
;     ...
;             PG8_LDA(At, 1, 1); PG8_STAGE(PG8_SA(1, 0), a3, voffA);
;             PG8_BAR; PG8_WAIT_L(0); PG8_MMA(1, 0, At, B0); PG8_BAR; PG8_SCHED;
;             PG8_STAGE(PG8_SB(1, 1), b3 + hstep, voffB);
;             PG8_WAIT_V(6); PG8_BAR; PG8_MMA(1, 1, At, B1); PG8_BAR;
	ds_read_b128 v[170:173], v152 offset:49152
	ds_read_b128 v[174:177], v152 offset:50176
	ds_read_b128 v[178:181], v152 offset:51200
	ds_read_b128 v[182:185], v152 offset:52224
	ds_read_b128 v[186:189], v152 offset:53248
	ds_read_b128 v[190:193], v152 offset:54272
	ds_read_b128 v[194:197], v152 offset:55296
	ds_read_b128 v[198:201], v152 offset:56320
	global_load_lds_dwordx4 v[148:149], off
	v_lshl_add_u64 v[148:149], v[222:223], 0, s[6:7]
	s_mov_b32 m0, s45
	s_nop 0
	global_load_lds_dwordx4 v[148:149], off
	s_barrier
	s_nop 0
	s_setprio 1
	s_nop 0
	s_waitcnt lgkmcnt(7)
	v_mfma_f32_16x16x32_bf16 v[62:65], v[154:157], v[170:173], v[62:65]
	v_mfma_f32_16x16x32_bf16 v[58:61], v[162:165], v[170:173], v[58:61]
	s_waitcnt lgkmcnt(5)
	v_mfma_f32_16x16x32_bf16 v[54:57], v[154:157], v[178:181], v[54:57]
	v_mfma_f32_16x16x32_bf16 v[46:49], v[162:165], v[178:181], v[46:49]
	s_waitcnt lgkmcnt(3)
	v_mfma_f32_16x16x32_bf16 v[38:41], v[154:157], v[186:189], v[38:41]
	v_mfma_f32_16x16x32_bf16 v[30:33], v[162:165], v[186:189], v[30:33]
	s_waitcnt lgkmcnt(1)
	v_mfma_f32_16x16x32_bf16 v[22:25], v[154:157], v[194:197], v[22:25]
	v_mfma_f32_16x16x32_bf16 v[14:17], v[162:165], v[194:197], v[14:17]
	v_mfma_f32_16x16x32_bf16 v[62:65], v[158:161], v[174:177], v[62:65]
	v_mfma_f32_16x16x32_bf16 v[58:61], v[166:169], v[174:177], v[58:61]
	v_mfma_f32_16x16x32_bf16 v[54:57], v[158:161], v[182:185], v[54:57]
	v_mfma_f32_16x16x32_bf16 v[46:49], v[166:169], v[182:185], v[46:49]
	v_mfma_f32_16x16x32_bf16 v[38:41], v[158:161], v[190:193], v[38:41]
	v_mfma_f32_16x16x32_bf16 v[30:33], v[166:169], v[190:193], v[30:33]
	s_waitcnt lgkmcnt(0)
	v_mfma_f32_16x16x32_bf16 v[22:25], v[158:161], v[198:201], v[22:25]
	v_mfma_f32_16x16x32_bf16 v[14:17], v[166:169], v[198:201], v[14:17]
	s_setprio 0
	s_barrier
	s_add_u32 s28, s28, 0x100080
	s_addc_u32 s29, s29, 0
	s_add_i32 s30, s30, s39
	v_lshl_add_u64 v[148:149], s[28:29], 0, v[134:135]
	s_mov_b32 m0, s30
	s_nop 0
	global_load_lds_dwordx4 v[148:149], off
	v_lshl_add_u64 v[148:149], s[28:29], 0, v[138:139]
	s_add_i32 m0, s30, 0x2000
	s_nop 0
	global_load_lds_dwordx4 v[148:149], off
	s_waitcnt vmcnt(6)
	s_barrier
	s_setprio 1
	v_mfma_f32_16x16x32_bf16 v[50:53], v[202:205], v[170:173], v[50:53]
	v_mfma_f32_16x16x32_bf16 v[42:45], v[210:213], v[170:173], v[42:45]
	v_mfma_f32_16x16x32_bf16 v[34:37], v[202:205], v[178:181], v[34:37]
	v_mfma_f32_16x16x32_bf16 v[26:29], v[210:213], v[178:181], v[26:29]
	v_mfma_f32_16x16x32_bf16 v[18:21], v[202:205], v[186:189], v[18:21]
	v_mfma_f32_16x16x32_bf16 v[10:13], v[210:213], v[186:189], v[10:13]
	v_mfma_f32_16x16x32_bf16 v[6:9], v[202:205], v[194:197], v[6:9]
	v_mfma_f32_16x16x32_bf16 v[2:5], v[210:213], v[194:197], v[2:5]
	v_mfma_f32_16x16x32_bf16 v[50:53], v[206:209], v[174:177], v[50:53]
	v_mfma_f32_16x16x32_bf16 v[42:45], v[214:217], v[174:177], v[42:45]
	v_mfma_f32_16x16x32_bf16 v[34:37], v[206:209], v[182:185], v[34:37]
	v_mfma_f32_16x16x32_bf16 v[26:29], v[214:217], v[182:185], v[26:29]
	v_mfma_f32_16x16x32_bf16 v[18:21], v[206:209], v[190:193], v[18:21]
	v_mfma_f32_16x16x32_bf16 v[10:13], v[214:217], v[190:193], v[10:13]
	v_mfma_f32_16x16x32_bf16 v[6:9], v[206:209], v[198:201], v[6:9]
	v_mfma_f32_16x16x32_bf16 v[2:5], v[214:217], v[198:201], v[2:5]
	s_setprio 0
	s_add_i32 s58, s58, 2
	s_add_u32 s26, s26, 0x100
	s_addc_u32 s27, s27, 0
	s_add_u32 s56, s56, 0x100
	s_addc_u32 s57, s57, 0
	s_cmp_gt_u32 s58, 61
	s_barrier
	s_cbranch_scc0 .LBB0_1089
; __device__ __forceinline__ unsigned pk2(float lo, float hi) { unsigned r; asm volatile("v_cvt_pk_bf16_f32 %0, %1, %2" : "=v"(r) : "v"(lo), "v"(hi)); return r; }
;     __device__ __forceinline__ void operator()(const f32x4 (&acc)[2][2][4][2], const Unit& u, int wr, int wc, int fr, int fq) const {
;         const int row0 = u.pm * BM + wr * 64 + fr, col0 = u.pn * BM + wc * 32 + 8 * fq;
; #pragma unroll
;         for (int ai = 0; ai < 2; ++ai)
; #pragma unroll
;             for (int m = 0; m < 4; ++m)
; #pragma unroll
;                 for (int bj = 0; bj < 2; ++bj) f(row0 + ai * HALF + m * 16, col0 + bj * HALF, acc[ai][bj][m][0], acc[ai][bj][m][1]);
;     }
; __device__ __forceinline__ void store8bf(u16* dst, f32x4 v0, f32x4 v1) { u32x4 w; w.x = pk2(v0[0], v0[1]); w.y = pk2(v0[2], v0[3]); w.z = pk2(v1[0], v1[1]); w.w = pk2(v1[2], v1[3]); *(u32x4*)dst = w; }
	v_lshl_add_u32 v154, s24, 8, v1
	v_lshl_or_b32 v148, s53, 8, v150
	v_ashrrev_i32_e32 v155, 31, v154
	v_lshlrev_b64 v[156:157], 12, v[154:155]
	v_ashrrev_i32_e32 v149, 31, v148
	v_lshl_add_u64 v[156:157], s[4:5], 0, v[156:157]
	v_lshlrev_b64 v[158:159], 1, v[148:149]
	v_lshl_add_u64 v[148:149], v[156:157], 0, v[158:159]
	v_cvt_pk_bf16_f32 v126, v126, v127
	v_cvt_pk_bf16_f32 v127, v128, v129
	v_cvt_pk_bf16_f32 v128, v122, v123
	v_cvt_pk_bf16_f32 v129, v124, v125
	global_store_dwordx4 v[148:149], v[126:129], off
	v_cvt_pk_bf16_f32 v118, v118, v119
	v_cvt_pk_bf16_f32 v119, v120, v121
	v_cvt_pk_bf16_f32 v120, v110, v111
	v_or_b32_e32 v110, 16, v154
	v_ashrrev_i32_e32 v111, 31, v110
	v_lshlrev_b64 v[110:111], 12, v[110:111]
	v_lshl_add_u64 v[110:111], s[4:5], 0, v[110:111]
	v_cvt_pk_bf16_f32 v121, v112, v113
	global_store_dwordx4 v[148:149], v[118:121], off offset:256
	s_mov_b32 s53, s16
	s_mov_b32 s24, s18
	v_lshl_add_u64 v[118:119], v[110:111], 0, v[158:159]
	v_cvt_pk_bf16_f32 v110, v114, v115
	v_cvt_pk_bf16_f32 v111, v116, v117
	v_cvt_pk_bf16_f32 v112, v106, v107
	v_cvt_pk_bf16_f32 v113, v108, v109
	global_store_dwordx4 v[118:119], v[110:113], off
	v_cvt_pk_bf16_f32 v102, v102, v103
	v_cvt_pk_bf16_f32 v103, v104, v105
	v_cvt_pk_bf16_f32 v104, v94, v95
	v_or_b32_e32 v94, 32, v154
	v_ashrrev_i32_e32 v95, 31, v94
	v_lshlrev_b64 v[94:95], 12, v[94:95]
	v_lshl_add_u64 v[94:95], s[4:5], 0, v[94:95]
	v_cvt_pk_bf16_f32 v105, v96, v97
	global_store_dwordx4 v[118:119], v[102:105], off offset:256
	s_mov_b64 s[28:29], s[22:23]
	s_mov_b64 s[26:27], s[20:21]
	v_lshl_add_u64 v[102:103], v[94:95], 0, v[158:159]
	v_cvt_pk_bf16_f32 v94, v98, v99
	v_cvt_pk_bf16_f32 v95, v100, v101
	v_cvt_pk_bf16_f32 v96, v90, v91
	v_cvt_pk_bf16_f32 v97, v92, v93
	global_store_dwordx4 v[102:103], v[94:97], off
	v_cvt_pk_bf16_f32 v86, v86, v87
	v_cvt_pk_bf16_f32 v87, v88, v89
	v_cvt_pk_bf16_f32 v88, v78, v79
	v_or_b32_e32 v78, 48, v154
	v_ashrrev_i32_e32 v79, 31, v78
	v_lshlrev_b64 v[78:79], 12, v[78:79]
	v_lshl_add_u64 v[78:79], s[4:5], 0, v[78:79]
	v_cvt_pk_bf16_f32 v89, v80, v81
	global_store_dwordx4 v[102:103], v[86:89], off offset:256
	s_nop 1
	v_lshl_add_u64 v[86:87], v[78:79], 0, v[158:159]
	v_cvt_pk_bf16_f32 v78, v82, v83
	v_cvt_pk_bf16_f32 v79, v84, v85
	v_cvt_pk_bf16_f32 v80, v74, v75
	v_cvt_pk_bf16_f32 v81, v76, v77
	global_store_dwordx4 v[86:87], v[78:81], off
	v_cvt_pk_bf16_f32 v70, v70, v71
	v_cvt_pk_bf16_f32 v71, v72, v73
	v_cvt_pk_bf16_f32 v72, v66, v67
	v_cvt_pk_bf16_f32 v73, v68, v69
	global_store_dwordx4 v[86:87], v[70:73], off offset:256
	v_cvt_pk_bf16_f32 v62, v62, v63
	v_cvt_pk_bf16_f32 v63, v64, v65
	v_cvt_pk_bf16_f32 v64, v58, v59
	v_add_co_u32_e32 v58, vcc, s49, v148
	v_lshl_add_u64 v[66:67], v[148:149], 0, s[8:9]
	s_nop 0
	v_addc_co_u32_e32 v59, vcc, 0, v149, vcc
	v_cvt_pk_bf16_f32 v65, v60, v61
	global_store_dwordx4 v[58:59], v[62:65], off
	v_cvt_pk_bf16_f32 v50, v50, v51
	v_cvt_pk_bf16_f32 v51, v52, v53
	v_cvt_pk_bf16_f32 v52, v42, v43
	v_cvt_pk_bf16_f32 v53, v44, v45
	global_store_dwordx4 v[66:67], v[50:53], off offset:256
	v_cvt_pk_bf16_f32 v42, v54, v55
	v_cvt_pk_bf16_f32 v43, v56, v57
	v_cvt_pk_bf16_f32 v44, v46, v47
	v_add_co_u32_e32 v46, vcc, s50, v148
	s_nop 0
	v_lshl_add_u64 v[50:51], v[148:149], 0, s[10:11]
	v_addc_co_u32_e32 v47, vcc, 0, v149, vcc
	v_cvt_pk_bf16_f32 v45, v48, v49
	global_store_dwordx4 v[46:47], v[42:45], off
	v_cvt_pk_bf16_f32 v34, v34, v35
	v_cvt_pk_bf16_f32 v35, v36, v37
	v_cvt_pk_bf16_f32 v36, v26, v27
	v_cvt_pk_bf16_f32 v37, v28, v29
	global_store_dwordx4 v[50:51], v[34:37], off offset:256
	v_cvt_pk_bf16_f32 v26, v38, v39
	v_cvt_pk_bf16_f32 v27, v40, v41
	v_cvt_pk_bf16_f32 v28, v30, v31
	v_add_co_u32_e32 v30, vcc, s51, v148
	s_nop 0
	v_lshl_add_u64 v[34:35], v[148:149], 0, s[12:13]
	v_addc_co_u32_e32 v31, vcc, 0, v149, vcc
	v_cvt_pk_bf16_f32 v29, v32, v33
	global_store_dwordx4 v[30:31], v[26:29], off
	v_cvt_pk_bf16_f32 v18, v18, v19
	v_cvt_pk_bf16_f32 v19, v20, v21
	v_cvt_pk_bf16_f32 v20, v10, v11
	v_cvt_pk_bf16_f32 v21, v12, v13
	global_store_dwordx4 v[34:35], v[18:21], off offset:256
	v_cvt_pk_bf16_f32 v10, v22, v23
	v_cvt_pk_bf16_f32 v11, v24, v25
	v_cvt_pk_bf16_f32 v12, v14, v15
	v_add_co_u32_e32 v14, vcc, s52, v148
	s_nop 0
	v_lshl_add_u64 v[18:19], v[148:149], 0, s[14:15]
	v_addc_co_u32_e32 v15, vcc, 0, v149, vcc
	s_and_b64 vcc, exec, s[0:1]
	v_cvt_pk_bf16_f32 v13, v16, v17
	global_store_dwordx4 v[14:15], v[10:13], off
	v_cvt_pk_bf16_f32 v6, v6, v7
	v_cvt_pk_bf16_f32 v7, v8, v9
	v_cvt_pk_bf16_f32 v8, v2, v3
	v_cvt_pk_bf16_f32 v9, v4, v5
	global_store_dwordx4 v[18:19], v[6:9], off offset:256
	s_cbranch_vccz .LBB0_1082
	s_waitcnt vmcnt(0)
	s_cmpk_gt_u32 s33, 0xff
	s_cbranch_scc1 .LBB0_1093
	s_barrier
